# gemm_big fused loop: next-tile global loads also interleaved into the MFMA stream (SALU-computed 64-bit offsets); mm64 loops prefetch 3 k-steps ahead
# speedup vs baseline: 1.0503x; 1.0078x over previous
; __device__ __forceinline__ void lds_barrier() { asm volatile("s_waitcnt lgkmcnt(0)\n\ts_barrier" ::: "memory"); }
; __device__ __forceinline__ f32x16 mfma32(bf16x8 a, bf16x8 b, f32x16 c) { return __builtin_amdgcn_mfma_f32_32x32x16_bf16(a, b, c, 0, 0, 0); }
; __device__ __forceinline__ void gemm_big(const bf16_t* __restrict__ A, long lda, const bf16_t* __restrict__ Bt, int K, f32x16 (&acc)[2][4], unsigned char* lds) {
;     ...
;     for (int kc = 0; kc < nk; ++kc) {
;         bf16x8 af[2][2], bfr[2][4];
;         af[0][0] = *(const bf16x8*)(Ac); af[0][1] = *(const bf16x8*)(Ac + 32 * GLD);
; #pragma unroll
;         for (int ni = 0; ni < 4; ++ni) bfr[0][ni] = *(const bf16x8*)(Bc + ni * 32 * GLD);
;         __builtin_amdgcn_s_setprio(3);
; #pragma unroll
;         for (int ks = 0; ks < 4; ++ks) {
;             const int cb = ks & 1, nb = cb ^ 1;
;             if (ks < 3) {
;                 af[nb][0] = *(const bf16x8*)(Ac + (ks + 1) * 16); af[nb][1] = *(const bf16x8*)(Ac + 32 * GLD + (ks + 1) * 16);
; #pragma unroll
;                 for (int ni = 0; ni < 4; ++ni) bfr[nb][ni] = *(const bf16x8*)(Bc + ni * 32 * GLD + (ks + 1) * 16);
;             }
;             __builtin_amdgcn_sched_barrier(0);
; #pragma unroll
;             for (int ni = 0; ni < 4; ++ni) { acc[0][ni] = mfma32(af[cb][0], bfr[cb][ni], acc[0][ni]); acc[1][ni] = mfma32(af[cb][1], bfr[cb][ni], acc[1][ni]); }
;             __builtin_amdgcn_sched_barrier(0);
;         }
;         __builtin_amdgcn_s_setprio(0);
;         lds_barrier();
;         if (kc + 1 < nk) {
;             lstore();
;             if (kc + 2 < nk) gload(kc + 2);
;             lds_barrier();
;         }
.LBB0_56:
	s_cmp_gt_u32 s13, 42
	s_cbranch_scc1 .Lmy_gorig_8
	ds_read_b128 v[190:193], v187
	ds_read_b128 v[194:197], v187 offset:4608
	ds_read_b128 v[198:201], v188 offset:18432
	ds_read_b128 v[202:205], v188 offset:23040
	ds_read_b128 v[206:209], v188 offset:27648
	ds_read_b128 v[210:213], v188 offset:32256
	s_setprio 3
	ds_read_b128 v[214:217], v187 offset:32
	ds_read_b128 v[218:221], v187 offset:4640
	ds_read_b128 v[224:227], v188 offset:18464
	ds_read_b128 v[234:237], v188 offset:23072
	ds_read_b128 v[238:241], v188 offset:27680
	ds_read_b128 v[242:245], v188 offset:32288
	s_waitcnt lgkmcnt(9)
	v_mfma_f32_32x32x16_bf16 v[114:129], v[190:193], v[198:201], v[114:129]
	v_mfma_f32_32x32x16_bf16 v[50:65], v[194:197], v[198:201], v[50:65]
	s_waitcnt lgkmcnt(8)
	v_mfma_f32_32x32x16_bf16 v[98:113], v[190:193], v[202:205], v[98:113]
	v_mfma_f32_32x32x16_bf16 v[34:49], v[194:197], v[202:205], v[34:49]
	s_waitcnt lgkmcnt(7)
	v_mfma_f32_32x32x16_bf16 v[82:97], v[190:193], v[206:209], v[82:97]
	v_mfma_f32_32x32x16_bf16 v[18:33], v[194:197], v[206:209], v[18:33]
	s_waitcnt lgkmcnt(6)
	v_mfma_f32_32x32x16_bf16 v[66:81], v[190:193], v[210:213], v[66:81]
	v_mfma_f32_32x32x16_bf16 v[2:17], v[194:197], v[210:213], v[2:17]
	ds_read_b128 v[190:193], v187 offset:64
	ds_read_b128 v[194:197], v187 offset:4672
	ds_read_b128 v[198:201], v188 offset:18496
	ds_read_b128 v[202:205], v188 offset:23104
	ds_read_b128 v[206:209], v188 offset:27712
	ds_read_b128 v[210:213], v188 offset:32320
	s_waitcnt lgkmcnt(9)
	v_mfma_f32_32x32x16_bf16 v[114:129], v[214:217], v[224:227], v[114:129]
	v_mfma_f32_32x32x16_bf16 v[50:65], v[218:221], v[224:227], v[50:65]
	s_waitcnt lgkmcnt(8)
	v_mfma_f32_32x32x16_bf16 v[98:113], v[214:217], v[234:237], v[98:113]
	v_mfma_f32_32x32x16_bf16 v[34:49], v[218:221], v[234:237], v[34:49]
	s_waitcnt lgkmcnt(7)
	v_mfma_f32_32x32x16_bf16 v[82:97], v[214:217], v[238:241], v[82:97]
	v_mfma_f32_32x32x16_bf16 v[18:33], v[218:221], v[238:241], v[18:33]
	s_waitcnt lgkmcnt(6)
	v_mfma_f32_32x32x16_bf16 v[66:81], v[214:217], v[242:245], v[66:81]
	v_mfma_f32_32x32x16_bf16 v[2:17], v[218:221], v[242:245], v[2:17]
	ds_read_b128 v[214:217], v187 offset:96
	ds_read_b128 v[218:221], v187 offset:4704
	ds_read_b128 v[224:227], v188 offset:18528
	ds_read_b128 v[234:237], v188 offset:23136
	ds_read_b128 v[238:241], v188 offset:27744
	ds_read_b128 v[242:245], v188 offset:32352
	s_waitcnt lgkmcnt(9)
	v_mfma_f32_32x32x16_bf16 v[114:129], v[190:193], v[198:201], v[114:129]
	v_mfma_f32_32x32x16_bf16 v[50:65], v[194:197], v[198:201], v[50:65]
	s_waitcnt lgkmcnt(8)
	v_mfma_f32_32x32x16_bf16 v[98:113], v[190:193], v[202:205], v[98:113]
	v_mfma_f32_32x32x16_bf16 v[34:49], v[194:197], v[202:205], v[34:49]
	s_waitcnt lgkmcnt(0)
	s_barrier
	s_cmpk_eq_i32 s4, 0x1500
	s_cbranch_scc1 .Lmy_gB_8
	v_mfma_f32_32x32x16_bf16 v[82:97], v[190:193], v[206:209], v[82:97]
	s_waitcnt vmcnt(9)
	ds_write_b128 v189, v[130:133]
	v_mfma_f32_32x32x16_bf16 v[18:33], v[194:197], v[206:209], v[18:33]
	ds_write_b128 v189, v[134:137] offset:4608
	v_mfma_f32_32x32x16_bf16 v[66:81], v[190:193], v[210:213], v[66:81]
	ds_write_b128 v189, v[138:141] offset:9216
	s_add_u32 vcc_lo, s4, 0x78a8000
	s_addc_u32 vcc_hi, s5, 0
	s_nop 0
	v_lshl_add_u64 v[130:131], v[184:185], 0, vcc
	global_load_dwordx4 v[130:133], v[130:131], off offset:256
	v_mfma_f32_32x32x16_bf16 v[2:17], v[194:197], v[210:213], v[2:17]
	s_waitcnt vmcnt(8)
	ds_write_b128 v189, v[142:145] offset:13824
	s_add_u32 vcc_lo, s4, 0x78d4000
	s_addc_u32 vcc_hi, s5, 0
	s_nop 0
	v_lshl_add_u64 v[134:135], v[184:185], 0, vcc
	global_load_dwordx4 v[134:137], v[134:135], off offset:256
	v_mfma_f32_32x32x16_bf16 v[114:129], v[214:217], v[224:227], v[114:129]
	ds_write_b128 v189, v[146:149] offset:18432
	s_add_u32 vcc_lo, s4, 0x7900000
	s_addc_u32 vcc_hi, s5, 0
	s_nop 0
	v_lshl_add_u64 v[138:139], v[184:185], 0, vcc
	global_load_dwordx4 v[138:141], v[138:139], off offset:256
	v_mfma_f32_32x32x16_bf16 v[50:65], v[218:221], v[224:227], v[50:65]
	s_waitcnt vmcnt(9)
	ds_write_b128 v189, v[150:153] offset:23040
	s_add_u32 vcc_lo, s4, 0x792c000
	s_addc_u32 vcc_hi, s5, 0
	s_nop 0
	v_lshl_add_u64 v[142:143], v[184:185], 0, vcc
	global_load_dwordx4 v[142:145], v[142:143], off offset:256
	v_mfma_f32_32x32x16_bf16 v[98:113], v[214:217], v[234:237], v[98:113]
	s_waitcnt vmcnt(9)
	ds_write_b128 v189, v[154:157] offset:27648
	s_add_u32 vcc_lo, s4, 0x3328000
	s_addc_u32 vcc_hi, s5, 0
	s_nop 0
	v_lshl_add_u64 v[146:147], v[182:183], 0, vcc
	global_load_dwordx4 v[146:149], v[146:147], off offset:256
	v_mfma_f32_32x32x16_bf16 v[34:49], v[218:221], v[234:237], v[34:49]
	s_waitcnt vmcnt(9)
	ds_write_b128 v189, v[158:161] offset:32256
	s_add_u32 vcc_lo, s4, 0x3354000
	s_addc_u32 vcc_hi, s5, 0
	s_nop 0
	v_lshl_add_u64 v[150:151], v[182:183], 0, vcc
	global_load_dwordx4 v[150:153], v[150:151], off offset:256
	v_mfma_f32_32x32x16_bf16 v[82:97], v[214:217], v[238:241], v[82:97]
	s_waitcnt vmcnt(9)
	ds_write_b128 v189, v[162:165] offset:36864
	s_add_u32 vcc_lo, s4, 0x3380000
	s_addc_u32 vcc_hi, s5, 0
	s_nop 0
	v_lshl_add_u64 v[154:155], v[182:183], 0, vcc
	global_load_dwordx4 v[154:157], v[154:155], off offset:256
	v_mfma_f32_32x32x16_bf16 v[18:33], v[218:221], v[238:241], v[18:33]
	s_waitcnt vmcnt(9)
	ds_write_b128 v189, v[166:169] offset:41472
	s_add_u32 vcc_lo, s4, 0x33ac000
	s_addc_u32 vcc_hi, s5, 0
	s_nop 0
	v_lshl_add_u64 v[158:159], v[182:183], 0, vcc
	global_load_dwordx4 v[158:161], v[158:159], off offset:256
	v_mfma_f32_32x32x16_bf16 v[66:81], v[214:217], v[242:245], v[66:81]
	s_waitcnt vmcnt(9)
	ds_write_b128 v189, v[170:173] offset:46080
	s_add_u32 vcc_lo, s4, 0x33d8000
	s_addc_u32 vcc_hi, s5, 0
	s_nop 0
	v_lshl_add_u64 v[162:163], v[182:183], 0, vcc
	global_load_dwordx4 v[162:165], v[162:163], off offset:256
	v_mfma_f32_32x32x16_bf16 v[2:17], v[218:221], v[242:245], v[2:17]
	s_waitcnt vmcnt(9)
	ds_write_b128 v189, v[174:177] offset:50688
	s_add_u32 vcc_lo, s4, 0x3404000
	s_addc_u32 vcc_hi, s5, 0
	s_nop 0
	v_lshl_add_u64 v[166:167], v[182:183], 0, vcc
	global_load_dwordx4 v[166:169], v[166:167], off offset:256
	s_add_u32 vcc_lo, s4, 0x3430000
	s_addc_u32 vcc_hi, s5, 0
	s_nop 0
	v_lshl_add_u64 v[170:171], v[182:183], 0, vcc
	global_load_dwordx4 v[170:173], v[170:171], off offset:256
	s_add_u32 vcc_lo, s4, 0x345c000
	s_addc_u32 vcc_hi, s5, 0
	s_nop 0
	v_lshl_add_u64 v[174:175], v[182:183], 0, vcc
	global_load_dwordx4 v[174:177], v[174:175], off offset:256
	s_setprio 0
	s_branch .LBB0_54
; __device__ __forceinline__ void lds_barrier() { asm volatile("s_waitcnt lgkmcnt(0)\n\ts_barrier" ::: "memory"); }
; __device__ __forceinline__ f32x16 mfma32(bf16x8 a, bf16x8 b, f32x16 c) { return __builtin_amdgcn_mfma_f32_32x32x16_bf16(a, b, c, 0, 0, 0); }
; __device__ __forceinline__ void gemm_big(const bf16_t* __restrict__ A, long lda, const bf16_t* __restrict__ Bt, int K, f32x16 (&acc)[2][4], unsigned char* lds) {
;     ...
;                 af[nb][0] = *(const bf16x8*)(Ac + (ks + 1) * 16); af[nb][1] = *(const bf16x8*)(Ac + 32 * GLD + (ks + 1) * 16);
; #pragma unroll
;                 for (int ni = 0; ni < 4; ++ni) bfr[nb][ni] = *(const bf16x8*)(Bc + ni * 32 * GLD + (ks + 1) * 16);
;             }
;             __builtin_amdgcn_sched_barrier(0);
; #pragma unroll
;             for (int ni = 0; ni < 4; ++ni) { acc[0][ni] = mfma32(af[cb][0], bfr[cb][ni], acc[0][ni]); acc[1][ni] = mfma32(af[cb][1], bfr[cb][ni], acc[1][ni]); }
;             __builtin_amdgcn_sched_barrier(0);
;         }
;         __builtin_amdgcn_s_setprio(0);
;         lds_barrier();
;         if (kc + 1 < nk) {
;             lstore();
;             if (kc + 2 < nk) gload(kc + 2);
;             lds_barrier();
.Lmy_gB_8:
	v_mfma_f32_32x32x16_bf16 v[82:97], v[190:193], v[206:209], v[82:97]
	s_waitcnt vmcnt(9)
	ds_write_b128 v189, v[130:133]
	v_mfma_f32_32x32x16_bf16 v[18:33], v[194:197], v[206:209], v[18:33]
	ds_write_b128 v189, v[134:137] offset:4608
	v_mfma_f32_32x32x16_bf16 v[66:81], v[190:193], v[210:213], v[66:81]
	ds_write_b128 v189, v[138:141] offset:9216
	v_mfma_f32_32x32x16_bf16 v[2:17], v[194:197], v[210:213], v[2:17]
	s_waitcnt vmcnt(7)
	ds_write_b128 v189, v[142:145] offset:13824
	v_mfma_f32_32x32x16_bf16 v[114:129], v[214:217], v[224:227], v[114:129]
	ds_write_b128 v189, v[146:149] offset:18432
	v_mfma_f32_32x32x16_bf16 v[50:65], v[218:221], v[224:227], v[50:65]
	s_waitcnt vmcnt(6)
	ds_write_b128 v189, v[150:153] offset:23040
	v_mfma_f32_32x32x16_bf16 v[98:113], v[214:217], v[234:237], v[98:113]
	s_waitcnt vmcnt(5)
	ds_write_b128 v189, v[154:157] offset:27648
	v_mfma_f32_32x32x16_bf16 v[34:49], v[218:221], v[234:237], v[34:49]
	s_waitcnt vmcnt(4)
	ds_write_b128 v189, v[158:161] offset:32256
	v_mfma_f32_32x32x16_bf16 v[82:97], v[214:217], v[238:241], v[82:97]
	s_waitcnt vmcnt(3)
	ds_write_b128 v189, v[162:165] offset:36864
	v_mfma_f32_32x32x16_bf16 v[18:33], v[218:221], v[238:241], v[18:33]
	s_waitcnt vmcnt(2)
	ds_write_b128 v189, v[166:169] offset:41472
	v_mfma_f32_32x32x16_bf16 v[66:81], v[214:217], v[242:245], v[66:81]
	s_waitcnt vmcnt(1)
	ds_write_b128 v189, v[170:173] offset:46080
	v_mfma_f32_32x32x16_bf16 v[2:17], v[218:221], v[242:245], v[2:17]
	s_waitcnt vmcnt(0)
	ds_write_b128 v189, v[174:177] offset:50688
	s_setprio 0
	s_branch .LBB0_54

; __device__ __forceinline__ void lds_barrier() { asm volatile("s_waitcnt lgkmcnt(0)\n\ts_barrier" ::: "memory"); }
; __device__ __forceinline__ f32x16 mfma32(bf16x8 a, bf16x8 b, f32x16 c) { return __builtin_amdgcn_mfma_f32_32x32x16_bf16(a, b, c, 0, 0, 0); }
; __device__ __forceinline__ void gemm_big(const bf16_t* __restrict__ A, long lda, const bf16_t* __restrict__ Bt, int K, f32x16 (&acc)[2][4], unsigned char* lds) {
;     ...
;     for (int kc = 0; kc < nk; ++kc) {
;         bf16x8 af[2][2], bfr[2][4];
;         af[0][0] = *(const bf16x8*)(Ac); af[0][1] = *(const bf16x8*)(Ac + 32 * GLD);
; #pragma unroll
;         for (int ni = 0; ni < 4; ++ni) bfr[0][ni] = *(const bf16x8*)(Bc + ni * 32 * GLD);
;         __builtin_amdgcn_s_setprio(3);
; #pragma unroll
;         for (int ks = 0; ks < 4; ++ks) {
;             const int cb = ks & 1, nb = cb ^ 1;
;             if (ks < 3) {
;                 af[nb][0] = *(const bf16x8*)(Ac + (ks + 1) * 16); af[nb][1] = *(const bf16x8*)(Ac + 32 * GLD + (ks + 1) * 16);
; #pragma unroll
;                 for (int ni = 0; ni < 4; ++ni) bfr[nb][ni] = *(const bf16x8*)(Bc + ni * 32 * GLD + (ks + 1) * 16);
;             }
;             __builtin_amdgcn_sched_barrier(0);
; #pragma unroll
;             for (int ni = 0; ni < 4; ++ni) { acc[0][ni] = mfma32(af[cb][0], bfr[cb][ni], acc[0][ni]); acc[1][ni] = mfma32(af[cb][1], bfr[cb][ni], acc[1][ni]); }
;             __builtin_amdgcn_sched_barrier(0);
;         }
;         __builtin_amdgcn_s_setprio(0);
;         lds_barrier();
;         if (kc + 1 < nk) {
;             lstore();
;             if (kc + 2 < nk) gload(kc + 2);
;             lds_barrier();
;         }
.LBB0_67:
	s_cmp_gt_u32 s5, 14
	s_cbranch_scc1 .Lmy_gorig_7
	ds_read_b128 v[190:193], v187
	ds_read_b128 v[194:197], v187 offset:4608
	ds_read_b128 v[198:201], v188 offset:18432
	ds_read_b128 v[202:205], v188 offset:23040
	ds_read_b128 v[206:209], v188 offset:27648
	ds_read_b128 v[210:213], v188 offset:32256
	s_setprio 3
	ds_read_b128 v[214:217], v187 offset:32
	ds_read_b128 v[218:221], v187 offset:4640
	ds_read_b128 v[224:227], v188 offset:18464
	ds_read_b128 v[234:237], v188 offset:23072
	ds_read_b128 v[238:241], v188 offset:27680
	ds_read_b128 v[242:245], v188 offset:32288
	s_waitcnt lgkmcnt(9)
	v_mfma_f32_32x32x16_bf16 v[114:129], v[190:193], v[198:201], v[114:129]
	v_mfma_f32_32x32x16_bf16 v[82:97], v[194:197], v[198:201], v[82:97]
	s_waitcnt lgkmcnt(8)
	v_mfma_f32_32x32x16_bf16 v[98:113], v[190:193], v[202:205], v[98:113]
	v_mfma_f32_32x32x16_bf16 v[66:81], v[194:197], v[202:205], v[66:81]
	s_waitcnt lgkmcnt(7)
	v_mfma_f32_32x32x16_bf16 v[50:65], v[190:193], v[206:209], v[50:65]
	v_mfma_f32_32x32x16_bf16 v[18:33], v[194:197], v[206:209], v[18:33]
	s_waitcnt lgkmcnt(6)
	v_mfma_f32_32x32x16_bf16 v[34:49], v[190:193], v[210:213], v[34:49]
	v_mfma_f32_32x32x16_bf16 v[2:17], v[194:197], v[210:213], v[2:17]
	ds_read_b128 v[190:193], v187 offset:64
	ds_read_b128 v[194:197], v187 offset:4672
	ds_read_b128 v[198:201], v188 offset:18496
	ds_read_b128 v[202:205], v188 offset:23104
	ds_read_b128 v[206:209], v188 offset:27712
	ds_read_b128 v[210:213], v188 offset:32320
	s_waitcnt lgkmcnt(9)
	v_mfma_f32_32x32x16_bf16 v[114:129], v[214:217], v[224:227], v[114:129]
	v_mfma_f32_32x32x16_bf16 v[82:97], v[218:221], v[224:227], v[82:97]
	s_waitcnt lgkmcnt(8)
	v_mfma_f32_32x32x16_bf16 v[98:113], v[214:217], v[234:237], v[98:113]
	v_mfma_f32_32x32x16_bf16 v[66:81], v[218:221], v[234:237], v[66:81]
	s_waitcnt lgkmcnt(7)
	v_mfma_f32_32x32x16_bf16 v[50:65], v[214:217], v[238:241], v[50:65]
	v_mfma_f32_32x32x16_bf16 v[18:33], v[218:221], v[238:241], v[18:33]
	s_waitcnt lgkmcnt(6)
	v_mfma_f32_32x32x16_bf16 v[34:49], v[214:217], v[242:245], v[34:49]
	v_mfma_f32_32x32x16_bf16 v[2:17], v[218:221], v[242:245], v[2:17]
	ds_read_b128 v[214:217], v187 offset:96
	ds_read_b128 v[218:221], v187 offset:4704
	ds_read_b128 v[224:227], v188 offset:18528
	ds_read_b128 v[234:237], v188 offset:23136
	ds_read_b128 v[238:241], v188 offset:27744
	ds_read_b128 v[242:245], v188 offset:32352
	s_waitcnt lgkmcnt(9)
	v_mfma_f32_32x32x16_bf16 v[114:129], v[190:193], v[198:201], v[114:129]
	v_mfma_f32_32x32x16_bf16 v[82:97], v[194:197], v[198:201], v[82:97]
	s_waitcnt lgkmcnt(8)
	v_mfma_f32_32x32x16_bf16 v[98:113], v[190:193], v[202:205], v[98:113]
	v_mfma_f32_32x32x16_bf16 v[66:81], v[194:197], v[202:205], v[66:81]
	s_waitcnt lgkmcnt(0)
	s_barrier
	s_cmpk_eq_i32 s6, 0x700
	s_cbranch_scc1 .Lmy_gB_7
	v_mfma_f32_32x32x16_bf16 v[50:65], v[190:193], v[206:209], v[50:65]
	s_waitcnt vmcnt(9)
	ds_write_b128 v189, v[130:133]
	v_mfma_f32_32x32x16_bf16 v[18:33], v[194:197], v[206:209], v[18:33]
	ds_write_b128 v189, v[134:137] offset:4608
	v_mfma_f32_32x32x16_bf16 v[34:49], v[190:193], v[210:213], v[34:49]
	ds_write_b128 v189, v[138:141] offset:9216
	s_add_u32 vcc_lo, s6, 0x38a8000
	s_addc_u32 vcc_hi, s7, 0
	s_nop 0
	v_lshl_add_u64 v[130:131], v[184:185], 0, vcc
	global_load_dwordx4 v[130:133], v[130:131], off offset:256
	v_mfma_f32_32x32x16_bf16 v[2:17], v[194:197], v[210:213], v[2:17]
	s_waitcnt vmcnt(8)
	ds_write_b128 v189, v[142:145] offset:13824
	s_add_u32 vcc_lo, s6, 0x38b8000
	s_addc_u32 vcc_hi, s7, 0
	s_nop 0
	v_lshl_add_u64 v[134:135], v[184:185], 0, vcc
	global_load_dwordx4 v[134:137], v[134:135], off offset:256
	v_mfma_f32_32x32x16_bf16 v[114:129], v[214:217], v[224:227], v[114:129]
	ds_write_b128 v189, v[146:149] offset:18432
	s_add_u32 vcc_lo, s6, 0x38c8000
	s_addc_u32 vcc_hi, s7, 0
	s_nop 0
	v_lshl_add_u64 v[138:139], v[184:185], 0, vcc
	global_load_dwordx4 v[138:141], v[138:139], off offset:256
	v_mfma_f32_32x32x16_bf16 v[82:97], v[218:221], v[224:227], v[82:97]
	s_waitcnt vmcnt(9)
	ds_write_b128 v189, v[150:153] offset:23040
	s_add_u32 vcc_lo, s6, 0x38d8000
	s_addc_u32 vcc_hi, s7, 0
	s_nop 0
	v_lshl_add_u64 v[142:143], v[184:185], 0, vcc
	global_load_dwordx4 v[142:145], v[142:143], off offset:256
	v_mfma_f32_32x32x16_bf16 v[98:113], v[214:217], v[234:237], v[98:113]
	s_waitcnt vmcnt(9)
	ds_write_b128 v189, v[154:157] offset:27648
	s_add_u32 vcc_lo, s6, 0x2828000
	s_addc_u32 vcc_hi, s7, 0
	s_nop 0
	v_lshl_add_u64 v[146:147], v[182:183], 0, vcc
	global_load_dwordx4 v[146:149], v[146:147], off offset:256
	v_mfma_f32_32x32x16_bf16 v[66:81], v[218:221], v[234:237], v[66:81]
	s_waitcnt vmcnt(9)
	ds_write_b128 v189, v[158:161] offset:32256
	s_add_u32 vcc_lo, s6, 0x2838000
	s_addc_u32 vcc_hi, s7, 0
	s_nop 0
	v_lshl_add_u64 v[150:151], v[182:183], 0, vcc
	global_load_dwordx4 v[150:153], v[150:151], off offset:256
	v_mfma_f32_32x32x16_bf16 v[50:65], v[214:217], v[238:241], v[50:65]
	s_waitcnt vmcnt(9)
	ds_write_b128 v189, v[162:165] offset:36864
	s_add_u32 vcc_lo, s6, 0x2848000
	s_addc_u32 vcc_hi, s7, 0
	s_nop 0
	v_lshl_add_u64 v[154:155], v[182:183], 0, vcc
	global_load_dwordx4 v[154:157], v[154:155], off offset:256
	v_mfma_f32_32x32x16_bf16 v[18:33], v[218:221], v[238:241], v[18:33]
	s_waitcnt vmcnt(9)
	ds_write_b128 v189, v[166:169] offset:41472
	s_add_u32 vcc_lo, s6, 0x2858000
	s_addc_u32 vcc_hi, s7, 0
	s_nop 0
	v_lshl_add_u64 v[158:159], v[182:183], 0, vcc
	global_load_dwordx4 v[158:161], v[158:159], off offset:256
	v_mfma_f32_32x32x16_bf16 v[34:49], v[214:217], v[242:245], v[34:49]
	s_waitcnt vmcnt(9)
	ds_write_b128 v189, v[170:173] offset:46080
	s_add_u32 vcc_lo, s6, 0x2868000
	s_addc_u32 vcc_hi, s7, 0
	s_nop 0
	v_lshl_add_u64 v[162:163], v[182:183], 0, vcc
	global_load_dwordx4 v[162:165], v[162:163], off offset:256
	v_mfma_f32_32x32x16_bf16 v[2:17], v[218:221], v[242:245], v[2:17]
	s_waitcnt vmcnt(9)
	ds_write_b128 v189, v[174:177] offset:50688
	s_add_u32 vcc_lo, s6, 0x2878000
	s_addc_u32 vcc_hi, s7, 0
	s_nop 0
	v_lshl_add_u64 v[166:167], v[182:183], 0, vcc
	global_load_dwordx4 v[166:169], v[166:167], off offset:256
	s_add_u32 vcc_lo, s6, 0x2888000
	s_addc_u32 vcc_hi, s7, 0
	s_nop 0
	v_lshl_add_u64 v[170:171], v[182:183], 0, vcc
	global_load_dwordx4 v[170:173], v[170:171], off offset:256
	s_add_u32 vcc_lo, s6, 0x2898000
	s_addc_u32 vcc_hi, s7, 0
	s_nop 0
	v_lshl_add_u64 v[174:175], v[182:183], 0, vcc
	global_load_dwordx4 v[174:177], v[174:175], off offset:256
	s_setprio 0
	s_branch .LBB0_65
; __device__ __forceinline__ void lds_barrier() { asm volatile("s_waitcnt lgkmcnt(0)\n\ts_barrier" ::: "memory"); }
; __device__ __forceinline__ f32x16 mfma32(bf16x8 a, bf16x8 b, f32x16 c) { return __builtin_amdgcn_mfma_f32_32x32x16_bf16(a, b, c, 0, 0, 0); }
; __device__ __forceinline__ void gemm_big(const bf16_t* __restrict__ A, long lda, const bf16_t* __restrict__ Bt, int K, f32x16 (&acc)[2][4], unsigned char* lds) {
;     ...
;                 af[nb][0] = *(const bf16x8*)(Ac + (ks + 1) * 16); af[nb][1] = *(const bf16x8*)(Ac + 32 * GLD + (ks + 1) * 16);
; #pragma unroll
;                 for (int ni = 0; ni < 4; ++ni) bfr[nb][ni] = *(const bf16x8*)(Bc + ni * 32 * GLD + (ks + 1) * 16);
;             }
;             __builtin_amdgcn_sched_barrier(0);
; #pragma unroll
;             for (int ni = 0; ni < 4; ++ni) { acc[0][ni] = mfma32(af[cb][0], bfr[cb][ni], acc[0][ni]); acc[1][ni] = mfma32(af[cb][1], bfr[cb][ni], acc[1][ni]); }
;             __builtin_amdgcn_sched_barrier(0);
;         }
;         __builtin_amdgcn_s_setprio(0);
;         lds_barrier();
;         if (kc + 1 < nk) {
;             lstore();
;             if (kc + 2 < nk) gload(kc + 2);
;             lds_barrier();
.Lmy_gB_7:
	v_mfma_f32_32x32x16_bf16 v[50:65], v[190:193], v[206:209], v[50:65]
	s_waitcnt vmcnt(9)
	ds_write_b128 v189, v[130:133]
	v_mfma_f32_32x32x16_bf16 v[18:33], v[194:197], v[206:209], v[18:33]
	ds_write_b128 v189, v[134:137] offset:4608
	v_mfma_f32_32x32x16_bf16 v[34:49], v[190:193], v[210:213], v[34:49]
	ds_write_b128 v189, v[138:141] offset:9216
	v_mfma_f32_32x32x16_bf16 v[2:17], v[194:197], v[210:213], v[2:17]
	s_waitcnt vmcnt(7)
	ds_write_b128 v189, v[142:145] offset:13824
	v_mfma_f32_32x32x16_bf16 v[114:129], v[214:217], v[224:227], v[114:129]
	ds_write_b128 v189, v[146:149] offset:18432
	v_mfma_f32_32x32x16_bf16 v[82:97], v[218:221], v[224:227], v[82:97]
	s_waitcnt vmcnt(6)
	ds_write_b128 v189, v[150:153] offset:23040
	v_mfma_f32_32x32x16_bf16 v[98:113], v[214:217], v[234:237], v[98:113]
	s_waitcnt vmcnt(5)
	ds_write_b128 v189, v[154:157] offset:27648
	v_mfma_f32_32x32x16_bf16 v[66:81], v[218:221], v[234:237], v[66:81]
	s_waitcnt vmcnt(4)
	ds_write_b128 v189, v[158:161] offset:32256
	v_mfma_f32_32x32x16_bf16 v[50:65], v[214:217], v[238:241], v[50:65]
	s_waitcnt vmcnt(3)
	ds_write_b128 v189, v[162:165] offset:36864
	v_mfma_f32_32x32x16_bf16 v[18:33], v[218:221], v[238:241], v[18:33]
	s_waitcnt vmcnt(2)
	ds_write_b128 v189, v[166:169] offset:41472
	v_mfma_f32_32x32x16_bf16 v[34:49], v[214:217], v[242:245], v[34:49]
	s_waitcnt vmcnt(1)
	ds_write_b128 v189, v[170:173] offset:46080
	v_mfma_f32_32x32x16_bf16 v[2:17], v[218:221], v[242:245], v[2:17]
	s_waitcnt vmcnt(0)
	ds_write_b128 v189, v[174:177] offset:50688
	s_setprio 0
	s_branch .LBB0_65

; __device__ __forceinline__ void lds_barrier() { asm volatile("s_waitcnt lgkmcnt(0)\n\ts_barrier" ::: "memory"); }
; __device__ __forceinline__ f32x16 mfma32(bf16x8 a, bf16x8 b, f32x16 c) { return __builtin_amdgcn_mfma_f32_32x32x16_bf16(a, b, c, 0, 0, 0); }
; __device__ __forceinline__ void gemm_big(const bf16_t* __restrict__ A, long lda, const bf16_t* __restrict__ Bt, int K, f32x16 (&acc)[2][4], unsigned char* lds) {
;     ...
;     for (int kc = 0; kc < nk; ++kc) {
;         bf16x8 af[2][2], bfr[2][4];
;         af[0][0] = *(const bf16x8*)(Ac); af[0][1] = *(const bf16x8*)(Ac + 32 * GLD);
; #pragma unroll
;         for (int ni = 0; ni < 4; ++ni) bfr[0][ni] = *(const bf16x8*)(Bc + ni * 32 * GLD);
;         __builtin_amdgcn_s_setprio(3);
; #pragma unroll
;         for (int ks = 0; ks < 4; ++ks) {
;             const int cb = ks & 1, nb = cb ^ 1;
;             if (ks < 3) {
;                 af[nb][0] = *(const bf16x8*)(Ac + (ks + 1) * 16); af[nb][1] = *(const bf16x8*)(Ac + 32 * GLD + (ks + 1) * 16);
; #pragma unroll
;                 for (int ni = 0; ni < 4; ++ni) bfr[nb][ni] = *(const bf16x8*)(Bc + ni * 32 * GLD + (ks + 1) * 16);
;             }
;             __builtin_amdgcn_sched_barrier(0);
; #pragma unroll
;             for (int ni = 0; ni < 4; ++ni) { acc[0][ni] = mfma32(af[cb][0], bfr[cb][ni], acc[0][ni]); acc[1][ni] = mfma32(af[cb][1], bfr[cb][ni], acc[1][ni]); }
;             __builtin_amdgcn_sched_barrier(0);
;         }
;         __builtin_amdgcn_s_setprio(0);
;         lds_barrier();
;         if (kc + 1 < nk) {
;             lstore();
;             if (kc + 2 < nk) gload(kc + 2);
;             lds_barrier();
;         }
.LBB0_84:
	s_cmp_gt_u32 s5, 14
	s_cbranch_scc1 .Lmy_gorig_6
	ds_read_b128 v[190:193], v187
	ds_read_b128 v[194:197], v187 offset:4608
	ds_read_b128 v[198:201], v188 offset:18432
	ds_read_b128 v[202:205], v188 offset:23040
	ds_read_b128 v[206:209], v188 offset:27648
	ds_read_b128 v[210:213], v188 offset:32256
	s_setprio 3
	ds_read_b128 v[214:217], v187 offset:32
	ds_read_b128 v[218:221], v187 offset:4640
	ds_read_b128 v[224:227], v188 offset:18464
	ds_read_b128 v[234:237], v188 offset:23072
	ds_read_b128 v[238:241], v188 offset:27680
	ds_read_b128 v[242:245], v188 offset:32288
	s_waitcnt lgkmcnt(9)
	v_mfma_f32_32x32x16_bf16 v[114:129], v[190:193], v[198:201], v[114:129]
	v_mfma_f32_32x32x16_bf16 v[50:65], v[194:197], v[198:201], v[50:65]
	s_waitcnt lgkmcnt(8)
	v_mfma_f32_32x32x16_bf16 v[98:113], v[190:193], v[202:205], v[98:113]
	v_mfma_f32_32x32x16_bf16 v[34:49], v[194:197], v[202:205], v[34:49]
	s_waitcnt lgkmcnt(7)
	v_mfma_f32_32x32x16_bf16 v[82:97], v[190:193], v[206:209], v[82:97]
	v_mfma_f32_32x32x16_bf16 v[18:33], v[194:197], v[206:209], v[18:33]
	s_waitcnt lgkmcnt(6)
	v_mfma_f32_32x32x16_bf16 v[66:81], v[190:193], v[210:213], v[66:81]
	v_mfma_f32_32x32x16_bf16 v[2:17], v[194:197], v[210:213], v[2:17]
	ds_read_b128 v[190:193], v187 offset:64
	ds_read_b128 v[194:197], v187 offset:4672
	ds_read_b128 v[198:201], v188 offset:18496
	ds_read_b128 v[202:205], v188 offset:23104
	ds_read_b128 v[206:209], v188 offset:27712
	ds_read_b128 v[210:213], v188 offset:32320
	s_waitcnt lgkmcnt(9)
	v_mfma_f32_32x32x16_bf16 v[114:129], v[214:217], v[224:227], v[114:129]
	v_mfma_f32_32x32x16_bf16 v[50:65], v[218:221], v[224:227], v[50:65]
	s_waitcnt lgkmcnt(8)
	v_mfma_f32_32x32x16_bf16 v[98:113], v[214:217], v[234:237], v[98:113]
	v_mfma_f32_32x32x16_bf16 v[34:49], v[218:221], v[234:237], v[34:49]
	s_waitcnt lgkmcnt(7)
	v_mfma_f32_32x32x16_bf16 v[82:97], v[214:217], v[238:241], v[82:97]
	v_mfma_f32_32x32x16_bf16 v[18:33], v[218:221], v[238:241], v[18:33]
	s_waitcnt lgkmcnt(6)
	v_mfma_f32_32x32x16_bf16 v[66:81], v[214:217], v[242:245], v[66:81]
	v_mfma_f32_32x32x16_bf16 v[2:17], v[218:221], v[242:245], v[2:17]
	ds_read_b128 v[214:217], v187 offset:96
	ds_read_b128 v[218:221], v187 offset:4704
	ds_read_b128 v[224:227], v188 offset:18528
	ds_read_b128 v[234:237], v188 offset:23136
	ds_read_b128 v[238:241], v188 offset:27744
	ds_read_b128 v[242:245], v188 offset:32352
	s_waitcnt lgkmcnt(9)
	v_mfma_f32_32x32x16_bf16 v[114:129], v[190:193], v[198:201], v[114:129]
	v_mfma_f32_32x32x16_bf16 v[50:65], v[194:197], v[198:201], v[50:65]
	s_waitcnt lgkmcnt(8)
	v_mfma_f32_32x32x16_bf16 v[98:113], v[190:193], v[202:205], v[98:113]
	v_mfma_f32_32x32x16_bf16 v[34:49], v[194:197], v[202:205], v[34:49]
	s_waitcnt lgkmcnt(0)
	s_barrier
	s_cmpk_eq_i32 s6, 0x700
	s_cbranch_scc1 .Lmy_gB_6
	v_mfma_f32_32x32x16_bf16 v[82:97], v[190:193], v[206:209], v[82:97]
	s_waitcnt vmcnt(9)
	ds_write_b128 v189, v[130:133]
	v_mfma_f32_32x32x16_bf16 v[18:33], v[194:197], v[206:209], v[18:33]
	ds_write_b128 v189, v[134:137] offset:4608
	v_mfma_f32_32x32x16_bf16 v[66:81], v[190:193], v[210:213], v[66:81]
	ds_write_b128 v189, v[138:141] offset:9216
	s_add_u32 vcc_lo, s6, 0x14948000
	s_addc_u32 vcc_hi, s7, 0
	s_nop 0
	v_lshl_add_u64 v[130:131], v[184:185], 0, vcc
	global_load_dwordx4 v[130:133], v[130:131], off offset:256
	v_mfma_f32_32x32x16_bf16 v[2:17], v[194:197], v[210:213], v[2:17]
	s_waitcnt vmcnt(8)
	ds_write_b128 v189, v[142:145] offset:13824
	s_add_u32 vcc_lo, s6, 0x14958000
	s_addc_u32 vcc_hi, s7, 0
	s_nop 0
	v_lshl_add_u64 v[134:135], v[184:185], 0, vcc
	global_load_dwordx4 v[134:137], v[134:135], off offset:256
	v_mfma_f32_32x32x16_bf16 v[114:129], v[214:217], v[224:227], v[114:129]
	ds_write_b128 v189, v[146:149] offset:18432
	s_add_u32 vcc_lo, s6, 0x14968000
	s_addc_u32 vcc_hi, s7, 0
	s_nop 0
	v_lshl_add_u64 v[138:139], v[184:185], 0, vcc
	global_load_dwordx4 v[138:141], v[138:139], off offset:256
	v_mfma_f32_32x32x16_bf16 v[50:65], v[218:221], v[224:227], v[50:65]
	s_waitcnt vmcnt(9)
	ds_write_b128 v189, v[150:153] offset:23040
	s_add_u32 vcc_lo, s6, 0x14978000
	s_addc_u32 vcc_hi, s7, 0
	s_nop 0
	v_lshl_add_u64 v[142:143], v[184:185], 0, vcc
	global_load_dwordx4 v[142:145], v[142:143], off offset:256
	v_mfma_f32_32x32x16_bf16 v[98:113], v[214:217], v[234:237], v[98:113]
	s_waitcnt vmcnt(9)
	ds_write_b128 v189, v[154:157] offset:27648
	s_add_u32 vcc_lo, s6, 0x2628000
	s_addc_u32 vcc_hi, s7, 0
	s_nop 0
	v_lshl_add_u64 v[146:147], v[182:183], 0, vcc
	global_load_dwordx4 v[146:149], v[146:147], off offset:256
	v_mfma_f32_32x32x16_bf16 v[34:49], v[218:221], v[234:237], v[34:49]
	s_waitcnt vmcnt(9)
	ds_write_b128 v189, v[158:161] offset:32256
	s_add_u32 vcc_lo, s6, 0x2638000
	s_addc_u32 vcc_hi, s7, 0
	s_nop 0
	v_lshl_add_u64 v[150:151], v[182:183], 0, vcc
	global_load_dwordx4 v[150:153], v[150:151], off offset:256
	v_mfma_f32_32x32x16_bf16 v[82:97], v[214:217], v[238:241], v[82:97]
	s_waitcnt vmcnt(9)
	ds_write_b128 v189, v[162:165] offset:36864
	s_add_u32 vcc_lo, s6, 0x2648000
	s_addc_u32 vcc_hi, s7, 0
	s_nop 0
	v_lshl_add_u64 v[154:155], v[182:183], 0, vcc
	global_load_dwordx4 v[154:157], v[154:155], off offset:256
	v_mfma_f32_32x32x16_bf16 v[18:33], v[218:221], v[238:241], v[18:33]
	s_waitcnt vmcnt(9)
	ds_write_b128 v189, v[166:169] offset:41472
	s_add_u32 vcc_lo, s6, 0x2658000
	s_addc_u32 vcc_hi, s7, 0
	s_nop 0
	v_lshl_add_u64 v[158:159], v[182:183], 0, vcc
	global_load_dwordx4 v[158:161], v[158:159], off offset:256
	v_mfma_f32_32x32x16_bf16 v[66:81], v[214:217], v[242:245], v[66:81]
	s_waitcnt vmcnt(9)
	ds_write_b128 v189, v[170:173] offset:46080
	s_add_u32 vcc_lo, s6, 0x2668000
	s_addc_u32 vcc_hi, s7, 0
	s_nop 0
	v_lshl_add_u64 v[162:163], v[182:183], 0, vcc
	global_load_dwordx4 v[162:165], v[162:163], off offset:256
	v_mfma_f32_32x32x16_bf16 v[2:17], v[218:221], v[242:245], v[2:17]
	s_waitcnt vmcnt(9)
	ds_write_b128 v189, v[174:177] offset:50688
	s_add_u32 vcc_lo, s6, 0x2678000
	s_addc_u32 vcc_hi, s7, 0
	s_nop 0
	v_lshl_add_u64 v[166:167], v[182:183], 0, vcc
	global_load_dwordx4 v[166:169], v[166:167], off offset:256
	s_add_u32 vcc_lo, s6, 0x2688000
	s_addc_u32 vcc_hi, s7, 0
	s_nop 0
	v_lshl_add_u64 v[170:171], v[182:183], 0, vcc
	global_load_dwordx4 v[170:173], v[170:171], off offset:256
	s_add_u32 vcc_lo, s6, 0x2698000
	s_addc_u32 vcc_hi, s7, 0
	s_nop 0
	v_lshl_add_u64 v[174:175], v[182:183], 0, vcc
	global_load_dwordx4 v[174:177], v[174:175], off offset:256
	s_setprio 0
	s_branch .LBB0_82

; __device__ __forceinline__ void lds_barrier() { asm volatile("s_waitcnt lgkmcnt(0)\n\ts_barrier" ::: "memory"); }
; __device__ __forceinline__ f32x16 mfma32(bf16x8 a, bf16x8 b, f32x16 c) { return __builtin_amdgcn_mfma_f32_32x32x16_bf16(a, b, c, 0, 0, 0); }
; __device__ __forceinline__ void gemm_big(const bf16_t* __restrict__ A, long lda, const bf16_t* __restrict__ Bt, int K, f32x16 (&acc)[2][4], unsigned char* lds) {
;     ...
;     for (int kc = 0; kc < nk; ++kc) {
;         bf16x8 af[2][2], bfr[2][4];
;         af[0][0] = *(const bf16x8*)(Ac); af[0][1] = *(const bf16x8*)(Ac + 32 * GLD);
; #pragma unroll
;         for (int ni = 0; ni < 4; ++ni) bfr[0][ni] = *(const bf16x8*)(Bc + ni * 32 * GLD);
;         __builtin_amdgcn_s_setprio(3);
; #pragma unroll
;         for (int ks = 0; ks < 4; ++ks) {
;             const int cb = ks & 1, nb = cb ^ 1;
;             if (ks < 3) {
;                 af[nb][0] = *(const bf16x8*)(Ac + (ks + 1) * 16); af[nb][1] = *(const bf16x8*)(Ac + 32 * GLD + (ks + 1) * 16);
; #pragma unroll
;                 for (int ni = 0; ni < 4; ++ni) bfr[nb][ni] = *(const bf16x8*)(Bc + ni * 32 * GLD + (ks + 1) * 16);
;             }
;             __builtin_amdgcn_sched_barrier(0);
; #pragma unroll
;             for (int ni = 0; ni < 4; ++ni) { acc[0][ni] = mfma32(af[cb][0], bfr[cb][ni], acc[0][ni]); acc[1][ni] = mfma32(af[cb][1], bfr[cb][ni], acc[1][ni]); }
;             __builtin_amdgcn_sched_barrier(0);
;         }
;         __builtin_amdgcn_s_setprio(0);
;         lds_barrier();
;         if (kc + 1 < nk) {
;             lstore();
;             if (kc + 2 < nk) gload(kc + 2);
;             lds_barrier();
;         }
.LBB0_115:
	s_cmp_gt_u32 s5, 14
	s_cbranch_scc1 .Lmy_gorig_5
	ds_read_b128 v[190:193], v187
	ds_read_b128 v[194:197], v187 offset:4608
	ds_read_b128 v[198:201], v188 offset:18432
	ds_read_b128 v[202:205], v188 offset:23040
	ds_read_b128 v[206:209], v188 offset:27648
	ds_read_b128 v[210:213], v188 offset:32256
	s_setprio 3
	ds_read_b128 v[214:217], v187 offset:32
	ds_read_b128 v[218:221], v187 offset:4640
	ds_read_b128 v[224:227], v188 offset:18464
	ds_read_b128 v[234:237], v188 offset:23072
	ds_read_b128 v[238:241], v188 offset:27680
	ds_read_b128 v[242:245], v188 offset:32288
	s_waitcnt lgkmcnt(9)
	v_mfma_f32_32x32x16_bf16 v[114:129], v[190:193], v[198:201], v[114:129]
	v_mfma_f32_32x32x16_bf16 v[98:113], v[194:197], v[198:201], v[98:113]
	s_waitcnt lgkmcnt(8)
	v_mfma_f32_32x32x16_bf16 v[82:97], v[190:193], v[202:205], v[82:97]
	v_mfma_f32_32x32x16_bf16 v[66:81], v[194:197], v[202:205], v[66:81]
	s_waitcnt lgkmcnt(7)
	v_mfma_f32_32x32x16_bf16 v[50:65], v[190:193], v[206:209], v[50:65]
	v_mfma_f32_32x32x16_bf16 v[34:49], v[194:197], v[206:209], v[34:49]
	s_waitcnt lgkmcnt(6)
	v_mfma_f32_32x32x16_bf16 v[18:33], v[190:193], v[210:213], v[18:33]
	v_mfma_f32_32x32x16_bf16 v[2:17], v[194:197], v[210:213], v[2:17]
	ds_read_b128 v[190:193], v187 offset:64
	ds_read_b128 v[194:197], v187 offset:4672
	ds_read_b128 v[198:201], v188 offset:18496
	ds_read_b128 v[202:205], v188 offset:23104
	ds_read_b128 v[206:209], v188 offset:27712
	ds_read_b128 v[210:213], v188 offset:32320
	s_waitcnt lgkmcnt(9)
	v_mfma_f32_32x32x16_bf16 v[114:129], v[214:217], v[224:227], v[114:129]
	v_mfma_f32_32x32x16_bf16 v[98:113], v[218:221], v[224:227], v[98:113]
	s_waitcnt lgkmcnt(8)
	v_mfma_f32_32x32x16_bf16 v[82:97], v[214:217], v[234:237], v[82:97]
	v_mfma_f32_32x32x16_bf16 v[66:81], v[218:221], v[234:237], v[66:81]
	s_waitcnt lgkmcnt(7)
	v_mfma_f32_32x32x16_bf16 v[50:65], v[214:217], v[238:241], v[50:65]
	v_mfma_f32_32x32x16_bf16 v[34:49], v[218:221], v[238:241], v[34:49]
	s_waitcnt lgkmcnt(6)
	v_mfma_f32_32x32x16_bf16 v[18:33], v[214:217], v[242:245], v[18:33]
	v_mfma_f32_32x32x16_bf16 v[2:17], v[218:221], v[242:245], v[2:17]
	ds_read_b128 v[214:217], v187 offset:96
	ds_read_b128 v[218:221], v187 offset:4704
	ds_read_b128 v[224:227], v188 offset:18528
	ds_read_b128 v[234:237], v188 offset:23136
	ds_read_b128 v[238:241], v188 offset:27744
	ds_read_b128 v[242:245], v188 offset:32352
	s_waitcnt lgkmcnt(9)
	v_mfma_f32_32x32x16_bf16 v[114:129], v[190:193], v[198:201], v[114:129]
	v_mfma_f32_32x32x16_bf16 v[98:113], v[194:197], v[198:201], v[98:113]
	s_waitcnt lgkmcnt(8)
	v_mfma_f32_32x32x16_bf16 v[82:97], v[190:193], v[202:205], v[82:97]
	v_mfma_f32_32x32x16_bf16 v[66:81], v[194:197], v[202:205], v[66:81]
	s_waitcnt lgkmcnt(0)
	s_barrier
	s_cmpk_eq_i32 s6, 0x700
	s_cbranch_scc1 .Lmy_gB_5
	v_mfma_f32_32x32x16_bf16 v[50:65], v[190:193], v[206:209], v[50:65]
	s_waitcnt vmcnt(9)
	ds_write_b128 v189, v[130:133]
	v_mfma_f32_32x32x16_bf16 v[34:49], v[194:197], v[206:209], v[34:49]
	ds_write_b128 v189, v[134:137] offset:4608
	v_mfma_f32_32x32x16_bf16 v[18:33], v[190:193], v[210:213], v[18:33]
	ds_write_b128 v189, v[138:141] offset:9216
	s_add_u32 vcc_lo, s6, 0x38a8000
	s_addc_u32 vcc_hi, s7, 0
	s_nop 0
	v_lshl_add_u64 v[130:131], v[184:185], 0, vcc
	global_load_dwordx4 v[130:133], v[130:131], off offset:256
	v_mfma_f32_32x32x16_bf16 v[2:17], v[194:197], v[210:213], v[2:17]
	s_waitcnt vmcnt(8)
	ds_write_b128 v189, v[142:145] offset:13824
	s_add_u32 vcc_lo, s6, 0x38b8000
	s_addc_u32 vcc_hi, s7, 0
	s_nop 0
	v_lshl_add_u64 v[134:135], v[184:185], 0, vcc
	global_load_dwordx4 v[134:137], v[134:135], off offset:256
	v_mfma_f32_32x32x16_bf16 v[114:129], v[214:217], v[224:227], v[114:129]
	ds_write_b128 v189, v[146:149] offset:18432
	s_add_u32 vcc_lo, s6, 0x38c8000
	s_addc_u32 vcc_hi, s7, 0
	s_nop 0
	v_lshl_add_u64 v[138:139], v[184:185], 0, vcc
	global_load_dwordx4 v[138:141], v[138:139], off offset:256
	v_mfma_f32_32x32x16_bf16 v[98:113], v[218:221], v[224:227], v[98:113]
	s_waitcnt vmcnt(9)
	ds_write_b128 v189, v[150:153] offset:23040
	s_add_u32 vcc_lo, s6, 0x38d8000
	s_addc_u32 vcc_hi, s7, 0
	s_nop 0
	v_lshl_add_u64 v[142:143], v[184:185], 0, vcc
	global_load_dwordx4 v[142:145], v[142:143], off offset:256
	v_mfma_f32_32x32x16_bf16 v[82:97], v[214:217], v[234:237], v[82:97]
	s_waitcnt vmcnt(9)
	ds_write_b128 v189, v[154:157] offset:27648
	s_add_u32 vcc_lo, s6, 0x1c88000
	s_addc_u32 vcc_hi, s7, 0
	s_nop 0
	v_lshl_add_u64 v[146:147], v[182:183], 0, vcc
	global_load_dwordx4 v[146:149], v[146:147], off offset:256
	v_mfma_f32_32x32x16_bf16 v[66:81], v[218:221], v[234:237], v[66:81]
	s_waitcnt vmcnt(9)
	ds_write_b128 v189, v[158:161] offset:32256
	s_add_u32 vcc_lo, s6, 0x1c98000
	s_addc_u32 vcc_hi, s7, 0
	s_nop 0
	v_lshl_add_u64 v[150:151], v[182:183], 0, vcc
	global_load_dwordx4 v[150:153], v[150:151], off offset:256
	v_mfma_f32_32x32x16_bf16 v[50:65], v[214:217], v[238:241], v[50:65]
	s_waitcnt vmcnt(9)
	ds_write_b128 v189, v[162:165] offset:36864
	s_add_u32 vcc_lo, s6, 0x1ca8000
	s_addc_u32 vcc_hi, s7, 0
	s_nop 0
	v_lshl_add_u64 v[154:155], v[182:183], 0, vcc
	global_load_dwordx4 v[154:157], v[154:155], off offset:256
	v_mfma_f32_32x32x16_bf16 v[34:49], v[218:221], v[238:241], v[34:49]
	s_waitcnt vmcnt(9)
	ds_write_b128 v189, v[166:169] offset:41472
	s_add_u32 vcc_lo, s6, 0x1cb8000
	s_addc_u32 vcc_hi, s7, 0
	s_nop 0
	v_lshl_add_u64 v[158:159], v[182:183], 0, vcc
	global_load_dwordx4 v[158:161], v[158:159], off offset:256
	v_mfma_f32_32x32x16_bf16 v[18:33], v[214:217], v[242:245], v[18:33]
	s_waitcnt vmcnt(9)
	ds_write_b128 v189, v[170:173] offset:46080
	s_add_u32 vcc_lo, s6, 0x1cc8000
	s_addc_u32 vcc_hi, s7, 0
	s_nop 0
	v_lshl_add_u64 v[162:163], v[182:183], 0, vcc
	global_load_dwordx4 v[162:165], v[162:163], off offset:256
	v_mfma_f32_32x32x16_bf16 v[2:17], v[218:221], v[242:245], v[2:17]
	s_waitcnt vmcnt(9)
	ds_write_b128 v189, v[174:177] offset:50688
	s_add_u32 vcc_lo, s6, 0x1cd8000
	s_addc_u32 vcc_hi, s7, 0
	s_nop 0
	v_lshl_add_u64 v[166:167], v[182:183], 0, vcc
	global_load_dwordx4 v[166:169], v[166:167], off offset:256
	s_add_u32 vcc_lo, s6, 0x1ce8000
	s_addc_u32 vcc_hi, s7, 0
	s_nop 0
	v_lshl_add_u64 v[170:171], v[182:183], 0, vcc
	global_load_dwordx4 v[170:173], v[170:171], off offset:256
	s_add_u32 vcc_lo, s6, 0x1cf8000
	s_addc_u32 vcc_hi, s7, 0
	s_nop 0
	v_lshl_add_u64 v[174:175], v[182:183], 0, vcc
	global_load_dwordx4 v[174:177], v[174:175], off offset:256
	s_setprio 0
	s_branch .LBB0_113
; __device__ __forceinline__ void lds_barrier() { asm volatile("s_waitcnt lgkmcnt(0)\n\ts_barrier" ::: "memory"); }
; __device__ __forceinline__ f32x16 mfma32(bf16x8 a, bf16x8 b, f32x16 c) { return __builtin_amdgcn_mfma_f32_32x32x16_bf16(a, b, c, 0, 0, 0); }
; __device__ __forceinline__ void gemm_big(const bf16_t* __restrict__ A, long lda, const bf16_t* __restrict__ Bt, int K, f32x16 (&acc)[2][4], unsigned char* lds) {
;     ...
;                 af[nb][0] = *(const bf16x8*)(Ac + (ks + 1) * 16); af[nb][1] = *(const bf16x8*)(Ac + 32 * GLD + (ks + 1) * 16);
; #pragma unroll
;                 for (int ni = 0; ni < 4; ++ni) bfr[nb][ni] = *(const bf16x8*)(Bc + ni * 32 * GLD + (ks + 1) * 16);
;             }
;             __builtin_amdgcn_sched_barrier(0);
; #pragma unroll
;             for (int ni = 0; ni < 4; ++ni) { acc[0][ni] = mfma32(af[cb][0], bfr[cb][ni], acc[0][ni]); acc[1][ni] = mfma32(af[cb][1], bfr[cb][ni], acc[1][ni]); }
;             __builtin_amdgcn_sched_barrier(0);
;         }
;         __builtin_amdgcn_s_setprio(0);
;         lds_barrier();
;         if (kc + 1 < nk) {
;             lstore();
;             if (kc + 2 < nk) gload(kc + 2);
;             lds_barrier();
.Lmy_gB_5:
	v_mfma_f32_32x32x16_bf16 v[50:65], v[190:193], v[206:209], v[50:65]
	s_waitcnt vmcnt(9)
	ds_write_b128 v189, v[130:133]
	v_mfma_f32_32x32x16_bf16 v[34:49], v[194:197], v[206:209], v[34:49]
	ds_write_b128 v189, v[134:137] offset:4608
	v_mfma_f32_32x32x16_bf16 v[18:33], v[190:193], v[210:213], v[18:33]
	ds_write_b128 v189, v[138:141] offset:9216
	v_mfma_f32_32x32x16_bf16 v[2:17], v[194:197], v[210:213], v[2:17]
	s_waitcnt vmcnt(7)
	ds_write_b128 v189, v[142:145] offset:13824
	v_mfma_f32_32x32x16_bf16 v[114:129], v[214:217], v[224:227], v[114:129]
	ds_write_b128 v189, v[146:149] offset:18432
	v_mfma_f32_32x32x16_bf16 v[98:113], v[218:221], v[224:227], v[98:113]
	s_waitcnt vmcnt(6)
	ds_write_b128 v189, v[150:153] offset:23040
	v_mfma_f32_32x32x16_bf16 v[82:97], v[214:217], v[234:237], v[82:97]
	s_waitcnt vmcnt(5)
	ds_write_b128 v189, v[154:157] offset:27648
	v_mfma_f32_32x32x16_bf16 v[66:81], v[218:221], v[234:237], v[66:81]
	s_waitcnt vmcnt(4)
	ds_write_b128 v189, v[158:161] offset:32256
	v_mfma_f32_32x32x16_bf16 v[50:65], v[214:217], v[238:241], v[50:65]
	s_waitcnt vmcnt(3)
	ds_write_b128 v189, v[162:165] offset:36864
	v_mfma_f32_32x32x16_bf16 v[34:49], v[218:221], v[238:241], v[34:49]
	s_waitcnt vmcnt(2)
	ds_write_b128 v189, v[166:169] offset:41472
	v_mfma_f32_32x32x16_bf16 v[18:33], v[214:217], v[242:245], v[18:33]
	s_waitcnt vmcnt(1)
	ds_write_b128 v189, v[170:173] offset:46080
	v_mfma_f32_32x32x16_bf16 v[2:17], v[218:221], v[242:245], v[2:17]
	s_waitcnt vmcnt(0)
	ds_write_b128 v189, v[174:177] offset:50688
	s_setprio 0
	s_branch .LBB0_113

; __device__ __forceinline__ void lds_barrier() { asm volatile("s_waitcnt lgkmcnt(0)\n\ts_barrier" ::: "memory"); }
; __device__ __forceinline__ f32x16 mfma32(bf16x8 a, bf16x8 b, f32x16 c) { return __builtin_amdgcn_mfma_f32_32x32x16_bf16(a, b, c, 0, 0, 0); }
; __device__ __forceinline__ void gemm_big(const bf16_t* __restrict__ A, long lda, const bf16_t* __restrict__ Bt, int K, f32x16 (&acc)[2][4], unsigned char* lds) {
;     ...
;     for (int kc = 0; kc < nk; ++kc) {
;         bf16x8 af[2][2], bfr[2][4];
;         af[0][0] = *(const bf16x8*)(Ac); af[0][1] = *(const bf16x8*)(Ac + 32 * GLD);
; #pragma unroll
;         for (int ni = 0; ni < 4; ++ni) bfr[0][ni] = *(const bf16x8*)(Bc + ni * 32 * GLD);
;         __builtin_amdgcn_s_setprio(3);
; #pragma unroll
;         for (int ks = 0; ks < 4; ++ks) {
;             const int cb = ks & 1, nb = cb ^ 1;
;             if (ks < 3) {
;                 af[nb][0] = *(const bf16x8*)(Ac + (ks + 1) * 16); af[nb][1] = *(const bf16x8*)(Ac + 32 * GLD + (ks + 1) * 16);
; #pragma unroll
;                 for (int ni = 0; ni < 4; ++ni) bfr[nb][ni] = *(const bf16x8*)(Bc + ni * 32 * GLD + (ks + 1) * 16);
;             }
;             __builtin_amdgcn_sched_barrier(0);
; #pragma unroll
;             for (int ni = 0; ni < 4; ++ni) { acc[0][ni] = mfma32(af[cb][0], bfr[cb][ni], acc[0][ni]); acc[1][ni] = mfma32(af[cb][1], bfr[cb][ni], acc[1][ni]); }
;             __builtin_amdgcn_sched_barrier(0);
;         }
;         __builtin_amdgcn_s_setprio(0);
;         lds_barrier();
;         if (kc + 1 < nk) {
;             lstore();
;             if (kc + 2 < nk) gload(kc + 2);
;             lds_barrier();
;         }
.LBB0_283:
	s_cmp_gt_u32 s5, 2
	s_cbranch_scc1 .Lmy_gorig_3
	ds_read_b128 v[192:195], v189
	ds_read_b128 v[196:199], v189 offset:4608
	ds_read_b128 v[200:203], v190 offset:18432
	ds_read_b128 v[204:207], v190 offset:23040
	ds_read_b128 v[208:211], v190 offset:27648
	ds_read_b128 v[212:215], v190 offset:32256
	s_setprio 3
	ds_read_b128 v[216:219], v189 offset:32
	ds_read_b128 v[224:227], v189 offset:4640
	ds_read_b128 v[234:237], v190 offset:18464
	ds_read_b128 v[238:241], v190 offset:23072
	ds_read_b128 v[242:245], v190 offset:27680
	ds_read_b128 v[246:249], v190 offset:32288
	s_waitcnt lgkmcnt(9)
	v_mfma_f32_32x32x16_bf16 v[114:129], v[192:195], v[200:203], v[114:129]
	v_mfma_f32_32x32x16_bf16 v[50:65], v[196:199], v[200:203], v[50:65]
	s_waitcnt lgkmcnt(8)
	v_mfma_f32_32x32x16_bf16 v[98:113], v[192:195], v[204:207], v[98:113]
	v_mfma_f32_32x32x16_bf16 v[34:49], v[196:199], v[204:207], v[34:49]
	s_waitcnt lgkmcnt(7)
	v_mfma_f32_32x32x16_bf16 v[82:97], v[192:195], v[208:211], v[82:97]
	v_mfma_f32_32x32x16_bf16 v[18:33], v[196:199], v[208:211], v[18:33]
	s_waitcnt lgkmcnt(6)
	v_mfma_f32_32x32x16_bf16 v[66:81], v[192:195], v[212:215], v[66:81]
	v_mfma_f32_32x32x16_bf16 v[2:17], v[196:199], v[212:215], v[2:17]
	ds_read_b128 v[192:195], v189 offset:64
	ds_read_b128 v[196:199], v189 offset:4672
	ds_read_b128 v[200:203], v190 offset:18496
	ds_read_b128 v[204:207], v190 offset:23104
	ds_read_b128 v[208:211], v190 offset:27712
	ds_read_b128 v[212:215], v190 offset:32320
	s_waitcnt lgkmcnt(9)
	v_mfma_f32_32x32x16_bf16 v[114:129], v[216:219], v[234:237], v[114:129]
	v_mfma_f32_32x32x16_bf16 v[50:65], v[224:227], v[234:237], v[50:65]
	s_waitcnt lgkmcnt(8)
	v_mfma_f32_32x32x16_bf16 v[98:113], v[216:219], v[238:241], v[98:113]
	v_mfma_f32_32x32x16_bf16 v[34:49], v[224:227], v[238:241], v[34:49]
	s_waitcnt lgkmcnt(7)
	v_mfma_f32_32x32x16_bf16 v[82:97], v[216:219], v[242:245], v[82:97]
	v_mfma_f32_32x32x16_bf16 v[18:33], v[224:227], v[242:245], v[18:33]
	s_waitcnt lgkmcnt(6)
	v_mfma_f32_32x32x16_bf16 v[66:81], v[216:219], v[246:249], v[66:81]
	v_mfma_f32_32x32x16_bf16 v[2:17], v[224:227], v[246:249], v[2:17]
	ds_read_b128 v[216:219], v189 offset:96
	ds_read_b128 v[224:227], v189 offset:4704
	ds_read_b128 v[234:237], v190 offset:18528
	ds_read_b128 v[238:241], v190 offset:23136
	ds_read_b128 v[242:245], v190 offset:27744
	ds_read_b128 v[246:249], v190 offset:32352
	s_waitcnt lgkmcnt(9)
	v_mfma_f32_32x32x16_bf16 v[114:129], v[192:195], v[200:203], v[114:129]
	v_mfma_f32_32x32x16_bf16 v[50:65], v[196:199], v[200:203], v[50:65]
	s_waitcnt lgkmcnt(8)
	v_mfma_f32_32x32x16_bf16 v[98:113], v[192:195], v[204:207], v[98:113]
	v_mfma_f32_32x32x16_bf16 v[34:49], v[196:199], v[204:207], v[34:49]
	s_waitcnt lgkmcnt(0)
	s_barrier
	s_cmpk_eq_i32 s6, 0x100
	s_cbranch_scc1 .Lmy_gB_3
	v_mfma_f32_32x32x16_bf16 v[82:97], v[192:195], v[208:211], v[82:97]
	s_waitcnt vmcnt(9)
	ds_write_b128 v191, v[130:133]
	v_mfma_f32_32x32x16_bf16 v[18:33], v[196:199], v[208:211], v[18:33]
	ds_write_b128 v191, v[134:137] offset:4608
	v_mfma_f32_32x32x16_bf16 v[66:81], v[192:195], v[212:215], v[66:81]
	ds_write_b128 v191, v[138:141] offset:9216
	s_add_u32 vcc_lo, s6, 0x78a8000
	s_addc_u32 vcc_hi, s7, 0
	s_nop 0
	v_lshl_add_u64 v[130:131], v[184:185], 0, vcc
	global_load_dwordx4 v[130:133], v[130:131], off offset:3328
	v_mfma_f32_32x32x16_bf16 v[2:17], v[196:199], v[212:215], v[2:17]
	s_waitcnt vmcnt(8)
	ds_write_b128 v191, v[142:145] offset:13824
	s_add_u32 vcc_lo, s6, 0x78e6000
	s_addc_u32 vcc_hi, s7, 0
	s_nop 0
	v_lshl_add_u64 v[134:135], v[184:185], 0, vcc
	global_load_dwordx4 v[134:137], v[134:135], off offset:3328
	v_mfma_f32_32x32x16_bf16 v[114:129], v[216:219], v[234:237], v[114:129]
	ds_write_b128 v191, v[146:149] offset:18432
	s_add_u32 vcc_lo, s6, 0x7924000
	s_addc_u32 vcc_hi, s7, 0
	s_nop 0
	v_lshl_add_u64 v[138:139], v[184:185], 0, vcc
	global_load_dwordx4 v[138:141], v[138:139], off offset:3328
	v_mfma_f32_32x32x16_bf16 v[50:65], v[224:227], v[234:237], v[50:65]
	s_waitcnt vmcnt(9)
	ds_write_b128 v191, v[150:153] offset:23040
	s_add_u32 vcc_lo, s6, 0x7962000
	s_addc_u32 vcc_hi, s7, 0
	s_nop 0
	v_lshl_add_u64 v[142:143], v[184:185], 0, vcc
	global_load_dwordx4 v[142:145], v[142:143], off offset:3328
	v_mfma_f32_32x32x16_bf16 v[98:113], v[216:219], v[238:241], v[98:113]
	s_waitcnt vmcnt(9)
	ds_write_b128 v191, v[154:157] offset:27648
	s_add_u32 vcc_lo, s6, 0x2288000
	s_addc_u32 vcc_hi, s7, 0
	s_nop 0
	v_lshl_add_u64 v[146:147], v[182:183], 0, vcc
	global_load_dwordx4 v[146:149], v[146:147], off offset:256
	v_mfma_f32_32x32x16_bf16 v[34:49], v[224:227], v[238:241], v[34:49]
	s_waitcnt vmcnt(9)
	ds_write_b128 v191, v[158:161] offset:32256
	s_add_u32 vcc_lo, s6, 0x228c000
	s_addc_u32 vcc_hi, s7, 0
	s_nop 0
	v_lshl_add_u64 v[150:151], v[182:183], 0, vcc
	global_load_dwordx4 v[150:153], v[150:151], off offset:256
	v_mfma_f32_32x32x16_bf16 v[82:97], v[216:219], v[242:245], v[82:97]
	s_waitcnt vmcnt(9)
	ds_write_b128 v191, v[162:165] offset:36864
	s_add_u32 vcc_lo, s6, 0x2290000
	s_addc_u32 vcc_hi, s7, 0
	s_nop 0
	v_lshl_add_u64 v[154:155], v[182:183], 0, vcc
	global_load_dwordx4 v[154:157], v[154:155], off offset:256
	v_mfma_f32_32x32x16_bf16 v[18:33], v[224:227], v[242:245], v[18:33]
	s_waitcnt vmcnt(9)
	ds_write_b128 v191, v[166:169] offset:41472
	s_add_u32 vcc_lo, s6, 0x2294000
	s_addc_u32 vcc_hi, s7, 0
	s_nop 0
	v_lshl_add_u64 v[158:159], v[182:183], 0, vcc
	global_load_dwordx4 v[158:161], v[158:159], off offset:256
	v_mfma_f32_32x32x16_bf16 v[66:81], v[216:219], v[246:249], v[66:81]
	s_waitcnt vmcnt(9)
	ds_write_b128 v191, v[170:173] offset:46080
	s_add_u32 vcc_lo, s6, 0x2298000
	s_addc_u32 vcc_hi, s7, 0
	s_nop 0
	v_lshl_add_u64 v[162:163], v[182:183], 0, vcc
	global_load_dwordx4 v[162:165], v[162:163], off offset:256
	v_mfma_f32_32x32x16_bf16 v[2:17], v[224:227], v[246:249], v[2:17]
	s_waitcnt vmcnt(9)
	ds_write_b128 v191, v[174:177] offset:50688
	s_add_u32 vcc_lo, s6, 0x229c000
	s_addc_u32 vcc_hi, s7, 0
	s_nop 0
	v_lshl_add_u64 v[166:167], v[182:183], 0, vcc
	global_load_dwordx4 v[166:169], v[166:167], off offset:256
	s_add_u32 vcc_lo, s6, 0x22a0000
	s_addc_u32 vcc_hi, s7, 0
	s_nop 0
	v_lshl_add_u64 v[170:171], v[182:183], 0, vcc
	global_load_dwordx4 v[170:173], v[170:171], off offset:256
	s_add_u32 vcc_lo, s6, 0x22a4000
	s_addc_u32 vcc_hi, s7, 0
	s_nop 0
	v_lshl_add_u64 v[174:175], v[182:183], 0, vcc
	global_load_dwordx4 v[174:177], v[174:175], off offset:256
	s_setprio 0
	s_branch .LBB0_281
; __device__ __forceinline__ void lds_barrier() { asm volatile("s_waitcnt lgkmcnt(0)\n\ts_barrier" ::: "memory"); }
; __device__ __forceinline__ f32x16 mfma32(bf16x8 a, bf16x8 b, f32x16 c) { return __builtin_amdgcn_mfma_f32_32x32x16_bf16(a, b, c, 0, 0, 0); }
; __device__ __forceinline__ void gemm_big(const bf16_t* __restrict__ A, long lda, const bf16_t* __restrict__ Bt, int K, f32x16 (&acc)[2][4], unsigned char* lds) {
;     ...
;                 af[nb][0] = *(const bf16x8*)(Ac + (ks + 1) * 16); af[nb][1] = *(const bf16x8*)(Ac + 32 * GLD + (ks + 1) * 16);
; #pragma unroll
;                 for (int ni = 0; ni < 4; ++ni) bfr[nb][ni] = *(const bf16x8*)(Bc + ni * 32 * GLD + (ks + 1) * 16);
;             }
;             __builtin_amdgcn_sched_barrier(0);
; #pragma unroll
;             for (int ni = 0; ni < 4; ++ni) { acc[0][ni] = mfma32(af[cb][0], bfr[cb][ni], acc[0][ni]); acc[1][ni] = mfma32(af[cb][1], bfr[cb][ni], acc[1][ni]); }
;             __builtin_amdgcn_sched_barrier(0);
;         }
;         __builtin_amdgcn_s_setprio(0);
;         lds_barrier();
;         if (kc + 1 < nk) {
;             lstore();
;             if (kc + 2 < nk) gload(kc + 2);
;             lds_barrier();
.Lmy_gB_3:
	v_mfma_f32_32x32x16_bf16 v[82:97], v[192:195], v[208:211], v[82:97]
	s_waitcnt vmcnt(9)
	ds_write_b128 v191, v[130:133]
	v_mfma_f32_32x32x16_bf16 v[18:33], v[196:199], v[208:211], v[18:33]
	ds_write_b128 v191, v[134:137] offset:4608
	v_mfma_f32_32x32x16_bf16 v[66:81], v[192:195], v[212:215], v[66:81]
	ds_write_b128 v191, v[138:141] offset:9216
	v_mfma_f32_32x32x16_bf16 v[2:17], v[196:199], v[212:215], v[2:17]
	s_waitcnt vmcnt(7)
	ds_write_b128 v191, v[142:145] offset:13824
	v_mfma_f32_32x32x16_bf16 v[114:129], v[216:219], v[234:237], v[114:129]
	ds_write_b128 v191, v[146:149] offset:18432
	v_mfma_f32_32x32x16_bf16 v[50:65], v[224:227], v[234:237], v[50:65]
	s_waitcnt vmcnt(6)
	ds_write_b128 v191, v[150:153] offset:23040
	v_mfma_f32_32x32x16_bf16 v[98:113], v[216:219], v[238:241], v[98:113]
	s_waitcnt vmcnt(5)
	ds_write_b128 v191, v[154:157] offset:27648
	v_mfma_f32_32x32x16_bf16 v[34:49], v[224:227], v[238:241], v[34:49]
	s_waitcnt vmcnt(4)
	ds_write_b128 v191, v[158:161] offset:32256
	v_mfma_f32_32x32x16_bf16 v[82:97], v[216:219], v[242:245], v[82:97]
	s_waitcnt vmcnt(3)
	ds_write_b128 v191, v[162:165] offset:36864
	v_mfma_f32_32x32x16_bf16 v[18:33], v[224:227], v[242:245], v[18:33]
	s_waitcnt vmcnt(2)
	ds_write_b128 v191, v[166:169] offset:41472
	v_mfma_f32_32x32x16_bf16 v[66:81], v[216:219], v[246:249], v[66:81]
	s_waitcnt vmcnt(1)
	ds_write_b128 v191, v[170:173] offset:46080
	v_mfma_f32_32x32x16_bf16 v[2:17], v[224:227], v[246:249], v[2:17]
	s_waitcnt vmcnt(0)
	ds_write_b128 v191, v[174:177] offset:50688
	s_setprio 0
	s_branch .LBB0_281

; #define ZERO44(a) { _Pragma("unroll") for (int _i = 0; _i < 4; ++_i) { _Pragma("unroll") for (int _j = 0; _j < 4; ++_j) a[_i][_j] = 0.f; } }
; __device__ __forceinline__ void mm64(const float* At, const float* B, float (&acc)[4][4], int ty, int tx) {
;     f32x2 c2[4][2];
; #pragma unroll
;     for (int rr = 0; rr < 4; ++rr) { c2[rr][0] = (f32x2){acc[rr][0], acc[rr][1]}; c2[rr][1] = (f32x2){acc[rr][2], acc[rr][3]}; }
; #pragma unroll 8
;     for (int k = 0; k < 64; ++k) {
;         const f32x4 a = *(const f32x4*)(At + k * DLD + 4 * ty);
;         const f32x4 b = *(const f32x4*)(B + k * DLD + 4 * tx);
;         const f32x2 b01 = {b.x, b.y}, b23 = {b.z, b.w};
; #pragma unroll
;         for (int rr = 0; rr < 4; ++rr) {
;             const f32x2 a2 = {a[rr], a[rr]};
;             c2[rr][0] = __builtin_elementwise_fma(a2, b01, c2[rr][0]);
;             c2[rr][1] = __builtin_elementwise_fma(a2, b23, c2[rr][1]);
;         }
;     }
; __device__ __forceinline__ void dn1_item(const Params& p, int l, int item, unsigned char* lds) {
;     ...
;     const float gci = sgc[i], beti = sbeta[i], gcl = sgc[63];
;     const float gl = __expf(gcl);
;     {
;         float a1[4][4], a2[4][4]; ZERO44(a1); ZERO44(a2);
;         mm64(B0, B0, a1, ty, tx);
;         mm64(B1, B0, a2, ty, tx);
.LBB0_587:
	s_or_b64 exec, exec, s[0:1]
	v_lshl_add_u32 v0, v108, 2, 0
	v_add_u32_e32 v2, 0x11000, v0
	v_readlane_b32 s0, v253, 48
	s_waitcnt lgkmcnt(0)
	s_barrier
	v_add_u32_e32 v0, 0x11100, v0
	v_mov_b32_e32 v3, s0
	ds_read_b32 v109, v2
	ds_read_b32 v92, v0
	ds_read_b32 v106, v3
	v_ashrrev_i32_e32 v104, 4, v107
	v_and_b32_e32 v111, 15, v107
	v_and_b32_e32 v0, -16, v107
	v_mov_b32_e32 v2, 0
	v_lshlrev_b32_e32 v105, 2, v104
	v_add_u32_e32 v51, 0, v0
	v_lshlrev_b32_e32 v50, 2, v111
	v_lshl_add_u32 v76, v111, 4, 0
	s_mov_b32 s0, 0
	v_mov_b32_e32 v3, v2
	v_mov_b32_e32 v16, v2
	v_mov_b32_e32 v17, v2
	v_mov_b32_e32 v14, v2
	v_mov_b32_e32 v15, v2
	v_mov_b32_e32 v12, v2
	v_mov_b32_e32 v13, v2
	v_mov_b32_e32 v10, v2
	v_mov_b32_e32 v11, v2
	v_mov_b32_e32 v8, v2
	v_mov_b32_e32 v9, v2
	v_mov_b32_e32 v6, v2
	v_mov_b32_e32 v7, v2
	v_mov_b32_e32 v4, v2
	v_mov_b32_e32 v5, v2
	v_add_u32_e32 v220, s0, v51
	v_add_u32_e32 v221, s0, v76
	ds_read_b128 v[204:207], v220
	ds_read_b128 v[208:211], v221
	ds_read_b128 v[212:215], v220 offset:272
	ds_read_b128 v[216:219], v221 offset:272
	ds_read_b128 v[224:227], v220 offset:544
	ds_read_b128 v[234:237], v221 offset:544
.LBB0_588:
	ds_read_b128 v[238:241], v220 offset:816
	ds_read_b128 v[242:245], v221 offset:816
	s_waitcnt lgkmcnt(6)
	v_pk_fma_f32 v[16:17], v[204:205], v[208:209], v[16:17] op_sel_hi:[0,1,1]
	v_pk_fma_f32 v[14:15], v[204:205], v[210:211], v[14:15] op_sel_hi:[0,1,1]
	v_pk_fma_f32 v[12:13], v[204:205], v[208:209], v[12:13] op_sel:[1,0,0]
	v_pk_fma_f32 v[10:11], v[204:205], v[210:211], v[10:11] op_sel:[1,0,0]
	v_pk_fma_f32 v[8:9], v[206:207], v[208:209], v[8:9] op_sel_hi:[0,1,1]
	v_pk_fma_f32 v[6:7], v[206:207], v[210:211], v[6:7] op_sel_hi:[0,1,1]
	v_pk_fma_f32 v[4:5], v[206:207], v[208:209], v[4:5] op_sel:[1,0,0]
	v_pk_fma_f32 v[2:3], v[206:207], v[210:211], v[2:3] op_sel:[1,0,0]
	ds_read_b128 v[204:207], v220 offset:1088
	ds_read_b128 v[208:211], v221 offset:1088
	s_waitcnt lgkmcnt(6)
	v_pk_fma_f32 v[16:17], v[212:213], v[216:217], v[16:17] op_sel_hi:[0,1,1]
	v_pk_fma_f32 v[14:15], v[212:213], v[218:219], v[14:15] op_sel_hi:[0,1,1]
	v_pk_fma_f32 v[12:13], v[212:213], v[216:217], v[12:13] op_sel:[1,0,0]
	v_pk_fma_f32 v[10:11], v[212:213], v[218:219], v[10:11] op_sel:[1,0,0]
	v_pk_fma_f32 v[8:9], v[214:215], v[216:217], v[8:9] op_sel_hi:[0,1,1]
	v_pk_fma_f32 v[6:7], v[214:215], v[218:219], v[6:7] op_sel_hi:[0,1,1]
	v_pk_fma_f32 v[4:5], v[214:215], v[216:217], v[4:5] op_sel:[1,0,0]
	v_pk_fma_f32 v[2:3], v[214:215], v[218:219], v[2:3] op_sel:[1,0,0]
	ds_read_b128 v[212:215], v220 offset:1360
	ds_read_b128 v[216:219], v221 offset:1360
	s_waitcnt lgkmcnt(6)
	v_pk_fma_f32 v[16:17], v[224:225], v[234:235], v[16:17] op_sel_hi:[0,1,1]
	v_pk_fma_f32 v[14:15], v[224:225], v[236:237], v[14:15] op_sel_hi:[0,1,1]
	v_pk_fma_f32 v[12:13], v[224:225], v[234:235], v[12:13] op_sel:[1,0,0]
	v_pk_fma_f32 v[10:11], v[224:225], v[236:237], v[10:11] op_sel:[1,0,0]
	v_pk_fma_f32 v[8:9], v[226:227], v[234:235], v[8:9] op_sel_hi:[0,1,1]
	v_pk_fma_f32 v[6:7], v[226:227], v[236:237], v[6:7] op_sel_hi:[0,1,1]
	v_pk_fma_f32 v[4:5], v[226:227], v[234:235], v[4:5] op_sel:[1,0,0]
	v_pk_fma_f32 v[2:3], v[226:227], v[236:237], v[2:3] op_sel:[1,0,0]
	ds_read_b128 v[224:227], v220 offset:1632
	ds_read_b128 v[234:237], v221 offset:1632
	s_waitcnt lgkmcnt(6)
	v_pk_fma_f32 v[16:17], v[238:239], v[242:243], v[16:17] op_sel_hi:[0,1,1]
	v_pk_fma_f32 v[14:15], v[238:239], v[244:245], v[14:15] op_sel_hi:[0,1,1]
	v_pk_fma_f32 v[12:13], v[238:239], v[242:243], v[12:13] op_sel:[1,0,0]
	v_pk_fma_f32 v[10:11], v[238:239], v[244:245], v[10:11] op_sel:[1,0,0]
	v_pk_fma_f32 v[8:9], v[240:241], v[242:243], v[8:9] op_sel_hi:[0,1,1]
	v_pk_fma_f32 v[6:7], v[240:241], v[244:245], v[6:7] op_sel_hi:[0,1,1]
	v_pk_fma_f32 v[4:5], v[240:241], v[242:243], v[4:5] op_sel:[1,0,0]
	v_pk_fma_f32 v[2:3], v[240:241], v[244:245], v[2:3] op_sel:[1,0,0]
	ds_read_b128 v[238:241], v220 offset:1904
	ds_read_b128 v[242:245], v221 offset:1904
	s_waitcnt lgkmcnt(6)
	v_pk_fma_f32 v[16:17], v[204:205], v[208:209], v[16:17] op_sel_hi:[0,1,1]
	v_pk_fma_f32 v[14:15], v[204:205], v[210:211], v[14:15] op_sel_hi:[0,1,1]
	v_pk_fma_f32 v[12:13], v[204:205], v[208:209], v[12:13] op_sel:[1,0,0]
	v_pk_fma_f32 v[10:11], v[204:205], v[210:211], v[10:11] op_sel:[1,0,0]
	v_pk_fma_f32 v[8:9], v[206:207], v[208:209], v[8:9] op_sel_hi:[0,1,1]
	v_pk_fma_f32 v[6:7], v[206:207], v[210:211], v[6:7] op_sel_hi:[0,1,1]
	v_pk_fma_f32 v[4:5], v[206:207], v[208:209], v[4:5] op_sel:[1,0,0]
	v_pk_fma_f32 v[2:3], v[206:207], v[210:211], v[2:3] op_sel:[1,0,0]
	s_addk_i32 s0, 0x880
	v_add_u32_e32 v220, s0, v51
	v_add_u32_e32 v221, s0, v76
	ds_read_b128 v[204:207], v220
	ds_read_b128 v[208:211], v221
	s_waitcnt lgkmcnt(6)
	v_pk_fma_f32 v[16:17], v[212:213], v[216:217], v[16:17] op_sel_hi:[0,1,1]
	v_pk_fma_f32 v[14:15], v[212:213], v[218:219], v[14:15] op_sel_hi:[0,1,1]
	v_pk_fma_f32 v[12:13], v[212:213], v[216:217], v[12:13] op_sel:[1,0,0]
	v_pk_fma_f32 v[10:11], v[212:213], v[218:219], v[10:11] op_sel:[1,0,0]
	v_pk_fma_f32 v[8:9], v[214:215], v[216:217], v[8:9] op_sel_hi:[0,1,1]
	v_pk_fma_f32 v[6:7], v[214:215], v[218:219], v[6:7] op_sel_hi:[0,1,1]
	v_pk_fma_f32 v[4:5], v[214:215], v[216:217], v[4:5] op_sel:[1,0,0]
	v_pk_fma_f32 v[2:3], v[214:215], v[218:219], v[2:3] op_sel:[1,0,0]
	ds_read_b128 v[212:215], v220 offset:272
	ds_read_b128 v[216:219], v221 offset:272
	s_waitcnt lgkmcnt(6)
	v_pk_fma_f32 v[16:17], v[224:225], v[234:235], v[16:17] op_sel_hi:[0,1,1]
	v_pk_fma_f32 v[14:15], v[224:225], v[236:237], v[14:15] op_sel_hi:[0,1,1]
	v_pk_fma_f32 v[12:13], v[224:225], v[234:235], v[12:13] op_sel:[1,0,0]
	v_pk_fma_f32 v[10:11], v[224:225], v[236:237], v[10:11] op_sel:[1,0,0]
	v_pk_fma_f32 v[8:9], v[226:227], v[234:235], v[8:9] op_sel_hi:[0,1,1]
	v_pk_fma_f32 v[6:7], v[226:227], v[236:237], v[6:7] op_sel_hi:[0,1,1]
	v_pk_fma_f32 v[4:5], v[226:227], v[234:235], v[4:5] op_sel:[1,0,0]
	v_pk_fma_f32 v[2:3], v[226:227], v[236:237], v[2:3] op_sel:[1,0,0]
	ds_read_b128 v[224:227], v220 offset:544
	ds_read_b128 v[234:237], v221 offset:544
	s_waitcnt lgkmcnt(6)
	v_pk_fma_f32 v[16:17], v[238:239], v[242:243], v[16:17] op_sel_hi:[0,1,1]
	v_pk_fma_f32 v[14:15], v[238:239], v[244:245], v[14:15] op_sel_hi:[0,1,1]
	v_pk_fma_f32 v[12:13], v[238:239], v[242:243], v[12:13] op_sel:[1,0,0]
	v_pk_fma_f32 v[10:11], v[238:239], v[244:245], v[10:11] op_sel:[1,0,0]
	v_pk_fma_f32 v[8:9], v[240:241], v[242:243], v[8:9] op_sel_hi:[0,1,1]
	v_pk_fma_f32 v[6:7], v[240:241], v[244:245], v[6:7] op_sel_hi:[0,1,1]
	v_pk_fma_f32 v[4:5], v[240:241], v[242:243], v[4:5] op_sel:[1,0,0]
	v_pk_fma_f32 v[2:3], v[240:241], v[244:245], v[2:3] op_sel:[1,0,0]
	s_cmpk_lg_i32 s0, 0x4400
	s_cbranch_scc1 .LBB0_588
; __device__ __forceinline__ void mm64(const float* At, const float* B, float (&acc)[4][4], int ty, int tx) {
;     f32x2 c2[4][2];
; #pragma unroll
;     for (int rr = 0; rr < 4; ++rr) { c2[rr][0] = (f32x2){acc[rr][0], acc[rr][1]}; c2[rr][1] = (f32x2){acc[rr][2], acc[rr][3]}; }
; #pragma unroll 8
;     for (int k = 0; k < 64; ++k) {
;         const f32x4 a = *(const f32x4*)(At + k * DLD + 4 * ty);
;         const f32x4 b = *(const f32x4*)(B + k * DLD + 4 * tx);
; __device__ __forceinline__ void dn1_item(const Params& p, int l, int item, unsigned char* lds) {
;     ...
;         mm64(B1, B0, a2, ty, tx);
	s_waitcnt lgkmcnt(0)
	v_lshlrev_b32_e32 v77, 4, v104
	v_readlane_b32 s0, v253, 47
	v_mov_b32_e32 v18, 0
	v_mov_b32_e32 v19, v18
	v_add_u32_e32 v93, s0, v77
	s_mov_b32 s0, 0
	v_mov_b32_e32 v102, v18
	v_mov_b32_e32 v103, v18
	v_mov_b32_e32 v100, v18
	v_mov_b32_e32 v101, v18
	v_mov_b32_e32 v98, v18
	v_mov_b32_e32 v99, v18
	v_mov_b32_e32 v96, v18
	v_mov_b32_e32 v97, v18
	v_mov_b32_e32 v94, v18
	v_mov_b32_e32 v95, v18
	v_mov_b32_e32 v52, v18
	v_mov_b32_e32 v53, v18
	v_mov_b32_e32 v20, v18
	v_mov_b32_e32 v21, v18
	v_add_u32_e32 v220, s0, v93
	v_add_u32_e32 v221, s0, v76
	ds_read_b128 v[204:207], v220
	ds_read_b128 v[208:211], v221
	ds_read_b128 v[212:215], v220 offset:272
	ds_read_b128 v[216:219], v221 offset:272
	ds_read_b128 v[224:227], v220 offset:544
	ds_read_b128 v[234:237], v221 offset:544
; __device__ __forceinline__ void mm64(const float* At, const float* B, float (&acc)[4][4], int ty, int tx) {
;     f32x2 c2[4][2];
; #pragma unroll
;     for (int rr = 0; rr < 4; ++rr) { c2[rr][0] = (f32x2){acc[rr][0], acc[rr][1]}; c2[rr][1] = (f32x2){acc[rr][2], acc[rr][3]}; }
; #pragma unroll 8
;     for (int k = 0; k < 64; ++k) {
;         const f32x4 a = *(const f32x4*)(At + k * DLD + 4 * ty);
;         const f32x4 b = *(const f32x4*)(B + k * DLD + 4 * tx);
;         const f32x2 b01 = {b.x, b.y}, b23 = {b.z, b.w};
; #pragma unroll
;         for (int rr = 0; rr < 4; ++rr) {
;             const f32x2 a2 = {a[rr], a[rr]};
;             c2[rr][0] = __builtin_elementwise_fma(a2, b01, c2[rr][0]);
;             c2[rr][1] = __builtin_elementwise_fma(a2, b23, c2[rr][1]);
;         }
;     }
; #pragma unroll
;     for (int rr = 0; rr < 4; ++rr) { acc[rr][0] = c2[rr][0].x; acc[rr][1] = c2[rr][0].y; acc[rr][2] = c2[rr][1].x; acc[rr][3] = c2[rr][1].y; }
; }
; __device__ __forceinline__ void dn1_item(const Params& p, int l, int item, unsigned char* lds) {
;     ...
; #pragma unroll
;         for (int rr = 0; rr < 4; ++rr) {
;             const int ii = 4 * ty + rr; const float gi = sgc[ii], bi = sbeta[ii];
; #pragma unroll
;             for (int cc = 0; cc < 4; ++cc) {
;                 const int jj = 4 * tx + cc; const float gj = sgc[jj];
;                 const float dec = (ii >= jj) ? __expf(gi - gj) : 0.f;
.LBB0_590:
	ds_read_b128 v[238:241], v220 offset:816
	ds_read_b128 v[242:245], v221 offset:816
	s_waitcnt lgkmcnt(6)
	v_pk_fma_f32 v[102:103], v[204:205], v[208:209], v[102:103] op_sel_hi:[0,1,1]
	v_pk_fma_f32 v[100:101], v[204:205], v[210:211], v[100:101] op_sel_hi:[0,1,1]
	v_pk_fma_f32 v[98:99], v[204:205], v[208:209], v[98:99] op_sel:[1,0,0]
	v_pk_fma_f32 v[96:97], v[204:205], v[210:211], v[96:97] op_sel:[1,0,0]
	v_pk_fma_f32 v[94:95], v[206:207], v[208:209], v[94:95] op_sel_hi:[0,1,1]
	v_pk_fma_f32 v[52:53], v[206:207], v[210:211], v[52:53] op_sel_hi:[0,1,1]
	v_pk_fma_f32 v[20:21], v[206:207], v[208:209], v[20:21] op_sel:[1,0,0]
	v_pk_fma_f32 v[18:19], v[206:207], v[210:211], v[18:19] op_sel:[1,0,0]
	ds_read_b128 v[204:207], v220 offset:1088
	ds_read_b128 v[208:211], v221 offset:1088
	s_waitcnt lgkmcnt(6)
	v_pk_fma_f32 v[102:103], v[212:213], v[216:217], v[102:103] op_sel_hi:[0,1,1]
	v_pk_fma_f32 v[100:101], v[212:213], v[218:219], v[100:101] op_sel_hi:[0,1,1]
	v_pk_fma_f32 v[98:99], v[212:213], v[216:217], v[98:99] op_sel:[1,0,0]
	v_pk_fma_f32 v[96:97], v[212:213], v[218:219], v[96:97] op_sel:[1,0,0]
	v_pk_fma_f32 v[94:95], v[214:215], v[216:217], v[94:95] op_sel_hi:[0,1,1]
	v_pk_fma_f32 v[52:53], v[214:215], v[218:219], v[52:53] op_sel_hi:[0,1,1]
	v_pk_fma_f32 v[20:21], v[214:215], v[216:217], v[20:21] op_sel:[1,0,0]
	v_pk_fma_f32 v[18:19], v[214:215], v[218:219], v[18:19] op_sel:[1,0,0]
	ds_read_b128 v[212:215], v220 offset:1360
	ds_read_b128 v[216:219], v221 offset:1360
	s_waitcnt lgkmcnt(6)
	v_pk_fma_f32 v[102:103], v[224:225], v[234:235], v[102:103] op_sel_hi:[0,1,1]
	v_pk_fma_f32 v[100:101], v[224:225], v[236:237], v[100:101] op_sel_hi:[0,1,1]
	v_pk_fma_f32 v[98:99], v[224:225], v[234:235], v[98:99] op_sel:[1,0,0]
	v_pk_fma_f32 v[96:97], v[224:225], v[236:237], v[96:97] op_sel:[1,0,0]
	v_pk_fma_f32 v[94:95], v[226:227], v[234:235], v[94:95] op_sel_hi:[0,1,1]
	v_pk_fma_f32 v[52:53], v[226:227], v[236:237], v[52:53] op_sel_hi:[0,1,1]
	v_pk_fma_f32 v[20:21], v[226:227], v[234:235], v[20:21] op_sel:[1,0,0]
	v_pk_fma_f32 v[18:19], v[226:227], v[236:237], v[18:19] op_sel:[1,0,0]
	ds_read_b128 v[224:227], v220 offset:1632
	ds_read_b128 v[234:237], v221 offset:1632
	s_waitcnt lgkmcnt(6)
	v_pk_fma_f32 v[102:103], v[238:239], v[242:243], v[102:103] op_sel_hi:[0,1,1]
	v_pk_fma_f32 v[100:101], v[238:239], v[244:245], v[100:101] op_sel_hi:[0,1,1]
	v_pk_fma_f32 v[98:99], v[238:239], v[242:243], v[98:99] op_sel:[1,0,0]
	v_pk_fma_f32 v[96:97], v[238:239], v[244:245], v[96:97] op_sel:[1,0,0]
	v_pk_fma_f32 v[94:95], v[240:241], v[242:243], v[94:95] op_sel_hi:[0,1,1]
	v_pk_fma_f32 v[52:53], v[240:241], v[244:245], v[52:53] op_sel_hi:[0,1,1]
	v_pk_fma_f32 v[20:21], v[240:241], v[242:243], v[20:21] op_sel:[1,0,0]
	v_pk_fma_f32 v[18:19], v[240:241], v[244:245], v[18:19] op_sel:[1,0,0]
	ds_read_b128 v[238:241], v220 offset:1904
	ds_read_b128 v[242:245], v221 offset:1904
	s_waitcnt lgkmcnt(6)
	v_pk_fma_f32 v[102:103], v[204:205], v[208:209], v[102:103] op_sel_hi:[0,1,1]
	v_pk_fma_f32 v[100:101], v[204:205], v[210:211], v[100:101] op_sel_hi:[0,1,1]
	v_pk_fma_f32 v[98:99], v[204:205], v[208:209], v[98:99] op_sel:[1,0,0]
	v_pk_fma_f32 v[96:97], v[204:205], v[210:211], v[96:97] op_sel:[1,0,0]
	v_pk_fma_f32 v[94:95], v[206:207], v[208:209], v[94:95] op_sel_hi:[0,1,1]
	v_pk_fma_f32 v[52:53], v[206:207], v[210:211], v[52:53] op_sel_hi:[0,1,1]
	v_pk_fma_f32 v[20:21], v[206:207], v[208:209], v[20:21] op_sel:[1,0,0]
	v_pk_fma_f32 v[18:19], v[206:207], v[210:211], v[18:19] op_sel:[1,0,0]
	s_addk_i32 s0, 0x880
	v_add_u32_e32 v220, s0, v93
	v_add_u32_e32 v221, s0, v76
	ds_read_b128 v[204:207], v220
	ds_read_b128 v[208:211], v221
	s_waitcnt lgkmcnt(6)
	v_pk_fma_f32 v[102:103], v[212:213], v[216:217], v[102:103] op_sel_hi:[0,1,1]
	v_pk_fma_f32 v[100:101], v[212:213], v[218:219], v[100:101] op_sel_hi:[0,1,1]
	v_pk_fma_f32 v[98:99], v[212:213], v[216:217], v[98:99] op_sel:[1,0,0]
	v_pk_fma_f32 v[96:97], v[212:213], v[218:219], v[96:97] op_sel:[1,0,0]
	v_pk_fma_f32 v[94:95], v[214:215], v[216:217], v[94:95] op_sel_hi:[0,1,1]
	v_pk_fma_f32 v[52:53], v[214:215], v[218:219], v[52:53] op_sel_hi:[0,1,1]
	v_pk_fma_f32 v[20:21], v[214:215], v[216:217], v[20:21] op_sel:[1,0,0]
	v_pk_fma_f32 v[18:19], v[214:215], v[218:219], v[18:19] op_sel:[1,0,0]
	ds_read_b128 v[212:215], v220 offset:272
	ds_read_b128 v[216:219], v221 offset:272
	s_waitcnt lgkmcnt(6)
	v_pk_fma_f32 v[102:103], v[224:225], v[234:235], v[102:103] op_sel_hi:[0,1,1]
	v_pk_fma_f32 v[100:101], v[224:225], v[236:237], v[100:101] op_sel_hi:[0,1,1]
	v_pk_fma_f32 v[98:99], v[224:225], v[234:235], v[98:99] op_sel:[1,0,0]
	v_pk_fma_f32 v[96:97], v[224:225], v[236:237], v[96:97] op_sel:[1,0,0]
	v_pk_fma_f32 v[94:95], v[226:227], v[234:235], v[94:95] op_sel_hi:[0,1,1]
	v_pk_fma_f32 v[52:53], v[226:227], v[236:237], v[52:53] op_sel_hi:[0,1,1]
	v_pk_fma_f32 v[20:21], v[226:227], v[234:235], v[20:21] op_sel:[1,0,0]
	v_pk_fma_f32 v[18:19], v[226:227], v[236:237], v[18:19] op_sel:[1,0,0]
	ds_read_b128 v[224:227], v220 offset:544
	ds_read_b128 v[234:237], v221 offset:544
	s_waitcnt lgkmcnt(6)
	v_pk_fma_f32 v[102:103], v[238:239], v[242:243], v[102:103] op_sel_hi:[0,1,1]
	v_pk_fma_f32 v[100:101], v[238:239], v[244:245], v[100:101] op_sel_hi:[0,1,1]
	v_pk_fma_f32 v[98:99], v[238:239], v[242:243], v[98:99] op_sel:[1,0,0]
	v_pk_fma_f32 v[96:97], v[238:239], v[244:245], v[96:97] op_sel:[1,0,0]
	v_pk_fma_f32 v[94:95], v[240:241], v[242:243], v[94:95] op_sel_hi:[0,1,1]
	v_pk_fma_f32 v[52:53], v[240:241], v[244:245], v[52:53] op_sel_hi:[0,1,1]
	v_pk_fma_f32 v[20:21], v[240:241], v[242:243], v[20:21] op_sel:[1,0,0]
	v_pk_fma_f32 v[18:19], v[240:241], v[244:245], v[18:19] op_sel:[1,0,0]
	s_cmpk_lg_i32 s0, 0x4400
	s_cbranch_scc1 .LBB0_590
	s_waitcnt lgkmcnt(0)
	v_lshl_add_u32 v0, v105, 2, 0
	v_add_u32_e32 v113, 0x11000, v0
	v_add_u32_e32 v0, 0x11100, v0
	ds_read_b32 v118, v113
	ds_read_b32 v117, v0
	v_cmp_lt_i32_e64 s[40:41], v105, v50
	v_cmp_ge_i32_e32 vcc, v105, v50
	v_mov_b32_e32 v115, 0
	v_lshl_add_u32 v113, v50, 2, 0
	v_mov_b32_e32 v114, 0
	s_and_saveexec_b64 s[0:1], vcc
	s_cbranch_execz .LBB0_593
	v_add_u32_e32 v0, 0x11000, v113
	ds_read_b32 v0, v0
	s_waitcnt lgkmcnt(0)
	v_sub_f32_e32 v0, v118, v0
	v_mul_f32_e32 v0, 0x3fb8aa3b, v0
	v_exp_f32_e32 v114, v0

; #define ZERO44(a) { _Pragma("unroll") for (int _i = 0; _i < 4; ++_i) { _Pragma("unroll") for (int _j = 0; _j < 4; ++_j) a[_i][_j] = 0.f; } }
; __device__ __forceinline__ void mm64(const float* At, const float* B, float (&acc)[4][4], int ty, int tx) {
;     f32x2 c2[4][2];
; #pragma unroll
;     for (int rr = 0; rr < 4; ++rr) { c2[rr][0] = (f32x2){acc[rr][0], acc[rr][1]}; c2[rr][1] = (f32x2){acc[rr][2], acc[rr][3]}; }
; #pragma unroll 8
;     for (int k = 0; k < 64; ++k) {
;         const f32x4 a = *(const f32x4*)(At + k * DLD + 4 * ty);
;         const f32x4 b = *(const f32x4*)(B + k * DLD + 4 * tx);
;         const f32x2 b01 = {b.x, b.y}, b23 = {b.z, b.w};
; #pragma unroll
;         for (int rr = 0; rr < 4; ++rr) {
;             const f32x2 a2 = {a[rr], a[rr]};
;             c2[rr][0] = __builtin_elementwise_fma(a2, b01, c2[rr][0]);
;             c2[rr][1] = __builtin_elementwise_fma(a2, b23, c2[rr][1]);
;         }
;     }
; __device__ __forceinline__ void dn1_item(const Params& p, int l, int item, unsigned char* lds) {
;     ...
; #pragma unroll 1
;             for (int bj = 0; bj < bi; ++bj) {
;                 float y = 0.f;
; #pragma unroll
;                 for (int m = 0; m < 16; ++m) y += B0[(16 * bi + m) * DLD + 16 * bi + br] * Xs[bj * 256 + m * 16 + bc];
;                 B0[(16 * bj + bc) * DLD + 16 * bi + br] = -y;
;             }
;             __syncthreads();
;         }
;     }
;     __syncthreads();
;     float wacc[4][4], uacc[4][4]; ZERO44(wacc); ZERO44(uacc);
;     mm64(B0, B1, wacc, ty, tx);
.LBB0_631:
	v_add_u32_e32 v14, 0, v8
	v_add_u32_e32 v12, 0x11200, v14
	ds_read2_b32 v[10:11], v7 offset1:68
	ds_read_b32 v12, v12
	v_add_u32_e32 v13, 0x11340, v14
	v_add_u32_e32 v16, 0x400, v7
	s_add_i32 s1, s1, -1
	v_add_u32_e32 v8, 0x400, v8
	s_waitcnt lgkmcnt(0)
	v_fma_f32 v15, v10, v12, 0
	v_add_u32_e32 v10, 0x11240, v14
	ds_read_b32 v10, v10
	ds_read_b32 v13, v13
	v_add_u32_e32 v12, 0x11280, v14
	ds_read_b32 v12, v12
	s_cmp_lg_u32 s1, 0
	s_waitcnt lgkmcnt(2)
	v_fmac_f32_e32 v15, v11, v10
	ds_read2_b32 v[10:11], v7 offset0:136 offset1:204
	s_waitcnt lgkmcnt(0)
	v_fmac_f32_e32 v15, v10, v12
	v_add_u32_e32 v10, 0x112c0, v14
	ds_read_b32 v10, v10
	v_add_u32_e32 v12, 0x11300, v14
	ds_read_b32 v12, v12
	s_waitcnt lgkmcnt(1)
	v_fmac_f32_e32 v15, v11, v10
	ds_read2_b32 v[10:11], v16 offset0:16 offset1:84
	s_waitcnt lgkmcnt(0)
	v_pk_mul_f32 v[10:11], v[10:11], v[12:13]
	s_nop 0
	v_add_f32_e32 v10, v15, v10
	v_add_u32_e32 v12, 0x11380, v14
	v_add_u32_e32 v13, 0x113c0, v14
	v_add_f32_e32 v15, v10, v11
	ds_read2_b32 v[10:11], v16 offset0:152 offset1:220
	ds_read_b32 v12, v12
	ds_read_b32 v13, v13
	v_add_u32_e32 v16, 0x800, v7
	s_waitcnt lgkmcnt(0)
	v_pk_mul_f32 v[10:11], v[10:11], v[12:13]
	s_nop 0
	v_add_f32_e32 v10, v15, v10
	v_add_u32_e32 v12, 0x11400, v14
	v_add_u32_e32 v13, 0x11440, v14
	v_add_f32_e32 v15, v10, v11
	ds_read2_b32 v[10:11], v16 offset0:32 offset1:100
	ds_read_b32 v12, v12
	ds_read_b32 v13, v13
	s_waitcnt lgkmcnt(0)
	v_pk_mul_f32 v[10:11], v[10:11], v[12:13]
	s_nop 0
	v_add_f32_e32 v10, v15, v10
	v_add_u32_e32 v12, 0x11480, v14
	v_add_u32_e32 v13, 0x114c0, v14
	v_add_f32_e32 v15, v10, v11
	ds_read2_b32 v[10:11], v16 offset0:168 offset1:236
	ds_read_b32 v12, v12
	ds_read_b32 v13, v13
	v_add_u32_e32 v16, 0xc00, v7
	s_waitcnt lgkmcnt(0)
	v_pk_mul_f32 v[10:11], v[10:11], v[12:13]
	s_nop 0
	v_add_f32_e32 v10, v15, v10
	v_add_u32_e32 v12, 0x11500, v14
	v_add_u32_e32 v13, 0x11540, v14
	v_add_f32_e32 v15, v10, v11
	ds_read2_b32 v[10:11], v16 offset0:48 offset1:116
	ds_read_b32 v12, v12
	ds_read_b32 v13, v13
	s_waitcnt lgkmcnt(0)
	v_pk_mul_f32 v[10:11], v[10:11], v[12:13]
	s_nop 0
	v_add_f32_e32 v10, v15, v10
	v_add_u32_e32 v12, 0x11580, v14
	v_add_u32_e32 v13, 0x115c0, v14
	v_add_f32_e32 v15, v10, v11
	ds_read2_b32 v[10:11], v16 offset0:184 offset1:252
	ds_read_b32 v12, v12
	ds_read_b32 v13, v13
	s_waitcnt lgkmcnt(0)
	v_pk_mul_f32 v[10:11], v[10:11], v[12:13]
	s_nop 0
	v_add_f32_e32 v10, v15, v10
	v_add_f32_e32 v10, v10, v11
	v_xor_b32_e32 v10, 0x80000000, v10
	v_add_u32_e32 v11, 0, v9
	v_add_u32_e32 v9, 0x1100, v9
	ds_write_b32 v11, v10
	s_cbranch_scc1 .LBB0_631
	s_add_i32 s0, s0, 1
	v_add_u32_e32 v4, 0x1100, v4
	s_cmp_eq_u32 s0, 4
	v_add_u32_e32 v6, 64, v6
	s_waitcnt lgkmcnt(0)
	s_barrier
	s_cbranch_scc0 .LBB0_626
	v_lshlrev_b32_e32 v94, 4, v111
	v_readlane_b32 s0, v253, 47
	v_mov_b32_e32 v4, 0
	v_mov_b32_e32 v5, v4
	v_add_u32_e32 v95, s0, v94
	s_mov_b32 s0, 0
	v_mov_b32_e32 v14, v4
	v_mov_b32_e32 v15, v4
	v_mov_b32_e32 v16, v4
	v_mov_b32_e32 v17, v4
	v_mov_b32_e32 v10, v4
	v_mov_b32_e32 v11, v4
	v_mov_b32_e32 v12, v4
	v_mov_b32_e32 v13, v4
	v_mov_b32_e32 v6, v4
	v_mov_b32_e32 v7, v4
	v_mov_b32_e32 v8, v4
	v_mov_b32_e32 v9, v4
	v_mov_b32_e32 v2, v4
	v_mov_b32_e32 v3, v4
	s_barrier
	v_add_u32_e32 v220, s0, v51
	v_add_u32_e32 v221, s0, v95
	ds_read_b128 v[204:207], v220
	ds_read_b128 v[208:211], v221
	ds_read_b128 v[212:215], v220 offset:272
	ds_read_b128 v[216:219], v221 offset:272
	ds_read_b128 v[224:227], v220 offset:544
	ds_read_b128 v[234:237], v221 offset:544
.LBB0_634:
	ds_read_b128 v[238:241], v220 offset:816
	ds_read_b128 v[242:245], v221 offset:816
	s_waitcnt lgkmcnt(6)
	v_pk_fma_f32 v[14:15], v[204:205], v[208:209], v[14:15] op_sel_hi:[0,1,1]
	v_pk_fma_f32 v[16:17], v[204:205], v[210:211], v[16:17] op_sel_hi:[0,1,1]
	v_pk_fma_f32 v[10:11], v[204:205], v[208:209], v[10:11] op_sel:[1,0,0]
	v_pk_fma_f32 v[12:13], v[204:205], v[210:211], v[12:13] op_sel:[1,0,0]
	v_pk_fma_f32 v[6:7], v[206:207], v[208:209], v[6:7] op_sel_hi:[0,1,1]
	v_pk_fma_f32 v[8:9], v[206:207], v[210:211], v[8:9] op_sel_hi:[0,1,1]
	v_pk_fma_f32 v[2:3], v[206:207], v[208:209], v[2:3] op_sel:[1,0,0]
	v_pk_fma_f32 v[4:5], v[206:207], v[210:211], v[4:5] op_sel:[1,0,0]
	ds_read_b128 v[204:207], v220 offset:1088
	ds_read_b128 v[208:211], v221 offset:1088
	s_waitcnt lgkmcnt(6)
	v_pk_fma_f32 v[14:15], v[212:213], v[216:217], v[14:15] op_sel_hi:[0,1,1]
	v_pk_fma_f32 v[16:17], v[212:213], v[218:219], v[16:17] op_sel_hi:[0,1,1]
	v_pk_fma_f32 v[10:11], v[212:213], v[216:217], v[10:11] op_sel:[1,0,0]
	v_pk_fma_f32 v[12:13], v[212:213], v[218:219], v[12:13] op_sel:[1,0,0]
	v_pk_fma_f32 v[6:7], v[214:215], v[216:217], v[6:7] op_sel_hi:[0,1,1]
	v_pk_fma_f32 v[8:9], v[214:215], v[218:219], v[8:9] op_sel_hi:[0,1,1]
	v_pk_fma_f32 v[2:3], v[214:215], v[216:217], v[2:3] op_sel:[1,0,0]
	v_pk_fma_f32 v[4:5], v[214:215], v[218:219], v[4:5] op_sel:[1,0,0]
	ds_read_b128 v[212:215], v220 offset:1360
	ds_read_b128 v[216:219], v221 offset:1360
	s_waitcnt lgkmcnt(6)
	v_pk_fma_f32 v[14:15], v[224:225], v[234:235], v[14:15] op_sel_hi:[0,1,1]
	v_pk_fma_f32 v[16:17], v[224:225], v[236:237], v[16:17] op_sel_hi:[0,1,1]
	v_pk_fma_f32 v[10:11], v[224:225], v[234:235], v[10:11] op_sel:[1,0,0]
	v_pk_fma_f32 v[12:13], v[224:225], v[236:237], v[12:13] op_sel:[1,0,0]
	v_pk_fma_f32 v[6:7], v[226:227], v[234:235], v[6:7] op_sel_hi:[0,1,1]
	v_pk_fma_f32 v[8:9], v[226:227], v[236:237], v[8:9] op_sel_hi:[0,1,1]
	v_pk_fma_f32 v[2:3], v[226:227], v[234:235], v[2:3] op_sel:[1,0,0]
	v_pk_fma_f32 v[4:5], v[226:227], v[236:237], v[4:5] op_sel:[1,0,0]
	ds_read_b128 v[224:227], v220 offset:1632
	ds_read_b128 v[234:237], v221 offset:1632
	s_waitcnt lgkmcnt(6)
; #define ZERO44(a) { _Pragma("unroll") for (int _i = 0; _i < 4; ++_i) { _Pragma("unroll") for (int _j = 0; _j < 4; ++_j) a[_i][_j] = 0.f; } }
; __device__ __forceinline__ void mm64(const float* At, const float* B, float (&acc)[4][4], int ty, int tx) {
;     f32x2 c2[4][2];
; #pragma unroll
;     for (int rr = 0; rr < 4; ++rr) { c2[rr][0] = (f32x2){acc[rr][0], acc[rr][1]}; c2[rr][1] = (f32x2){acc[rr][2], acc[rr][3]}; }
; #pragma unroll 8
;     for (int k = 0; k < 64; ++k) {
;         const f32x4 a = *(const f32x4*)(At + k * DLD + 4 * ty);
;         const f32x4 b = *(const f32x4*)(B + k * DLD + 4 * tx);
;         const f32x2 b01 = {b.x, b.y}, b23 = {b.z, b.w};
; #pragma unroll
;         for (int rr = 0; rr < 4; ++rr) {
;             const f32x2 a2 = {a[rr], a[rr]};
;             c2[rr][0] = __builtin_elementwise_fma(a2, b01, c2[rr][0]);
;             c2[rr][1] = __builtin_elementwise_fma(a2, b23, c2[rr][1]);
;         }
;     }
; #pragma unroll
;     for (int rr = 0; rr < 4; ++rr) { acc[rr][0] = c2[rr][0].x; acc[rr][1] = c2[rr][0].y; acc[rr][2] = c2[rr][1].x; acc[rr][3] = c2[rr][1].y; }
; }
; __device__ __forceinline__ void dn1_item(const Params& p, int l, int item, unsigned char* lds) {
;     ...
;     float wacc[4][4], uacc[4][4]; ZERO44(wacc); ZERO44(uacc);
;     mm64(B0, B1, wacc, ty, tx);
; #pragma unroll
;     for (int e = 0; e < 16; e += 4) { f32x4 w = {vv[e] * beti, vv[e + 1] * beti, vv[e + 2] * beti, vv[e + 3] * beti}; *(f32x4*)(B2 + i * DLD + d0 + e) = w; }
;     __syncthreads();
;     mm64(B0, B2, uacc, ty, tx);
	v_pk_fma_f32 v[14:15], v[238:239], v[242:243], v[14:15] op_sel_hi:[0,1,1]
	v_pk_fma_f32 v[16:17], v[238:239], v[244:245], v[16:17] op_sel_hi:[0,1,1]
	v_pk_fma_f32 v[10:11], v[238:239], v[242:243], v[10:11] op_sel:[1,0,0]
	v_pk_fma_f32 v[12:13], v[238:239], v[244:245], v[12:13] op_sel:[1,0,0]
	v_pk_fma_f32 v[6:7], v[240:241], v[242:243], v[6:7] op_sel_hi:[0,1,1]
	v_pk_fma_f32 v[8:9], v[240:241], v[244:245], v[8:9] op_sel_hi:[0,1,1]
	v_pk_fma_f32 v[2:3], v[240:241], v[242:243], v[2:3] op_sel:[1,0,0]
	v_pk_fma_f32 v[4:5], v[240:241], v[244:245], v[4:5] op_sel:[1,0,0]
	ds_read_b128 v[238:241], v220 offset:1904
	ds_read_b128 v[242:245], v221 offset:1904
	s_waitcnt lgkmcnt(6)
	v_pk_fma_f32 v[14:15], v[204:205], v[208:209], v[14:15] op_sel_hi:[0,1,1]
	v_pk_fma_f32 v[16:17], v[204:205], v[210:211], v[16:17] op_sel_hi:[0,1,1]
	v_pk_fma_f32 v[10:11], v[204:205], v[208:209], v[10:11] op_sel:[1,0,0]
	v_pk_fma_f32 v[12:13], v[204:205], v[210:211], v[12:13] op_sel:[1,0,0]
	v_pk_fma_f32 v[6:7], v[206:207], v[208:209], v[6:7] op_sel_hi:[0,1,1]
	v_pk_fma_f32 v[8:9], v[206:207], v[210:211], v[8:9] op_sel_hi:[0,1,1]
	v_pk_fma_f32 v[2:3], v[206:207], v[208:209], v[2:3] op_sel:[1,0,0]
	v_pk_fma_f32 v[4:5], v[206:207], v[210:211], v[4:5] op_sel:[1,0,0]
	s_addk_i32 s0, 0x880
	v_add_u32_e32 v220, s0, v51
	v_add_u32_e32 v221, s0, v95
	ds_read_b128 v[204:207], v220
	ds_read_b128 v[208:211], v221
	s_waitcnt lgkmcnt(6)
	v_pk_fma_f32 v[14:15], v[212:213], v[216:217], v[14:15] op_sel_hi:[0,1,1]
	v_pk_fma_f32 v[16:17], v[212:213], v[218:219], v[16:17] op_sel_hi:[0,1,1]
	v_pk_fma_f32 v[10:11], v[212:213], v[216:217], v[10:11] op_sel:[1,0,0]
	v_pk_fma_f32 v[12:13], v[212:213], v[218:219], v[12:13] op_sel:[1,0,0]
	v_pk_fma_f32 v[6:7], v[214:215], v[216:217], v[6:7] op_sel_hi:[0,1,1]
	v_pk_fma_f32 v[8:9], v[214:215], v[218:219], v[8:9] op_sel_hi:[0,1,1]
	v_pk_fma_f32 v[2:3], v[214:215], v[216:217], v[2:3] op_sel:[1,0,0]
	v_pk_fma_f32 v[4:5], v[214:215], v[218:219], v[4:5] op_sel:[1,0,0]
	ds_read_b128 v[212:215], v220 offset:272
	ds_read_b128 v[216:219], v221 offset:272
	s_waitcnt lgkmcnt(6)
	v_pk_fma_f32 v[14:15], v[224:225], v[234:235], v[14:15] op_sel_hi:[0,1,1]
	v_pk_fma_f32 v[16:17], v[224:225], v[236:237], v[16:17] op_sel_hi:[0,1,1]
	v_pk_fma_f32 v[10:11], v[224:225], v[234:235], v[10:11] op_sel:[1,0,0]
	v_pk_fma_f32 v[12:13], v[224:225], v[236:237], v[12:13] op_sel:[1,0,0]
	v_pk_fma_f32 v[6:7], v[226:227], v[234:235], v[6:7] op_sel_hi:[0,1,1]
	v_pk_fma_f32 v[8:9], v[226:227], v[236:237], v[8:9] op_sel_hi:[0,1,1]
	v_pk_fma_f32 v[2:3], v[226:227], v[234:235], v[2:3] op_sel:[1,0,0]
	v_pk_fma_f32 v[4:5], v[226:227], v[236:237], v[4:5] op_sel:[1,0,0]
	ds_read_b128 v[224:227], v220 offset:544
	ds_read_b128 v[234:237], v221 offset:544
	s_waitcnt lgkmcnt(6)
	v_pk_fma_f32 v[14:15], v[238:239], v[242:243], v[14:15] op_sel_hi:[0,1,1]
	v_pk_fma_f32 v[16:17], v[238:239], v[244:245], v[16:17] op_sel_hi:[0,1,1]
	v_pk_fma_f32 v[10:11], v[238:239], v[242:243], v[10:11] op_sel:[1,0,0]
	v_pk_fma_f32 v[12:13], v[238:239], v[244:245], v[12:13] op_sel:[1,0,0]
	v_pk_fma_f32 v[6:7], v[240:241], v[242:243], v[6:7] op_sel_hi:[0,1,1]
	v_pk_fma_f32 v[8:9], v[240:241], v[244:245], v[8:9] op_sel_hi:[0,1,1]
	v_pk_fma_f32 v[2:3], v[240:241], v[242:243], v[2:3] op_sel:[1,0,0]
	v_pk_fma_f32 v[4:5], v[240:241], v[244:245], v[4:5] op_sel:[1,0,0]
	s_cmpk_lg_i32 s0, 0x4400
	s_cbranch_scc1 .LBB0_634
	s_waitcnt lgkmcnt(0)
	v_pk_mul_f32 v[18:19], v[22:23], v[30:31]
	v_pk_mul_f32 v[20:21], v[24:25], v[78:79]
	v_pk_mul_f32 v[18:19], v[18:19], v[92:93] op_sel_hi:[1,0]
	v_pk_mul_f32 v[20:21], v[20:21], v[92:93] op_sel_hi:[1,0]
	ds_write_b128 v53, v[18:21] offset:34816
	v_pk_mul_f32 v[18:19], v[26:27], v[80:81]
	v_pk_mul_f32 v[20:21], v[28:29], v[82:83]
	v_pk_mul_f32 v[18:19], v[18:19], v[92:93] op_sel_hi:[1,0]
	v_pk_mul_f32 v[20:21], v[20:21], v[92:93] op_sel_hi:[1,0]
	ds_write_b128 v53, v[18:21] offset:34832
	v_pk_mul_f32 v[18:19], v[32:33], v[84:85]
	v_pk_mul_f32 v[20:21], v[70:71], v[86:87]
	v_pk_mul_f32 v[18:19], v[18:19], v[92:93] op_sel_hi:[1,0]
	v_pk_mul_f32 v[20:21], v[20:21], v[92:93] op_sel_hi:[1,0]
	ds_write_b128 v53, v[18:21] offset:34848
	v_pk_mul_f32 v[18:19], v[72:73], v[88:89]
	v_pk_mul_f32 v[20:21], v[74:75], v[90:91]
	v_pk_mul_f32 v[18:19], v[18:19], v[92:93] op_sel_hi:[1,0]
	v_pk_mul_f32 v[20:21], v[20:21], v[92:93] op_sel_hi:[1,0]
	ds_write_b128 v53, v[18:21] offset:34864
	v_readlane_b32 s0, v253, 51
	v_mov_b32_e32 v20, 0
	v_mov_b32_e32 v21, v20
	v_add_u32_e32 v70, s0, v94
	s_mov_b32 s0, 0
	v_mov_b32_e32 v30, v20
	v_mov_b32_e32 v31, v20
	v_mov_b32_e32 v32, v20
	v_mov_b32_e32 v33, v20
	v_mov_b32_e32 v26, v20
	v_mov_b32_e32 v27, v20
	v_mov_b32_e32 v28, v20
	v_mov_b32_e32 v29, v20
	v_mov_b32_e32 v22, v20
	v_mov_b32_e32 v23, v20
	v_mov_b32_e32 v24, v20
	v_mov_b32_e32 v25, v20
	v_mov_b32_e32 v18, v20
	v_mov_b32_e32 v19, v20
	s_waitcnt lgkmcnt(0)
	s_barrier
	v_add_u32_e32 v220, s0, v51
	v_add_u32_e32 v221, s0, v70
	ds_read_b128 v[204:207], v220
	ds_read_b128 v[208:211], v221
	ds_read_b128 v[212:215], v220 offset:272
	ds_read_b128 v[216:219], v221 offset:272
	ds_read_b128 v[224:227], v220 offset:544
	ds_read_b128 v[234:237], v221 offset:544
; __device__ __forceinline__ void mm64(const float* At, const float* B, float (&acc)[4][4], int ty, int tx) {
;     f32x2 c2[4][2];
; #pragma unroll
;     for (int rr = 0; rr < 4; ++rr) { c2[rr][0] = (f32x2){acc[rr][0], acc[rr][1]}; c2[rr][1] = (f32x2){acc[rr][2], acc[rr][3]}; }
; #pragma unroll 8
;     for (int k = 0; k < 64; ++k) {
;         const f32x4 a = *(const f32x4*)(At + k * DLD + 4 * ty);
;         const f32x4 b = *(const f32x4*)(B + k * DLD + 4 * tx);
;         const f32x2 b01 = {b.x, b.y}, b23 = {b.z, b.w};
; #pragma unroll
;         for (int rr = 0; rr < 4; ++rr) {
;             const f32x2 a2 = {a[rr], a[rr]};
;             c2[rr][0] = __builtin_elementwise_fma(a2, b01, c2[rr][0]);
;             c2[rr][1] = __builtin_elementwise_fma(a2, b23, c2[rr][1]);
;         }
;     }
; #pragma unroll
;     for (int rr = 0; rr < 4; ++rr) { acc[rr][0] = c2[rr][0].x; acc[rr][1] = c2[rr][0].y; acc[rr][2] = c2[rr][1].x; acc[rr][3] = c2[rr][1].y; }
; }
.LBB0_636:
	ds_read_b128 v[238:241], v220 offset:816
	ds_read_b128 v[242:245], v221 offset:816
	s_waitcnt lgkmcnt(6)
	v_pk_fma_f32 v[30:31], v[204:205], v[208:209], v[30:31] op_sel_hi:[0,1,1]
	v_pk_fma_f32 v[32:33], v[204:205], v[210:211], v[32:33] op_sel_hi:[0,1,1]
	v_pk_fma_f32 v[26:27], v[204:205], v[208:209], v[26:27] op_sel:[1,0,0]
	v_pk_fma_f32 v[28:29], v[204:205], v[210:211], v[28:29] op_sel:[1,0,0]
	v_pk_fma_f32 v[22:23], v[206:207], v[208:209], v[22:23] op_sel_hi:[0,1,1]
	v_pk_fma_f32 v[24:25], v[206:207], v[210:211], v[24:25] op_sel_hi:[0,1,1]
	v_pk_fma_f32 v[18:19], v[206:207], v[208:209], v[18:19] op_sel:[1,0,0]
	v_pk_fma_f32 v[20:21], v[206:207], v[210:211], v[20:21] op_sel:[1,0,0]
	ds_read_b128 v[204:207], v220 offset:1088
	ds_read_b128 v[208:211], v221 offset:1088
	s_waitcnt lgkmcnt(6)
	v_pk_fma_f32 v[30:31], v[212:213], v[216:217], v[30:31] op_sel_hi:[0,1,1]
	v_pk_fma_f32 v[32:33], v[212:213], v[218:219], v[32:33] op_sel_hi:[0,1,1]
	v_pk_fma_f32 v[26:27], v[212:213], v[216:217], v[26:27] op_sel:[1,0,0]
	v_pk_fma_f32 v[28:29], v[212:213], v[218:219], v[28:29] op_sel:[1,0,0]
	v_pk_fma_f32 v[22:23], v[214:215], v[216:217], v[22:23] op_sel_hi:[0,1,1]
	v_pk_fma_f32 v[24:25], v[214:215], v[218:219], v[24:25] op_sel_hi:[0,1,1]
	v_pk_fma_f32 v[18:19], v[214:215], v[216:217], v[18:19] op_sel:[1,0,0]
	v_pk_fma_f32 v[20:21], v[214:215], v[218:219], v[20:21] op_sel:[1,0,0]
	ds_read_b128 v[212:215], v220 offset:1360
	ds_read_b128 v[216:219], v221 offset:1360
	s_waitcnt lgkmcnt(6)
	v_pk_fma_f32 v[30:31], v[224:225], v[234:235], v[30:31] op_sel_hi:[0,1,1]
	v_pk_fma_f32 v[32:33], v[224:225], v[236:237], v[32:33] op_sel_hi:[0,1,1]
	v_pk_fma_f32 v[26:27], v[224:225], v[234:235], v[26:27] op_sel:[1,0,0]
	v_pk_fma_f32 v[28:29], v[224:225], v[236:237], v[28:29] op_sel:[1,0,0]
	v_pk_fma_f32 v[22:23], v[226:227], v[234:235], v[22:23] op_sel_hi:[0,1,1]
	v_pk_fma_f32 v[24:25], v[226:227], v[236:237], v[24:25] op_sel_hi:[0,1,1]
	v_pk_fma_f32 v[18:19], v[226:227], v[234:235], v[18:19] op_sel:[1,0,0]
	v_pk_fma_f32 v[20:21], v[226:227], v[236:237], v[20:21] op_sel:[1,0,0]
	ds_read_b128 v[224:227], v220 offset:1632
	ds_read_b128 v[234:237], v221 offset:1632
	s_waitcnt lgkmcnt(6)
	v_pk_fma_f32 v[30:31], v[238:239], v[242:243], v[30:31] op_sel_hi:[0,1,1]
	v_pk_fma_f32 v[32:33], v[238:239], v[244:245], v[32:33] op_sel_hi:[0,1,1]
	v_pk_fma_f32 v[26:27], v[238:239], v[242:243], v[26:27] op_sel:[1,0,0]
	v_pk_fma_f32 v[28:29], v[238:239], v[244:245], v[28:29] op_sel:[1,0,0]
	v_pk_fma_f32 v[22:23], v[240:241], v[242:243], v[22:23] op_sel_hi:[0,1,1]
	v_pk_fma_f32 v[24:25], v[240:241], v[244:245], v[24:25] op_sel_hi:[0,1,1]
	v_pk_fma_f32 v[18:19], v[240:241], v[242:243], v[18:19] op_sel:[1,0,0]
	v_pk_fma_f32 v[20:21], v[240:241], v[244:245], v[20:21] op_sel:[1,0,0]
	ds_read_b128 v[238:241], v220 offset:1904
	ds_read_b128 v[242:245], v221 offset:1904
	s_waitcnt lgkmcnt(6)
	v_pk_fma_f32 v[30:31], v[204:205], v[208:209], v[30:31] op_sel_hi:[0,1,1]
	v_pk_fma_f32 v[32:33], v[204:205], v[210:211], v[32:33] op_sel_hi:[0,1,1]
	v_pk_fma_f32 v[26:27], v[204:205], v[208:209], v[26:27] op_sel:[1,0,0]
	v_pk_fma_f32 v[28:29], v[204:205], v[210:211], v[28:29] op_sel:[1,0,0]
	v_pk_fma_f32 v[22:23], v[206:207], v[208:209], v[22:23] op_sel_hi:[0,1,1]
	v_pk_fma_f32 v[24:25], v[206:207], v[210:211], v[24:25] op_sel_hi:[0,1,1]
	v_pk_fma_f32 v[18:19], v[206:207], v[208:209], v[18:19] op_sel:[1,0,0]
	v_pk_fma_f32 v[20:21], v[206:207], v[210:211], v[20:21] op_sel:[1,0,0]
	s_addk_i32 s0, 0x880
	v_add_u32_e32 v220, s0, v51
	v_add_u32_e32 v221, s0, v70
	ds_read_b128 v[204:207], v220
	ds_read_b128 v[208:211], v221
	s_waitcnt lgkmcnt(6)
	v_pk_fma_f32 v[30:31], v[212:213], v[216:217], v[30:31] op_sel_hi:[0,1,1]
	v_pk_fma_f32 v[32:33], v[212:213], v[218:219], v[32:33] op_sel_hi:[0,1,1]
	v_pk_fma_f32 v[26:27], v[212:213], v[216:217], v[26:27] op_sel:[1,0,0]
	v_pk_fma_f32 v[28:29], v[212:213], v[218:219], v[28:29] op_sel:[1,0,0]
	v_pk_fma_f32 v[22:23], v[214:215], v[216:217], v[22:23] op_sel_hi:[0,1,1]
	v_pk_fma_f32 v[24:25], v[214:215], v[218:219], v[24:25] op_sel_hi:[0,1,1]
	v_pk_fma_f32 v[18:19], v[214:215], v[216:217], v[18:19] op_sel:[1,0,0]
	v_pk_fma_f32 v[20:21], v[214:215], v[218:219], v[20:21] op_sel:[1,0,0]
	ds_read_b128 v[212:215], v220 offset:272
	ds_read_b128 v[216:219], v221 offset:272
	s_waitcnt lgkmcnt(6)
	v_pk_fma_f32 v[30:31], v[224:225], v[234:235], v[30:31] op_sel_hi:[0,1,1]
	v_pk_fma_f32 v[32:33], v[224:225], v[236:237], v[32:33] op_sel_hi:[0,1,1]
	v_pk_fma_f32 v[26:27], v[224:225], v[234:235], v[26:27] op_sel:[1,0,0]
	v_pk_fma_f32 v[28:29], v[224:225], v[236:237], v[28:29] op_sel:[1,0,0]
	v_pk_fma_f32 v[22:23], v[226:227], v[234:235], v[22:23] op_sel_hi:[0,1,1]
	v_pk_fma_f32 v[24:25], v[226:227], v[236:237], v[24:25] op_sel_hi:[0,1,1]
	v_pk_fma_f32 v[18:19], v[226:227], v[234:235], v[18:19] op_sel:[1,0,0]
	v_pk_fma_f32 v[20:21], v[226:227], v[236:237], v[20:21] op_sel:[1,0,0]
	ds_read_b128 v[224:227], v220 offset:544
	ds_read_b128 v[234:237], v221 offset:544
	s_waitcnt lgkmcnt(6)
	v_pk_fma_f32 v[30:31], v[238:239], v[242:243], v[30:31] op_sel_hi:[0,1,1]
	v_pk_fma_f32 v[32:33], v[238:239], v[244:245], v[32:33] op_sel_hi:[0,1,1]
	v_pk_fma_f32 v[26:27], v[238:239], v[242:243], v[26:27] op_sel:[1,0,0]
	v_pk_fma_f32 v[28:29], v[238:239], v[244:245], v[28:29] op_sel:[1,0,0]
	v_pk_fma_f32 v[22:23], v[240:241], v[242:243], v[22:23] op_sel_hi:[0,1,1]
	v_pk_fma_f32 v[24:25], v[240:241], v[244:245], v[24:25] op_sel_hi:[0,1,1]
	v_pk_fma_f32 v[18:19], v[240:241], v[242:243], v[18:19] op_sel:[1,0,0]
	v_pk_fma_f32 v[20:21], v[240:241], v[244:245], v[20:21] op_sel:[1,0,0]
	s_cmpk_lg_i32 s0, 0x4400
	s_cbranch_scc1 .LBB0_636
; #define ZERO44(a) { _Pragma("unroll") for (int _i = 0; _i < 4; ++_i) { _Pragma("unroll") for (int _j = 0; _j < 4; ++_j) a[_i][_j] = 0.f; } }
; __device__ __forceinline__ void mm64(const float* At, const float* B, float (&acc)[4][4], int ty, int tx) {
;     ...
;     for (int k = 0; k < 64; ++k) {
;         const f32x4 a = *(const f32x4*)(At + k * DLD + 4 * ty);
;         const f32x4 b = *(const f32x4*)(B + k * DLD + 4 * tx);
;         const f32x2 b01 = {b.x, b.y}, b23 = {b.z, b.w};
; #pragma unroll
;         for (int rr = 0; rr < 4; ++rr) {
;             const f32x2 a2 = {a[rr], a[rr]};
;             c2[rr][0] = __builtin_elementwise_fma(a2, b01, c2[rr][0]);
;             c2[rr][1] = __builtin_elementwise_fma(a2, b23, c2[rr][1]);
;         }
;     }
; __device__ __forceinline__ void dn1_item(const Params& p, int l, int item, unsigned char* lds) {
;     ...
;     __syncthreads();
; #pragma unroll
;     for (int rr = 0; rr < 4; ++rr) {
;         f32x4 w = {wacc[rr][0], wacc[rr][1], wacc[rr][2], wacc[rr][3]}; *(f32x4*)(B1 + (4 * ty + rr) * DLD + 4 * tx) = w;
;         f32x4 u = {uacc[rr][0], uacc[rr][1], uacc[rr][2], uacc[rr][3]}; *(f32x4*)(B2 + (4 * ty + rr) * DLD + 4 * tx) = u;
;     }
;     {
;         const float s = __expf(gcl - gci);
; #pragma unroll
;         for (int e = 0; e < 16; e += 4) { f32x4 w = {kn[e] * s, kn[e + 1] * s, kn[e + 2] * s, kn[e + 3] * s}; *(f32x4*)(B0 + i * DLD + d0 + e) = w; }
;     }
;     __syncthreads();
;     {
;         float a1[4][4]; ZERO44(a1);
;         mm64(B0, B1, a1, ty, tx);
	s_waitcnt lgkmcnt(0)
	v_lshl_add_u32 v71, v96, 2, v76
	s_movk_i32 s0, 0x110
	s_barrier
	ds_write_b128 v71, v[14:17] offset:17408
	ds_write_b128 v71, v[30:33] offset:34816
	v_mad_u64_u32 v[14:15], s[0:1], v103, s0, v[76:77]
	ds_write_b128 v14, v[10:13] offset:17408
	ds_write_b128 v14, v[26:29] offset:34816
	ds_write_b128 v14, v[6:9] offset:17680
	v_sub_f32_e32 v6, v106, v109
	v_mul_f32_e32 v6, 0x3fb8aa3b, v6
	v_exp_f32_e32 v6, v6
	ds_write_b128 v14, v[22:25] offset:35088
	ds_write_b128 v14, v[2:5] offset:17952
	ds_write_b128 v14, v[18:21] offset:35360
	s_mov_b32 s0, 0
	v_pk_mul_f32 v[4:5], v[68:69], v[6:7] op_sel_hi:[1,0]
	v_pk_mul_f32 v[2:3], v[66:67], v[6:7] op_sel_hi:[1,0]
	ds_write_b128 v53, v[2:5]
	v_pk_mul_f32 v[4:5], v[64:65], v[6:7] op_sel_hi:[1,0]
	v_pk_mul_f32 v[2:3], v[62:63], v[6:7] op_sel_hi:[1,0]
	ds_write_b128 v53, v[2:5] offset:16
	v_pk_mul_f32 v[4:5], v[60:61], v[6:7] op_sel_hi:[1,0]
	v_pk_mul_f32 v[2:3], v[58:59], v[6:7] op_sel_hi:[1,0]
	ds_write_b128 v53, v[2:5] offset:32
	v_pk_mul_f32 v[4:5], v[56:57], v[6:7] op_sel_hi:[1,0]
	v_pk_mul_f32 v[2:3], v[54:55], v[6:7] op_sel_hi:[1,0]
	ds_write_b128 v53, v[2:5] offset:48
	v_mov_b32_e32 v2, 0
	v_mov_b32_e32 v3, v2
	v_mov_b32_e32 v14, v2
	v_mov_b32_e32 v15, v2
	v_mov_b32_e32 v16, v2
	v_mov_b32_e32 v17, v2
	v_mov_b32_e32 v10, v2
	v_mov_b32_e32 v11, v2
	v_mov_b32_e32 v12, v2
	v_mov_b32_e32 v13, v2
	v_mov_b32_e32 v6, v2
	v_mov_b32_e32 v7, v2
	v_mov_b32_e32 v8, v2
	v_mov_b32_e32 v9, v2
	v_mov_b32_e32 v4, v2
	v_mov_b32_e32 v5, v2
	s_waitcnt lgkmcnt(0)
	s_barrier
	v_add_u32_e32 v220, s0, v51
	v_add_u32_e32 v221, s0, v95
	ds_read_b128 v[204:207], v220
	ds_read_b128 v[208:211], v221
	ds_read_b128 v[212:215], v220 offset:272
	ds_read_b128 v[216:219], v221 offset:272
	ds_read_b128 v[224:227], v220 offset:544
	ds_read_b128 v[234:237], v221 offset:544
.LBB0_638:
	ds_read_b128 v[238:241], v220 offset:816
	ds_read_b128 v[242:245], v221 offset:816
	s_waitcnt lgkmcnt(6)
	v_pk_fma_f32 v[14:15], v[204:205], v[208:209], v[14:15] op_sel_hi:[0,1,1]
	v_pk_fma_f32 v[16:17], v[204:205], v[210:211], v[16:17] op_sel_hi:[0,1,1]
	v_pk_fma_f32 v[10:11], v[204:205], v[208:209], v[10:11] op_sel:[1,0,0]
	v_pk_fma_f32 v[12:13], v[204:205], v[210:211], v[12:13] op_sel:[1,0,0]
	v_pk_fma_f32 v[6:7], v[206:207], v[208:209], v[6:7] op_sel_hi:[0,1,1]
	v_pk_fma_f32 v[8:9], v[206:207], v[210:211], v[8:9] op_sel_hi:[0,1,1]
	v_pk_fma_f32 v[4:5], v[206:207], v[208:209], v[4:5] op_sel:[1,0,0]
	v_pk_fma_f32 v[2:3], v[206:207], v[210:211], v[2:3] op_sel:[1,0,0]
	ds_read_b128 v[204:207], v220 offset:1088
	ds_read_b128 v[208:211], v221 offset:1088
	s_waitcnt lgkmcnt(6)
	v_pk_fma_f32 v[14:15], v[212:213], v[216:217], v[14:15] op_sel_hi:[0,1,1]
	v_pk_fma_f32 v[16:17], v[212:213], v[218:219], v[16:17] op_sel_hi:[0,1,1]
	v_pk_fma_f32 v[10:11], v[212:213], v[216:217], v[10:11] op_sel:[1,0,0]
	v_pk_fma_f32 v[12:13], v[212:213], v[218:219], v[12:13] op_sel:[1,0,0]
	v_pk_fma_f32 v[6:7], v[214:215], v[216:217], v[6:7] op_sel_hi:[0,1,1]
	v_pk_fma_f32 v[8:9], v[214:215], v[218:219], v[8:9] op_sel_hi:[0,1,1]
	v_pk_fma_f32 v[4:5], v[214:215], v[216:217], v[4:5] op_sel:[1,0,0]
	v_pk_fma_f32 v[2:3], v[214:215], v[218:219], v[2:3] op_sel:[1,0,0]
	ds_read_b128 v[212:215], v220 offset:1360
	ds_read_b128 v[216:219], v221 offset:1360
	s_waitcnt lgkmcnt(6)
	v_pk_fma_f32 v[14:15], v[224:225], v[234:235], v[14:15] op_sel_hi:[0,1,1]
	v_pk_fma_f32 v[16:17], v[224:225], v[236:237], v[16:17] op_sel_hi:[0,1,1]
	v_pk_fma_f32 v[10:11], v[224:225], v[234:235], v[10:11] op_sel:[1,0,0]
	v_pk_fma_f32 v[12:13], v[224:225], v[236:237], v[12:13] op_sel:[1,0,0]
	v_pk_fma_f32 v[6:7], v[226:227], v[234:235], v[6:7] op_sel_hi:[0,1,1]
	v_pk_fma_f32 v[8:9], v[226:227], v[236:237], v[8:9] op_sel_hi:[0,1,1]
	v_pk_fma_f32 v[4:5], v[226:227], v[234:235], v[4:5] op_sel:[1,0,0]
	v_pk_fma_f32 v[2:3], v[226:227], v[236:237], v[2:3] op_sel:[1,0,0]
	ds_read_b128 v[224:227], v220 offset:1632
	ds_read_b128 v[234:237], v221 offset:1632
	s_waitcnt lgkmcnt(6)
	v_pk_fma_f32 v[14:15], v[238:239], v[242:243], v[14:15] op_sel_hi:[0,1,1]
	v_pk_fma_f32 v[16:17], v[238:239], v[244:245], v[16:17] op_sel_hi:[0,1,1]
	v_pk_fma_f32 v[10:11], v[238:239], v[242:243], v[10:11] op_sel:[1,0,0]
	v_pk_fma_f32 v[12:13], v[238:239], v[244:245], v[12:13] op_sel:[1,0,0]
	v_pk_fma_f32 v[6:7], v[240:241], v[242:243], v[6:7] op_sel_hi:[0,1,1]
	v_pk_fma_f32 v[8:9], v[240:241], v[244:245], v[8:9] op_sel_hi:[0,1,1]
	v_pk_fma_f32 v[4:5], v[240:241], v[242:243], v[4:5] op_sel:[1,0,0]
	v_pk_fma_f32 v[2:3], v[240:241], v[244:245], v[2:3] op_sel:[1,0,0]
	ds_read_b128 v[238:241], v220 offset:1904
	ds_read_b128 v[242:245], v221 offset:1904
	s_waitcnt lgkmcnt(6)
	v_pk_fma_f32 v[14:15], v[204:205], v[208:209], v[14:15] op_sel_hi:[0,1,1]
	v_pk_fma_f32 v[16:17], v[204:205], v[210:211], v[16:17] op_sel_hi:[0,1,1]
	v_pk_fma_f32 v[10:11], v[204:205], v[208:209], v[10:11] op_sel:[1,0,0]
	v_pk_fma_f32 v[12:13], v[204:205], v[210:211], v[12:13] op_sel:[1,0,0]
	v_pk_fma_f32 v[6:7], v[206:207], v[208:209], v[6:7] op_sel_hi:[0,1,1]
	v_pk_fma_f32 v[8:9], v[206:207], v[210:211], v[8:9] op_sel_hi:[0,1,1]
	v_pk_fma_f32 v[4:5], v[206:207], v[208:209], v[4:5] op_sel:[1,0,0]
	v_pk_fma_f32 v[2:3], v[206:207], v[210:211], v[2:3] op_sel:[1,0,0]
	s_addk_i32 s0, 0x880
	v_add_u32_e32 v220, s0, v51
	v_add_u32_e32 v221, s0, v95
	ds_read_b128 v[204:207], v220
	ds_read_b128 v[208:211], v221
	s_waitcnt lgkmcnt(6)
; #define ZERO44(a) { _Pragma("unroll") for (int _i = 0; _i < 4; ++_i) { _Pragma("unroll") for (int _j = 0; _j < 4; ++_j) a[_i][_j] = 0.f; } }
; __device__ __forceinline__ void mm64(const float* At, const float* B, float (&acc)[4][4], int ty, int tx) {
;     ...
;     for (int k = 0; k < 64; ++k) {
;         const f32x4 a = *(const f32x4*)(At + k * DLD + 4 * ty);
;         const f32x4 b = *(const f32x4*)(B + k * DLD + 4 * tx);
;         const f32x2 b01 = {b.x, b.y}, b23 = {b.z, b.w};
; #pragma unroll
;         for (int rr = 0; rr < 4; ++rr) {
;             const f32x2 a2 = {a[rr], a[rr]};
;             c2[rr][0] = __builtin_elementwise_fma(a2, b01, c2[rr][0]);
;             c2[rr][1] = __builtin_elementwise_fma(a2, b23, c2[rr][1]);
;         }
;     }
; __device__ __forceinline__ void dn1_item(const Params& p, int l, int item, unsigned char* lds) {
;     ...
;         mm64(B0, B1, a1, ty, tx);
; #pragma unroll
;         for (int rr = 0; rr < 4; ++rr) {
;             f32x4 w;
; #pragma unroll
;             for (int cc = 0; cc < 4; ++cc) w[cc] = ((4 * ty + rr) == (4 * tx + cc) ? gl : 0.f) - a1[rr][cc];
;             *(f32x4*)(DNA + (4 * ty + rr) * 64 + 4 * tx) = w;
;         }
;         ZERO44(a1);
;         mm64(B0, B2, a1, ty, tx);
	v_pk_fma_f32 v[14:15], v[212:213], v[216:217], v[14:15] op_sel_hi:[0,1,1]
	v_pk_fma_f32 v[16:17], v[212:213], v[218:219], v[16:17] op_sel_hi:[0,1,1]
	v_pk_fma_f32 v[10:11], v[212:213], v[216:217], v[10:11] op_sel:[1,0,0]
	v_pk_fma_f32 v[12:13], v[212:213], v[218:219], v[12:13] op_sel:[1,0,0]
	v_pk_fma_f32 v[6:7], v[214:215], v[216:217], v[6:7] op_sel_hi:[0,1,1]
	v_pk_fma_f32 v[8:9], v[214:215], v[218:219], v[8:9] op_sel_hi:[0,1,1]
	v_pk_fma_f32 v[4:5], v[214:215], v[216:217], v[4:5] op_sel:[1,0,0]
	v_pk_fma_f32 v[2:3], v[214:215], v[218:219], v[2:3] op_sel:[1,0,0]
	ds_read_b128 v[212:215], v220 offset:272
	ds_read_b128 v[216:219], v221 offset:272
	s_waitcnt lgkmcnt(6)
	v_pk_fma_f32 v[14:15], v[224:225], v[234:235], v[14:15] op_sel_hi:[0,1,1]
	v_pk_fma_f32 v[16:17], v[224:225], v[236:237], v[16:17] op_sel_hi:[0,1,1]
	v_pk_fma_f32 v[10:11], v[224:225], v[234:235], v[10:11] op_sel:[1,0,0]
	v_pk_fma_f32 v[12:13], v[224:225], v[236:237], v[12:13] op_sel:[1,0,0]
	v_pk_fma_f32 v[6:7], v[226:227], v[234:235], v[6:7] op_sel_hi:[0,1,1]
	v_pk_fma_f32 v[8:9], v[226:227], v[236:237], v[8:9] op_sel_hi:[0,1,1]
	v_pk_fma_f32 v[4:5], v[226:227], v[234:235], v[4:5] op_sel:[1,0,0]
	v_pk_fma_f32 v[2:3], v[226:227], v[236:237], v[2:3] op_sel:[1,0,0]
	ds_read_b128 v[224:227], v220 offset:544
	ds_read_b128 v[234:237], v221 offset:544
	s_waitcnt lgkmcnt(6)
	v_pk_fma_f32 v[14:15], v[238:239], v[242:243], v[14:15] op_sel_hi:[0,1,1]
	v_pk_fma_f32 v[16:17], v[238:239], v[244:245], v[16:17] op_sel_hi:[0,1,1]
	v_pk_fma_f32 v[10:11], v[238:239], v[242:243], v[10:11] op_sel:[1,0,0]
	v_pk_fma_f32 v[12:13], v[238:239], v[244:245], v[12:13] op_sel:[1,0,0]
	v_pk_fma_f32 v[6:7], v[240:241], v[242:243], v[6:7] op_sel_hi:[0,1,1]
	v_pk_fma_f32 v[8:9], v[240:241], v[244:245], v[8:9] op_sel_hi:[0,1,1]
	v_pk_fma_f32 v[4:5], v[240:241], v[242:243], v[4:5] op_sel:[1,0,0]
	v_pk_fma_f32 v[2:3], v[240:241], v[244:245], v[2:3] op_sel:[1,0,0]
	s_cmpk_lg_i32 s0, 0x4400
	s_cbranch_scc1 .LBB0_638
	s_waitcnt lgkmcnt(0)
	v_mul_f32_e32 v18, 0x3fb8aa3b, v106
	v_exp_f32_e32 v19, v18
	s_lshl_b32 s88, s21, 12
	s_lshl_b64 s[0:1], s[88:89], 2
	s_add_u32 s4, s3, s0
	s_addc_u32 s5, s8, s1
	v_lshlrev_b32_e32 v18, 8, v104
	v_cmp_eq_u32_e32 vcc, v105, v50
	v_lshl_add_u64 v[20:21], s[4:5], 0, v[0:1]
	v_pk_add_f32 v[16:17], v[16:17], 0 op_sel_hi:[1,0] neg_lo:[1,0] neg_hi:[1,0]
	v_cndmask_b32_e32 v0, 0, v19, vcc
	v_ashrrev_i32_e32 v19, 31, v18
	v_pk_add_f32 v[14:15], v[0:1], v[14:15] neg_lo:[0,1] neg_hi:[0,1]
	v_lshl_add_u64 v[20:21], v[18:19], 2, v[20:21]
	global_store_dwordx4 v[20:21], v[14:17], off
	v_pk_add_f32 v[6:7], v[6:7], 0 op_sel_hi:[1,0] neg_lo:[1,0] neg_hi:[1,0]
	v_pk_add_f32 v[8:9], v[0:1], v[8:9] neg_lo:[0,1] neg_hi:[0,1]
	v_mov_b32_e32 v14, v1
	v_mov_b32_e32 v15, v0
	global_store_dwordx4 v[20:21], v[6:9], off offset:512
	v_pk_add_f32 v[4:5], v[4:5], 0 op_sel_hi:[1,0] neg_lo:[1,0] neg_hi:[1,0]
	v_pk_add_f32 v[10:11], v[14:15], v[10:11] neg_lo:[0,1] neg_hi:[0,1]
	v_pk_add_f32 v[6:7], v[14:15], v[2:3] neg_lo:[0,1] neg_hi:[0,1]
	v_pk_add_f32 v[12:13], v[12:13], 0 op_sel_hi:[1,0] neg_lo:[1,0] neg_hi:[1,0]
	global_store_dwordx4 v[20:21], v[4:7], off offset:768
	s_mov_b32 s4, 0
	global_store_dwordx4 v[20:21], v[10:13], off offset:256
	v_mov_b32_e32 v4, 0
	v_mov_b32_e32 v5, v4
	v_mov_b32_e32 v14, v4
	v_mov_b32_e32 v15, v4
	v_mov_b32_e32 v16, v4
	v_mov_b32_e32 v17, v4
	v_mov_b32_e32 v10, v4
	v_mov_b32_e32 v11, v4
	v_mov_b32_e32 v12, v4
	v_mov_b32_e32 v13, v4
	v_mov_b32_e32 v6, v4
	v_mov_b32_e32 v7, v4
	v_mov_b32_e32 v8, v4
	v_mov_b32_e32 v9, v4
	v_mov_b32_e32 v2, v4
	v_mov_b32_e32 v3, v4
	v_add_u32_e32 v220, s4, v51
	v_add_u32_e32 v221, s4, v70
	ds_read_b128 v[204:207], v220
	ds_read_b128 v[208:211], v221
	ds_read_b128 v[212:215], v220 offset:272
	ds_read_b128 v[216:219], v221 offset:272
	ds_read_b128 v[224:227], v220 offset:544
	ds_read_b128 v[234:237], v221 offset:544
.LBB0_640:
	ds_read_b128 v[238:241], v220 offset:816
	ds_read_b128 v[242:245], v221 offset:816
	s_waitcnt lgkmcnt(6)
	v_pk_fma_f32 v[14:15], v[204:205], v[208:209], v[14:15] op_sel_hi:[0,1,1]
	v_pk_fma_f32 v[16:17], v[204:205], v[210:211], v[16:17] op_sel_hi:[0,1,1]
	v_pk_fma_f32 v[10:11], v[204:205], v[208:209], v[10:11] op_sel:[1,0,0]
	v_pk_fma_f32 v[12:13], v[204:205], v[210:211], v[12:13] op_sel:[1,0,0]
	v_pk_fma_f32 v[6:7], v[206:207], v[208:209], v[6:7] op_sel_hi:[0,1,1]
	v_pk_fma_f32 v[8:9], v[206:207], v[210:211], v[8:9] op_sel_hi:[0,1,1]
	v_pk_fma_f32 v[2:3], v[206:207], v[208:209], v[2:3] op_sel:[1,0,0]
	v_pk_fma_f32 v[4:5], v[206:207], v[210:211], v[4:5] op_sel:[1,0,0]
	ds_read_b128 v[204:207], v220 offset:1088
	ds_read_b128 v[208:211], v221 offset:1088
	s_waitcnt lgkmcnt(6)
	v_pk_fma_f32 v[14:15], v[212:213], v[216:217], v[14:15] op_sel_hi:[0,1,1]
	v_pk_fma_f32 v[16:17], v[212:213], v[218:219], v[16:17] op_sel_hi:[0,1,1]
	v_pk_fma_f32 v[10:11], v[212:213], v[216:217], v[10:11] op_sel:[1,0,0]
	v_pk_fma_f32 v[12:13], v[212:213], v[218:219], v[12:13] op_sel:[1,0,0]
	v_pk_fma_f32 v[6:7], v[214:215], v[216:217], v[6:7] op_sel_hi:[0,1,1]
	v_pk_fma_f32 v[8:9], v[214:215], v[218:219], v[8:9] op_sel_hi:[0,1,1]
	v_pk_fma_f32 v[2:3], v[214:215], v[216:217], v[2:3] op_sel:[1,0,0]
	v_pk_fma_f32 v[4:5], v[214:215], v[218:219], v[4:5] op_sel:[1,0,0]
	ds_read_b128 v[212:215], v220 offset:1360
	ds_read_b128 v[216:219], v221 offset:1360
	s_waitcnt lgkmcnt(6)
; #define ZERO44(a) { _Pragma("unroll") for (int _i = 0; _i < 4; ++_i) { _Pragma("unroll") for (int _j = 0; _j < 4; ++_j) a[_i][_j] = 0.f; } }
; __device__ __forceinline__ void mm64(const float* At, const float* B, float (&acc)[4][4], int ty, int tx) {
;     ...
;     for (int k = 0; k < 64; ++k) {
;         const f32x4 a = *(const f32x4*)(At + k * DLD + 4 * ty);
;         const f32x4 b = *(const f32x4*)(B + k * DLD + 4 * tx);
;         const f32x2 b01 = {b.x, b.y}, b23 = {b.z, b.w};
; #pragma unroll
;         for (int rr = 0; rr < 4; ++rr) {
;             const f32x2 a2 = {a[rr], a[rr]};
;             c2[rr][0] = __builtin_elementwise_fma(a2, b01, c2[rr][0]);
;             c2[rr][1] = __builtin_elementwise_fma(a2, b23, c2[rr][1]);
;         }
;     }
; __device__ __forceinline__ void dn1_item(const Params& p, int l, int item, unsigned char* lds) {
;     ...
;         mm64(B0, B2, a1, ty, tx);
; #pragma unroll
;         for (int rr = 0; rr < 4; ++rr) { f32x4 w = {a1[rr][0], a1[rr][1], a1[rr][2], a1[rr][3]}; *(f32x4*)(DNB + (4 * ty + rr) * 64 + 4 * tx) = w; }
;     }
;     float hacc[4][4]; ZERO44(hacc);
;     mm64(B1, B3, hacc, ty, tx);
	v_pk_fma_f32 v[14:15], v[224:225], v[234:235], v[14:15] op_sel_hi:[0,1,1]
	v_pk_fma_f32 v[16:17], v[224:225], v[236:237], v[16:17] op_sel_hi:[0,1,1]
	v_pk_fma_f32 v[10:11], v[224:225], v[234:235], v[10:11] op_sel:[1,0,0]
	v_pk_fma_f32 v[12:13], v[224:225], v[236:237], v[12:13] op_sel:[1,0,0]
	v_pk_fma_f32 v[6:7], v[226:227], v[234:235], v[6:7] op_sel_hi:[0,1,1]
	v_pk_fma_f32 v[8:9], v[226:227], v[236:237], v[8:9] op_sel_hi:[0,1,1]
	v_pk_fma_f32 v[2:3], v[226:227], v[234:235], v[2:3] op_sel:[1,0,0]
	v_pk_fma_f32 v[4:5], v[226:227], v[236:237], v[4:5] op_sel:[1,0,0]
	ds_read_b128 v[224:227], v220 offset:1632
	ds_read_b128 v[234:237], v221 offset:1632
	s_waitcnt lgkmcnt(6)
	v_pk_fma_f32 v[14:15], v[238:239], v[242:243], v[14:15] op_sel_hi:[0,1,1]
	v_pk_fma_f32 v[16:17], v[238:239], v[244:245], v[16:17] op_sel_hi:[0,1,1]
	v_pk_fma_f32 v[10:11], v[238:239], v[242:243], v[10:11] op_sel:[1,0,0]
	v_pk_fma_f32 v[12:13], v[238:239], v[244:245], v[12:13] op_sel:[1,0,0]
	v_pk_fma_f32 v[6:7], v[240:241], v[242:243], v[6:7] op_sel_hi:[0,1,1]
	v_pk_fma_f32 v[8:9], v[240:241], v[244:245], v[8:9] op_sel_hi:[0,1,1]
	v_pk_fma_f32 v[2:3], v[240:241], v[242:243], v[2:3] op_sel:[1,0,0]
	v_pk_fma_f32 v[4:5], v[240:241], v[244:245], v[4:5] op_sel:[1,0,0]
	ds_read_b128 v[238:241], v220 offset:1904
	ds_read_b128 v[242:245], v221 offset:1904
	s_waitcnt lgkmcnt(6)
	v_pk_fma_f32 v[14:15], v[204:205], v[208:209], v[14:15] op_sel_hi:[0,1,1]
	v_pk_fma_f32 v[16:17], v[204:205], v[210:211], v[16:17] op_sel_hi:[0,1,1]
	v_pk_fma_f32 v[10:11], v[204:205], v[208:209], v[10:11] op_sel:[1,0,0]
	v_pk_fma_f32 v[12:13], v[204:205], v[210:211], v[12:13] op_sel:[1,0,0]
	v_pk_fma_f32 v[6:7], v[206:207], v[208:209], v[6:7] op_sel_hi:[0,1,1]
	v_pk_fma_f32 v[8:9], v[206:207], v[210:211], v[8:9] op_sel_hi:[0,1,1]
	v_pk_fma_f32 v[2:3], v[206:207], v[208:209], v[2:3] op_sel:[1,0,0]
	v_pk_fma_f32 v[4:5], v[206:207], v[210:211], v[4:5] op_sel:[1,0,0]
	s_addk_i32 s4, 0x880
	v_add_u32_e32 v220, s4, v51
	v_add_u32_e32 v221, s4, v70
	ds_read_b128 v[204:207], v220
	ds_read_b128 v[208:211], v221
	s_waitcnt lgkmcnt(6)
	v_pk_fma_f32 v[14:15], v[212:213], v[216:217], v[14:15] op_sel_hi:[0,1,1]
	v_pk_fma_f32 v[16:17], v[212:213], v[218:219], v[16:17] op_sel_hi:[0,1,1]
	v_pk_fma_f32 v[10:11], v[212:213], v[216:217], v[10:11] op_sel:[1,0,0]
	v_pk_fma_f32 v[12:13], v[212:213], v[218:219], v[12:13] op_sel:[1,0,0]
	v_pk_fma_f32 v[6:7], v[214:215], v[216:217], v[6:7] op_sel_hi:[0,1,1]
	v_pk_fma_f32 v[8:9], v[214:215], v[218:219], v[8:9] op_sel_hi:[0,1,1]
	v_pk_fma_f32 v[2:3], v[214:215], v[216:217], v[2:3] op_sel:[1,0,0]
	v_pk_fma_f32 v[4:5], v[214:215], v[218:219], v[4:5] op_sel:[1,0,0]
	ds_read_b128 v[212:215], v220 offset:272
	ds_read_b128 v[216:219], v221 offset:272
	s_waitcnt lgkmcnt(6)
	v_pk_fma_f32 v[14:15], v[224:225], v[234:235], v[14:15] op_sel_hi:[0,1,1]
	v_pk_fma_f32 v[16:17], v[224:225], v[236:237], v[16:17] op_sel_hi:[0,1,1]
	v_pk_fma_f32 v[10:11], v[224:225], v[234:235], v[10:11] op_sel:[1,0,0]
	v_pk_fma_f32 v[12:13], v[224:225], v[236:237], v[12:13] op_sel:[1,0,0]
	v_pk_fma_f32 v[6:7], v[226:227], v[234:235], v[6:7] op_sel_hi:[0,1,1]
	v_pk_fma_f32 v[8:9], v[226:227], v[236:237], v[8:9] op_sel_hi:[0,1,1]
	v_pk_fma_f32 v[2:3], v[226:227], v[234:235], v[2:3] op_sel:[1,0,0]
	v_pk_fma_f32 v[4:5], v[226:227], v[236:237], v[4:5] op_sel:[1,0,0]
	ds_read_b128 v[224:227], v220 offset:544
	ds_read_b128 v[234:237], v221 offset:544
	s_waitcnt lgkmcnt(6)
	v_pk_fma_f32 v[14:15], v[238:239], v[242:243], v[14:15] op_sel_hi:[0,1,1]
	v_pk_fma_f32 v[16:17], v[238:239], v[244:245], v[16:17] op_sel_hi:[0,1,1]
	v_pk_fma_f32 v[10:11], v[238:239], v[242:243], v[10:11] op_sel:[1,0,0]
	v_pk_fma_f32 v[12:13], v[238:239], v[244:245], v[12:13] op_sel:[1,0,0]
	v_pk_fma_f32 v[6:7], v[240:241], v[242:243], v[6:7] op_sel_hi:[0,1,1]
	v_pk_fma_f32 v[8:9], v[240:241], v[244:245], v[8:9] op_sel_hi:[0,1,1]
	v_pk_fma_f32 v[2:3], v[240:241], v[242:243], v[2:3] op_sel:[1,0,0]
	v_pk_fma_f32 v[4:5], v[240:241], v[244:245], v[4:5] op_sel:[1,0,0]
	s_cmpk_lg_i32 s4, 0x4400
	s_cbranch_scc1 .LBB0_640
	s_waitcnt lgkmcnt(0)
	s_add_u32 s4, s9, s0
	s_addc_u32 s5, s10, s1
	v_lshlrev_b32_e32 v0, 2, v50
	v_lshl_add_u64 v[20:21], s[4:5], 0, v[0:1]
	v_lshl_add_u64 v[20:21], v[18:19], 2, v[20:21]
	global_store_dwordx4 v[20:21], v[14:17], off
	global_store_dwordx4 v[20:21], v[10:13], off offset:256
	global_store_dwordx4 v[20:21], v[6:9], off offset:512
	global_store_dwordx4 v[20:21], v[2:5], off offset:768
	v_readlane_b32 s4, v253, 52
	v_mov_b32_e32 v20, 0
	v_mov_b32_e32 v21, v20
	v_add_u32_e32 v2, s4, v94
	s_mov_b32 s4, 0
	v_mov_b32_e32 v32, v20
	v_mov_b32_e32 v33, v20
	v_mov_b32_e32 v50, v20
	v_mov_b32_e32 v51, v20
	v_mov_b32_e32 v28, v20
	v_mov_b32_e32 v29, v20
	v_mov_b32_e32 v30, v20
	v_mov_b32_e32 v31, v20
	v_mov_b32_e32 v24, v20
	v_mov_b32_e32 v25, v20
	v_mov_b32_e32 v26, v20
	v_mov_b32_e32 v27, v20
	v_mov_b32_e32 v22, v20
	v_mov_b32_e32 v23, v20
	v_add_u32_e32 v220, s4, v93
	v_add_u32_e32 v221, s4, v2
	ds_read_b128 v[204:207], v220
	ds_read_b128 v[208:211], v221
	ds_read_b128 v[212:215], v220 offset:272
	ds_read_b128 v[216:219], v221 offset:272
	ds_read_b128 v[224:227], v220 offset:544
	ds_read_b128 v[234:237], v221 offset:544
; #define ZERO44(a) { _Pragma("unroll") for (int _i = 0; _i < 4; ++_i) { _Pragma("unroll") for (int _j = 0; _j < 4; ++_j) a[_i][_j] = 0.f; } }
; __device__ __forceinline__ void mm64(const float* At, const float* B, float (&acc)[4][4], int ty, int tx) {
;     ...
;     for (int k = 0; k < 64; ++k) {
;         const f32x4 a = *(const f32x4*)(At + k * DLD + 4 * ty);
;         const f32x4 b = *(const f32x4*)(B + k * DLD + 4 * tx);
;         const f32x2 b01 = {b.x, b.y}, b23 = {b.z, b.w};
; #pragma unroll
;         for (int rr = 0; rr < 4; ++rr) {
;             const f32x2 a2 = {a[rr], a[rr]};
;             c2[rr][0] = __builtin_elementwise_fma(a2, b01, c2[rr][0]);
;             c2[rr][1] = __builtin_elementwise_fma(a2, b23, c2[rr][1]);
;         }
;     }
; __device__ __forceinline__ void dn1_item(const Params& p, int l, int item, unsigned char* lds) {
;     ...
;     float hacc[4][4]; ZERO44(hacc);
;     mm64(B1, B3, hacc, ty, tx);
;     {
;         float a1[4][4]; ZERO44(a1);
;         mm64(B3, B2, a1, ty, tx);
.LBB0_642:
	ds_read_b128 v[238:241], v220 offset:816
	ds_read_b128 v[242:245], v221 offset:816
	s_waitcnt lgkmcnt(6)
	v_pk_fma_f32 v[32:33], v[204:205], v[208:209], v[32:33] op_sel_hi:[0,1,1]
	v_pk_fma_f32 v[50:51], v[204:205], v[210:211], v[50:51] op_sel_hi:[0,1,1]
	v_pk_fma_f32 v[28:29], v[204:205], v[208:209], v[28:29] op_sel:[1,0,0]
	v_pk_fma_f32 v[30:31], v[204:205], v[210:211], v[30:31] op_sel:[1,0,0]
	v_pk_fma_f32 v[24:25], v[206:207], v[208:209], v[24:25] op_sel_hi:[0,1,1]
	v_pk_fma_f32 v[26:27], v[206:207], v[210:211], v[26:27] op_sel_hi:[0,1,1]
	v_pk_fma_f32 v[22:23], v[206:207], v[208:209], v[22:23] op_sel:[1,0,0]
	v_pk_fma_f32 v[20:21], v[206:207], v[210:211], v[20:21] op_sel:[1,0,0]
	ds_read_b128 v[204:207], v220 offset:1088
	ds_read_b128 v[208:211], v221 offset:1088
	s_waitcnt lgkmcnt(6)
	v_pk_fma_f32 v[32:33], v[212:213], v[216:217], v[32:33] op_sel_hi:[0,1,1]
	v_pk_fma_f32 v[50:51], v[212:213], v[218:219], v[50:51] op_sel_hi:[0,1,1]
	v_pk_fma_f32 v[28:29], v[212:213], v[216:217], v[28:29] op_sel:[1,0,0]
	v_pk_fma_f32 v[30:31], v[212:213], v[218:219], v[30:31] op_sel:[1,0,0]
	v_pk_fma_f32 v[24:25], v[214:215], v[216:217], v[24:25] op_sel_hi:[0,1,1]
	v_pk_fma_f32 v[26:27], v[214:215], v[218:219], v[26:27] op_sel_hi:[0,1,1]
	v_pk_fma_f32 v[22:23], v[214:215], v[216:217], v[22:23] op_sel:[1,0,0]
	v_pk_fma_f32 v[20:21], v[214:215], v[218:219], v[20:21] op_sel:[1,0,0]
	ds_read_b128 v[212:215], v220 offset:1360
	ds_read_b128 v[216:219], v221 offset:1360
	s_waitcnt lgkmcnt(6)
	v_pk_fma_f32 v[32:33], v[224:225], v[234:235], v[32:33] op_sel_hi:[0,1,1]
	v_pk_fma_f32 v[50:51], v[224:225], v[236:237], v[50:51] op_sel_hi:[0,1,1]
	v_pk_fma_f32 v[28:29], v[224:225], v[234:235], v[28:29] op_sel:[1,0,0]
	v_pk_fma_f32 v[30:31], v[224:225], v[236:237], v[30:31] op_sel:[1,0,0]
	v_pk_fma_f32 v[24:25], v[226:227], v[234:235], v[24:25] op_sel_hi:[0,1,1]
	v_pk_fma_f32 v[26:27], v[226:227], v[236:237], v[26:27] op_sel_hi:[0,1,1]
	v_pk_fma_f32 v[22:23], v[226:227], v[234:235], v[22:23] op_sel:[1,0,0]
	v_pk_fma_f32 v[20:21], v[226:227], v[236:237], v[20:21] op_sel:[1,0,0]
	ds_read_b128 v[224:227], v220 offset:1632
	ds_read_b128 v[234:237], v221 offset:1632
	s_waitcnt lgkmcnt(6)
	v_pk_fma_f32 v[32:33], v[238:239], v[242:243], v[32:33] op_sel_hi:[0,1,1]
	v_pk_fma_f32 v[50:51], v[238:239], v[244:245], v[50:51] op_sel_hi:[0,1,1]
	v_pk_fma_f32 v[28:29], v[238:239], v[242:243], v[28:29] op_sel:[1,0,0]
	v_pk_fma_f32 v[30:31], v[238:239], v[244:245], v[30:31] op_sel:[1,0,0]
	v_pk_fma_f32 v[24:25], v[240:241], v[242:243], v[24:25] op_sel_hi:[0,1,1]
	v_pk_fma_f32 v[26:27], v[240:241], v[244:245], v[26:27] op_sel_hi:[0,1,1]
	v_pk_fma_f32 v[22:23], v[240:241], v[242:243], v[22:23] op_sel:[1,0,0]
	v_pk_fma_f32 v[20:21], v[240:241], v[244:245], v[20:21] op_sel:[1,0,0]
	ds_read_b128 v[238:241], v220 offset:1904
	ds_read_b128 v[242:245], v221 offset:1904
	s_waitcnt lgkmcnt(6)
	v_pk_fma_f32 v[32:33], v[204:205], v[208:209], v[32:33] op_sel_hi:[0,1,1]
	v_pk_fma_f32 v[50:51], v[204:205], v[210:211], v[50:51] op_sel_hi:[0,1,1]
	v_pk_fma_f32 v[28:29], v[204:205], v[208:209], v[28:29] op_sel:[1,0,0]
	v_pk_fma_f32 v[30:31], v[204:205], v[210:211], v[30:31] op_sel:[1,0,0]
	v_pk_fma_f32 v[24:25], v[206:207], v[208:209], v[24:25] op_sel_hi:[0,1,1]
	v_pk_fma_f32 v[26:27], v[206:207], v[210:211], v[26:27] op_sel_hi:[0,1,1]
	v_pk_fma_f32 v[22:23], v[206:207], v[208:209], v[22:23] op_sel:[1,0,0]
	v_pk_fma_f32 v[20:21], v[206:207], v[210:211], v[20:21] op_sel:[1,0,0]
	s_addk_i32 s4, 0x880
	v_add_u32_e32 v220, s4, v93
	v_add_u32_e32 v221, s4, v2
	ds_read_b128 v[204:207], v220
	ds_read_b128 v[208:211], v221
	s_waitcnt lgkmcnt(6)
	v_pk_fma_f32 v[32:33], v[212:213], v[216:217], v[32:33] op_sel_hi:[0,1,1]
	v_pk_fma_f32 v[50:51], v[212:213], v[218:219], v[50:51] op_sel_hi:[0,1,1]
	v_pk_fma_f32 v[28:29], v[212:213], v[216:217], v[28:29] op_sel:[1,0,0]
	v_pk_fma_f32 v[30:31], v[212:213], v[218:219], v[30:31] op_sel:[1,0,0]
	v_pk_fma_f32 v[24:25], v[214:215], v[216:217], v[24:25] op_sel_hi:[0,1,1]
	v_pk_fma_f32 v[26:27], v[214:215], v[218:219], v[26:27] op_sel_hi:[0,1,1]
	v_pk_fma_f32 v[22:23], v[214:215], v[216:217], v[22:23] op_sel:[1,0,0]
	v_pk_fma_f32 v[20:21], v[214:215], v[218:219], v[20:21] op_sel:[1,0,0]
	ds_read_b128 v[212:215], v220 offset:272
	ds_read_b128 v[216:219], v221 offset:272
	s_waitcnt lgkmcnt(6)
	v_pk_fma_f32 v[32:33], v[224:225], v[234:235], v[32:33] op_sel_hi:[0,1,1]
	v_pk_fma_f32 v[50:51], v[224:225], v[236:237], v[50:51] op_sel_hi:[0,1,1]
	v_pk_fma_f32 v[28:29], v[224:225], v[234:235], v[28:29] op_sel:[1,0,0]
	v_pk_fma_f32 v[30:31], v[224:225], v[236:237], v[30:31] op_sel:[1,0,0]
	v_pk_fma_f32 v[24:25], v[226:227], v[234:235], v[24:25] op_sel_hi:[0,1,1]
	v_pk_fma_f32 v[26:27], v[226:227], v[236:237], v[26:27] op_sel_hi:[0,1,1]
	v_pk_fma_f32 v[22:23], v[226:227], v[234:235], v[22:23] op_sel:[1,0,0]
	v_pk_fma_f32 v[20:21], v[226:227], v[236:237], v[20:21] op_sel:[1,0,0]
	ds_read_b128 v[224:227], v220 offset:544
	ds_read_b128 v[234:237], v221 offset:544
	s_waitcnt lgkmcnt(6)
	v_pk_fma_f32 v[32:33], v[238:239], v[242:243], v[32:33] op_sel_hi:[0,1,1]
	v_pk_fma_f32 v[50:51], v[238:239], v[244:245], v[50:51] op_sel_hi:[0,1,1]
	v_pk_fma_f32 v[28:29], v[238:239], v[242:243], v[28:29] op_sel:[1,0,0]
	v_pk_fma_f32 v[30:31], v[238:239], v[244:245], v[30:31] op_sel:[1,0,0]
	v_pk_fma_f32 v[24:25], v[240:241], v[242:243], v[24:25] op_sel_hi:[0,1,1]
	v_pk_fma_f32 v[26:27], v[240:241], v[244:245], v[26:27] op_sel_hi:[0,1,1]
	v_pk_fma_f32 v[22:23], v[240:241], v[242:243], v[22:23] op_sel:[1,0,0]
	v_pk_fma_f32 v[20:21], v[240:241], v[244:245], v[20:21] op_sel:[1,0,0]
	s_cmpk_lg_i32 s4, 0x4400
	s_cbranch_scc1 .LBB0_642
	s_waitcnt lgkmcnt(0)
	v_readlane_b32 s4, v253, 52
	v_mov_b32_e32 v4, 0
	v_mov_b32_e32 v5, v4
	v_add_u32_e32 v54, s4, v77
	s_mov_b32 s4, 0
	v_mov_b32_e32 v14, v4
	v_mov_b32_e32 v15, v4
	v_mov_b32_e32 v16, v4
	v_mov_b32_e32 v17, v4
	v_mov_b32_e32 v10, v4
	v_mov_b32_e32 v11, v4
	v_mov_b32_e32 v12, v4
	v_mov_b32_e32 v13, v4
	v_mov_b32_e32 v6, v4
	v_mov_b32_e32 v7, v4
	v_mov_b32_e32 v8, v4
	v_mov_b32_e32 v9, v4
	v_mov_b32_e32 v2, v4
	v_mov_b32_e32 v3, v4
	v_add_u32_e32 v220, s4, v54
	v_add_u32_e32 v221, s4, v70
	ds_read_b128 v[204:207], v220
	ds_read_b128 v[208:211], v221
	ds_read_b128 v[212:215], v220 offset:272
	ds_read_b128 v[216:219], v221 offset:272
	ds_read_b128 v[224:227], v220 offset:544
	ds_read_b128 v[234:237], v221 offset:544
; #define ZERO44(a) { _Pragma("unroll") for (int _i = 0; _i < 4; ++_i) { _Pragma("unroll") for (int _j = 0; _j < 4; ++_j) a[_i][_j] = 0.f; } }
; __device__ __forceinline__ void mm64(const float* At, const float* B, float (&acc)[4][4], int ty, int tx) {
;     ...
;     for (int k = 0; k < 64; ++k) {
;         const f32x4 a = *(const f32x4*)(At + k * DLD + 4 * ty);
;         const f32x4 b = *(const f32x4*)(B + k * DLD + 4 * tx);
;         const f32x2 b01 = {b.x, b.y}, b23 = {b.z, b.w};
; #pragma unroll
;         for (int rr = 0; rr < 4; ++rr) {
;             const f32x2 a2 = {a[rr], a[rr]};
;             c2[rr][0] = __builtin_elementwise_fma(a2, b01, c2[rr][0]);
;             c2[rr][1] = __builtin_elementwise_fma(a2, b23, c2[rr][1]);
;         }
;     }
; __device__ __forceinline__ void dn1_item(const Params& p, int l, int item, unsigned char* lds) {
;     ...
;         float a1[4][4]; ZERO44(a1);
;         mm64(B3, B2, a1, ty, tx);
.LBB0_644:
	ds_read_b128 v[238:241], v220 offset:816
	ds_read_b128 v[242:245], v221 offset:816
	s_waitcnt lgkmcnt(6)
	v_pk_fma_f32 v[14:15], v[204:205], v[208:209], v[14:15] op_sel_hi:[0,1,1]
	v_pk_fma_f32 v[16:17], v[204:205], v[210:211], v[16:17] op_sel_hi:[0,1,1]
	v_pk_fma_f32 v[10:11], v[204:205], v[208:209], v[10:11] op_sel:[1,0,0]
	v_pk_fma_f32 v[12:13], v[204:205], v[210:211], v[12:13] op_sel:[1,0,0]
	v_pk_fma_f32 v[6:7], v[206:207], v[208:209], v[6:7] op_sel_hi:[0,1,1]
	v_pk_fma_f32 v[8:9], v[206:207], v[210:211], v[8:9] op_sel_hi:[0,1,1]
	v_pk_fma_f32 v[2:3], v[206:207], v[208:209], v[2:3] op_sel:[1,0,0]
	v_pk_fma_f32 v[4:5], v[206:207], v[210:211], v[4:5] op_sel:[1,0,0]
	ds_read_b128 v[204:207], v220 offset:1088
	ds_read_b128 v[208:211], v221 offset:1088
	s_waitcnt lgkmcnt(6)
	v_pk_fma_f32 v[14:15], v[212:213], v[216:217], v[14:15] op_sel_hi:[0,1,1]
	v_pk_fma_f32 v[16:17], v[212:213], v[218:219], v[16:17] op_sel_hi:[0,1,1]
	v_pk_fma_f32 v[10:11], v[212:213], v[216:217], v[10:11] op_sel:[1,0,0]
	v_pk_fma_f32 v[12:13], v[212:213], v[218:219], v[12:13] op_sel:[1,0,0]
	v_pk_fma_f32 v[6:7], v[214:215], v[216:217], v[6:7] op_sel_hi:[0,1,1]
	v_pk_fma_f32 v[8:9], v[214:215], v[218:219], v[8:9] op_sel_hi:[0,1,1]
	v_pk_fma_f32 v[2:3], v[214:215], v[216:217], v[2:3] op_sel:[1,0,0]
	v_pk_fma_f32 v[4:5], v[214:215], v[218:219], v[4:5] op_sel:[1,0,0]
	ds_read_b128 v[212:215], v220 offset:1360
	ds_read_b128 v[216:219], v221 offset:1360
	s_waitcnt lgkmcnt(6)
	v_pk_fma_f32 v[14:15], v[224:225], v[234:235], v[14:15] op_sel_hi:[0,1,1]
	v_pk_fma_f32 v[16:17], v[224:225], v[236:237], v[16:17] op_sel_hi:[0,1,1]
	v_pk_fma_f32 v[10:11], v[224:225], v[234:235], v[10:11] op_sel:[1,0,0]
	v_pk_fma_f32 v[12:13], v[224:225], v[236:237], v[12:13] op_sel:[1,0,0]
	v_pk_fma_f32 v[6:7], v[226:227], v[234:235], v[6:7] op_sel_hi:[0,1,1]
	v_pk_fma_f32 v[8:9], v[226:227], v[236:237], v[8:9] op_sel_hi:[0,1,1]
	v_pk_fma_f32 v[2:3], v[226:227], v[234:235], v[2:3] op_sel:[1,0,0]
	v_pk_fma_f32 v[4:5], v[226:227], v[236:237], v[4:5] op_sel:[1,0,0]
	ds_read_b128 v[224:227], v220 offset:1632
	ds_read_b128 v[234:237], v221 offset:1632
	s_waitcnt lgkmcnt(6)
	v_pk_fma_f32 v[14:15], v[238:239], v[242:243], v[14:15] op_sel_hi:[0,1,1]
	v_pk_fma_f32 v[16:17], v[238:239], v[244:245], v[16:17] op_sel_hi:[0,1,1]
	v_pk_fma_f32 v[10:11], v[238:239], v[242:243], v[10:11] op_sel:[1,0,0]
	v_pk_fma_f32 v[12:13], v[238:239], v[244:245], v[12:13] op_sel:[1,0,0]
	v_pk_fma_f32 v[6:7], v[240:241], v[242:243], v[6:7] op_sel_hi:[0,1,1]
	v_pk_fma_f32 v[8:9], v[240:241], v[244:245], v[8:9] op_sel_hi:[0,1,1]
	v_pk_fma_f32 v[2:3], v[240:241], v[242:243], v[2:3] op_sel:[1,0,0]
	v_pk_fma_f32 v[4:5], v[240:241], v[244:245], v[4:5] op_sel:[1,0,0]
	ds_read_b128 v[238:241], v220 offset:1904
	ds_read_b128 v[242:245], v221 offset:1904
	s_waitcnt lgkmcnt(6)
	v_pk_fma_f32 v[14:15], v[204:205], v[208:209], v[14:15] op_sel_hi:[0,1,1]
	v_pk_fma_f32 v[16:17], v[204:205], v[210:211], v[16:17] op_sel_hi:[0,1,1]
	v_pk_fma_f32 v[10:11], v[204:205], v[208:209], v[10:11] op_sel:[1,0,0]
	v_pk_fma_f32 v[12:13], v[204:205], v[210:211], v[12:13] op_sel:[1,0,0]
	v_pk_fma_f32 v[6:7], v[206:207], v[208:209], v[6:7] op_sel_hi:[0,1,1]
	v_pk_fma_f32 v[8:9], v[206:207], v[210:211], v[8:9] op_sel_hi:[0,1,1]
	v_pk_fma_f32 v[2:3], v[206:207], v[208:209], v[2:3] op_sel:[1,0,0]
	v_pk_fma_f32 v[4:5], v[206:207], v[210:211], v[4:5] op_sel:[1,0,0]
	s_addk_i32 s4, 0x880
	v_add_u32_e32 v220, s4, v54
	v_add_u32_e32 v221, s4, v70
	ds_read_b128 v[204:207], v220
	ds_read_b128 v[208:211], v221
	s_waitcnt lgkmcnt(6)
	v_pk_fma_f32 v[14:15], v[212:213], v[216:217], v[14:15] op_sel_hi:[0,1,1]
	v_pk_fma_f32 v[16:17], v[212:213], v[218:219], v[16:17] op_sel_hi:[0,1,1]
	v_pk_fma_f32 v[10:11], v[212:213], v[216:217], v[10:11] op_sel:[1,0,0]
	v_pk_fma_f32 v[12:13], v[212:213], v[218:219], v[12:13] op_sel:[1,0,0]
	v_pk_fma_f32 v[6:7], v[214:215], v[216:217], v[6:7] op_sel_hi:[0,1,1]
	v_pk_fma_f32 v[8:9], v[214:215], v[218:219], v[8:9] op_sel_hi:[0,1,1]
	v_pk_fma_f32 v[2:3], v[214:215], v[216:217], v[2:3] op_sel:[1,0,0]
	v_pk_fma_f32 v[4:5], v[214:215], v[218:219], v[4:5] op_sel:[1,0,0]
	ds_read_b128 v[212:215], v220 offset:272
	ds_read_b128 v[216:219], v221 offset:272
	s_waitcnt lgkmcnt(6)
	v_pk_fma_f32 v[14:15], v[224:225], v[234:235], v[14:15] op_sel_hi:[0,1,1]
	v_pk_fma_f32 v[16:17], v[224:225], v[236:237], v[16:17] op_sel_hi:[0,1,1]
	v_pk_fma_f32 v[10:11], v[224:225], v[234:235], v[10:11] op_sel:[1,0,0]
	v_pk_fma_f32 v[12:13], v[224:225], v[236:237], v[12:13] op_sel:[1,0,0]
	v_pk_fma_f32 v[6:7], v[226:227], v[234:235], v[6:7] op_sel_hi:[0,1,1]
	v_pk_fma_f32 v[8:9], v[226:227], v[236:237], v[8:9] op_sel_hi:[0,1,1]
	v_pk_fma_f32 v[2:3], v[226:227], v[234:235], v[2:3] op_sel:[1,0,0]
	v_pk_fma_f32 v[4:5], v[226:227], v[236:237], v[4:5] op_sel:[1,0,0]
	ds_read_b128 v[224:227], v220 offset:544
	ds_read_b128 v[234:237], v221 offset:544
	s_waitcnt lgkmcnt(6)
	v_pk_fma_f32 v[14:15], v[238:239], v[242:243], v[14:15] op_sel_hi:[0,1,1]
	v_pk_fma_f32 v[16:17], v[238:239], v[244:245], v[16:17] op_sel_hi:[0,1,1]
	v_pk_fma_f32 v[10:11], v[238:239], v[242:243], v[10:11] op_sel:[1,0,0]
	v_pk_fma_f32 v[12:13], v[238:239], v[244:245], v[12:13] op_sel:[1,0,0]
	v_pk_fma_f32 v[6:7], v[240:241], v[242:243], v[6:7] op_sel_hi:[0,1,1]
	v_pk_fma_f32 v[8:9], v[240:241], v[244:245], v[8:9] op_sel_hi:[0,1,1]
	v_pk_fma_f32 v[2:3], v[240:241], v[242:243], v[2:3] op_sel:[1,0,0]
	v_pk_fma_f32 v[4:5], v[240:241], v[244:245], v[4:5] op_sel:[1,0,0]
	s_cmpk_lg_i32 s4, 0x4400
	s_cbranch_scc1 .LBB0_644
; __device__ __forceinline__ void dn1_item(const Params& p, int l, int item, unsigned char* lds) {
;     ...
;         mm64(B3, B2, a1, ty, tx);
; #pragma unroll
;         for (int rr = 0; rr < 4; ++rr) { f32x4 w = {a1[rr][0], a1[rr][1], a1[rr][2], a1[rr][3]}; *(f32x4*)(DNO + (4 * ty + rr) * 64 + 4 * tx) = w; }
;     }
;     __syncthreads();
;     {
;         const float s = __expf(gci);
; #pragma unroll
;         for (int e = 0; e < 16; e += 4) { f32x4 w = {qn[e] * s, qn[e + 1] * s, qn[e + 2] * s, qn[e + 3] * s}; *(f32x4*)(B0 + i * DLD + d0 + e) = w; }
;     }
;     __syncthreads();
; #pragma unroll
;     for (int rr = 0; rr < 4; ++rr) {
;         f32x4 w;
; #pragma unroll
;         for (int cc = 0; cc < 4; ++cc) w[cc] = B0[(4 * tx + cc) * DLD + 4 * ty + rr] - hacc[rr][cc];
;         *(f32x4*)(DNQ + (4 * ty + rr) * 64 + 4 * tx) = w;
;     }
	s_waitcnt lgkmcnt(0)
	s_add_u32 s4, s12, s0
	s_addc_u32 s5, s13, s1
	v_lshl_add_u64 v[54:55], s[4:5], 0, v[0:1]
	v_lshlrev_b64 v[18:19], 2, v[18:19]
	v_lshl_add_u64 v[54:55], v[54:55], 0, v[18:19]
	global_store_dwordx4 v[54:55], v[14:17], off
	global_store_dwordx4 v[54:55], v[10:13], off offset:256
	global_store_dwordx4 v[54:55], v[6:9], off offset:512
	global_store_dwordx4 v[54:55], v[2:5], off offset:768
	s_barrier
	s_nop 0
	v_pk_mul_f32 v[4:5], v[48:49], v[52:53] op_sel_hi:[1,0]
	v_pk_mul_f32 v[2:3], v[44:45], v[52:53] op_sel_hi:[1,0]
	ds_write_b128 v53, v[2:5]
	v_pk_mul_f32 v[4:5], v[46:47], v[52:53] op_sel_hi:[1,0]
	v_pk_mul_f32 v[2:3], v[40:41], v[52:53] op_sel_hi:[1,0]
	ds_write_b128 v53, v[2:5] offset:16
	v_pk_mul_f32 v[4:5], v[42:43], v[52:53] op_sel_hi:[1,0]
	v_pk_mul_f32 v[2:3], v[36:37], v[52:53] op_sel_hi:[1,0]
	ds_write_b128 v53, v[2:5] offset:32
	v_pk_mul_f32 v[4:5], v[38:39], v[52:53] op_sel_hi:[1,0]
	v_pk_mul_f32 v[2:3], v[34:35], v[52:53] op_sel_hi:[1,0]
	ds_write_b128 v53, v[2:5] offset:48
	s_waitcnt lgkmcnt(0)
	s_barrier
	ds_read_b128 v[2:5], v102
	ds_read_b128 v[6:9], v102 offset:272
	ds_read_b128 v[10:13], v102 offset:544
	ds_read_b128 v[14:17], v102 offset:816
	s_add_u32 s0, s14, s0
	s_addc_u32 s1, s15, s1
	s_waitcnt lgkmcnt(2)
	v_mov_b32_e32 v35, v6
	v_mov_b32_e32 v6, v3
	v_lshl_add_u64 v[36:37], s[0:1], 0, v[0:1]
	v_mov_b32_e32 v34, v2
	s_waitcnt lgkmcnt(1)
	v_mov_b32_e32 v38, v10
	s_waitcnt lgkmcnt(0)
	v_mov_b32_e32 v39, v14
	v_mov_b32_e32 v14, v11
	v_pk_add_f32 v[28:29], v[6:7], v[28:29] neg_lo:[0,1] neg_hi:[0,1]
	v_mov_b32_e32 v2, v4
	v_mov_b32_e32 v3, v8
	v_mov_b32_e32 v6, v12
	v_mov_b32_e32 v7, v16
	v_mov_b32_e32 v8, v5
	v_mov_b32_e32 v16, v13
	v_pk_add_f32 v[32:33], v[34:35], v[32:33] neg_lo:[0,1] neg_hi:[0,1]
	v_pk_add_f32 v[34:35], v[38:39], v[50:51] neg_lo:[0,1] neg_hi:[0,1]
	v_lshl_add_u64 v[18:19], v[36:37], 0, v[18:19]
	v_pk_add_f32 v[30:31], v[14:15], v[30:31] neg_lo:[0,1] neg_hi:[0,1]
	v_pk_add_f32 v[24:25], v[2:3], v[24:25] neg_lo:[0,1] neg_hi:[0,1]
	v_pk_add_f32 v[26:27], v[6:7], v[26:27] neg_lo:[0,1] neg_hi:[0,1]
	v_pk_add_f32 v[2:3], v[8:9], v[22:23] neg_lo:[0,1] neg_hi:[0,1]
	v_pk_add_f32 v[4:5], v[16:17], v[20:21] neg_lo:[0,1] neg_hi:[0,1]
	global_store_dwordx4 v[18:19], v[32:35], off
	global_store_dwordx4 v[18:19], v[28:31], off offset:256
	global_store_dwordx4 v[18:19], v[24:27], off offset:512
	global_store_dwordx4 v[18:19], v[2:5], off offset:768
	s_barrier
	s_mov_b64 s[0:1], 0

; __device__ __forceinline__ void lds_barrier() { asm volatile("s_waitcnt lgkmcnt(0)\n\ts_barrier" ::: "memory"); }
; __device__ __forceinline__ f32x16 mfma32(bf16x8 a, bf16x8 b, f32x16 c) { return __builtin_amdgcn_mfma_f32_32x32x16_bf16(a, b, c, 0, 0, 0); }
; __device__ __forceinline__ void gemm_big(const bf16_t* __restrict__ A, long lda, const bf16_t* __restrict__ Bt, int K, f32x16 (&acc)[2][4], unsigned char* lds) {
;     ...
;     for (int kc = 0; kc < nk; ++kc) {
;         bf16x8 af[2][2], bfr[2][4];
;         af[0][0] = *(const bf16x8*)(Ac); af[0][1] = *(const bf16x8*)(Ac + 32 * GLD);
; #pragma unroll
;         for (int ni = 0; ni < 4; ++ni) bfr[0][ni] = *(const bf16x8*)(Bc + ni * 32 * GLD);
;         __builtin_amdgcn_s_setprio(3);
; #pragma unroll
;         for (int ks = 0; ks < 4; ++ks) {
;             const int cb = ks & 1, nb = cb ^ 1;
;             if (ks < 3) {
;                 af[nb][0] = *(const bf16x8*)(Ac + (ks + 1) * 16); af[nb][1] = *(const bf16x8*)(Ac + 32 * GLD + (ks + 1) * 16);
; #pragma unroll
;                 for (int ni = 0; ni < 4; ++ni) bfr[nb][ni] = *(const bf16x8*)(Bc + ni * 32 * GLD + (ks + 1) * 16);
;             }
;             __builtin_amdgcn_sched_barrier(0);
; #pragma unroll
;             for (int ni = 0; ni < 4; ++ni) { acc[0][ni] = mfma32(af[cb][0], bfr[cb][ni], acc[0][ni]); acc[1][ni] = mfma32(af[cb][1], bfr[cb][ni], acc[1][ni]); }
;             __builtin_amdgcn_sched_barrier(0);
;         }
;         __builtin_amdgcn_s_setprio(0);
;         lds_barrier();
;         if (kc + 1 < nk) {
;             lstore();
;             if (kc + 2 < nk) gload(kc + 2);
;             lds_barrier();
;         }
.LBB0_678:
	s_cmp_gt_u32 s6, 14
	s_cbranch_scc1 .Lmy_gorig_2
	ds_read_b128 v[192:195], v189
	ds_read_b128 v[196:199], v189 offset:4608
	ds_read_b128 v[200:203], v190 offset:18432
	ds_read_b128 v[204:207], v190 offset:23040
	ds_read_b128 v[208:211], v190 offset:27648
	ds_read_b128 v[212:215], v190 offset:32256
	s_setprio 3
	ds_read_b128 v[216:219], v189 offset:32
	ds_read_b128 v[234:237], v189 offset:4640
	ds_read_b128 v[238:241], v190 offset:18464
	ds_read_b128 v[242:245], v190 offset:23072
	ds_read_b128 v[246:249], v190 offset:27680
	ds_read_b128 v[224:227], v190 offset:32288
	s_waitcnt lgkmcnt(9)
	v_mfma_f32_32x32x16_bf16 v[114:129], v[192:195], v[200:203], v[114:129]
	v_mfma_f32_32x32x16_bf16 v[98:113], v[196:199], v[200:203], v[98:113]
	s_waitcnt lgkmcnt(8)
	v_mfma_f32_32x32x16_bf16 v[82:97], v[192:195], v[204:207], v[82:97]
	v_mfma_f32_32x32x16_bf16 v[66:81], v[196:199], v[204:207], v[66:81]
	s_waitcnt lgkmcnt(7)
	v_mfma_f32_32x32x16_bf16 v[50:65], v[192:195], v[208:211], v[50:65]
	v_mfma_f32_32x32x16_bf16 v[34:49], v[196:199], v[208:211], v[34:49]
	s_waitcnt lgkmcnt(6)
	v_mfma_f32_32x32x16_bf16 v[18:33], v[192:195], v[212:215], v[18:33]
	v_mfma_f32_32x32x16_bf16 v[2:17], v[196:199], v[212:215], v[2:17]
	ds_read_b128 v[192:195], v189 offset:64
	ds_read_b128 v[196:199], v189 offset:4672
	ds_read_b128 v[200:203], v190 offset:18496
	ds_read_b128 v[204:207], v190 offset:23104
	ds_read_b128 v[208:211], v190 offset:27712
	ds_read_b128 v[212:215], v190 offset:32320
	s_waitcnt lgkmcnt(9)
	v_mfma_f32_32x32x16_bf16 v[114:129], v[216:219], v[238:241], v[114:129]
	v_mfma_f32_32x32x16_bf16 v[98:113], v[234:237], v[238:241], v[98:113]
	s_waitcnt lgkmcnt(8)
	v_mfma_f32_32x32x16_bf16 v[82:97], v[216:219], v[242:245], v[82:97]
	v_mfma_f32_32x32x16_bf16 v[66:81], v[234:237], v[242:245], v[66:81]
	s_waitcnt lgkmcnt(7)
	v_mfma_f32_32x32x16_bf16 v[50:65], v[216:219], v[246:249], v[50:65]
	v_mfma_f32_32x32x16_bf16 v[34:49], v[234:237], v[246:249], v[34:49]
	s_waitcnt lgkmcnt(6)
	v_mfma_f32_32x32x16_bf16 v[18:33], v[216:219], v[224:227], v[18:33]
	v_mfma_f32_32x32x16_bf16 v[2:17], v[234:237], v[224:227], v[2:17]
	ds_read_b128 v[216:219], v189 offset:96
	ds_read_b128 v[224:227], v189 offset:4704
	ds_read_b128 v[234:237], v190 offset:18528
	ds_read_b128 v[238:241], v190 offset:23136
	ds_read_b128 v[242:245], v190 offset:27744
	ds_read_b128 v[246:249], v190 offset:32352
	s_waitcnt lgkmcnt(9)
	v_mfma_f32_32x32x16_bf16 v[114:129], v[192:195], v[200:203], v[114:129]
	v_mfma_f32_32x32x16_bf16 v[98:113], v[196:199], v[200:203], v[98:113]
	s_waitcnt lgkmcnt(8)
	v_mfma_f32_32x32x16_bf16 v[82:97], v[192:195], v[204:207], v[82:97]
	v_mfma_f32_32x32x16_bf16 v[66:81], v[196:199], v[204:207], v[66:81]
	s_waitcnt lgkmcnt(0)
	s_barrier
	s_cmpk_eq_i32 s0, 0x700
	s_cbranch_scc1 .Lmy_gB_2
	v_mfma_f32_32x32x16_bf16 v[50:65], v[192:195], v[208:211], v[50:65]
	s_waitcnt vmcnt(9)
	ds_write_b128 v188, v[130:133]
	v_mfma_f32_32x32x16_bf16 v[34:49], v[196:199], v[208:211], v[34:49]
	ds_write_b128 v188, v[134:137] offset:4608
	v_mfma_f32_32x32x16_bf16 v[18:33], v[192:195], v[212:215], v[18:33]
	ds_write_b128 v188, v[138:141] offset:9216
	s_add_u32 vcc_lo, s0, 0x38a8000
	s_addc_u32 vcc_hi, s1, 0
	s_nop 0
	v_lshl_add_u64 v[130:131], v[184:185], 0, vcc
	global_load_dwordx4 v[130:133], v[130:131], off offset:256
	v_mfma_f32_32x32x16_bf16 v[2:17], v[196:199], v[212:215], v[2:17]
	s_waitcnt vmcnt(8)
	ds_write_b128 v188, v[142:145] offset:13824
	s_add_u32 vcc_lo, s0, 0x38b8000
	s_addc_u32 vcc_hi, s1, 0
	s_nop 0
	v_lshl_add_u64 v[134:135], v[184:185], 0, vcc
	global_load_dwordx4 v[134:137], v[134:135], off offset:256
	v_mfma_f32_32x32x16_bf16 v[114:129], v[216:219], v[234:237], v[114:129]
	ds_write_b128 v188, v[146:149] offset:18432
	s_add_u32 vcc_lo, s0, 0x38c8000
	s_addc_u32 vcc_hi, s1, 0
	s_nop 0
	v_lshl_add_u64 v[138:139], v[184:185], 0, vcc
	global_load_dwordx4 v[138:141], v[138:139], off offset:256
	v_mfma_f32_32x32x16_bf16 v[98:113], v[224:227], v[234:237], v[98:113]
	s_waitcnt vmcnt(9)
	ds_write_b128 v188, v[150:153] offset:23040
	s_add_u32 vcc_lo, s0, 0x38d8000
	s_addc_u32 vcc_hi, s1, 0
	s_nop 0
	v_lshl_add_u64 v[142:143], v[184:185], 0, vcc
	global_load_dwordx4 v[142:145], v[142:143], off offset:256
	v_mfma_f32_32x32x16_bf16 v[82:97], v[216:219], v[238:241], v[82:97]
	s_waitcnt vmcnt(9)
	ds_write_b128 v188, v[154:157] offset:27648
	s_add_u32 vcc_lo, s0, 0x1488000
	s_addc_u32 vcc_hi, s1, 0
	s_nop 0
	v_lshl_add_u64 v[146:147], v[182:183], 0, vcc
	global_load_dwordx4 v[146:149], v[146:147], off offset:256
	v_mfma_f32_32x32x16_bf16 v[66:81], v[224:227], v[238:241], v[66:81]
	s_waitcnt vmcnt(9)
	ds_write_b128 v188, v[158:161] offset:32256
	s_add_u32 vcc_lo, s0, 0x1498000
	s_addc_u32 vcc_hi, s1, 0
	s_nop 0
	v_lshl_add_u64 v[150:151], v[182:183], 0, vcc
	global_load_dwordx4 v[150:153], v[150:151], off offset:256
	v_mfma_f32_32x32x16_bf16 v[50:65], v[216:219], v[242:245], v[50:65]
	s_waitcnt vmcnt(9)
	ds_write_b128 v188, v[162:165] offset:36864
	s_add_u32 vcc_lo, s0, 0x14a8000
	s_addc_u32 vcc_hi, s1, 0
	s_nop 0
	v_lshl_add_u64 v[154:155], v[182:183], 0, vcc
	global_load_dwordx4 v[154:157], v[154:155], off offset:256
	v_mfma_f32_32x32x16_bf16 v[34:49], v[224:227], v[242:245], v[34:49]
	s_waitcnt vmcnt(9)
	ds_write_b128 v188, v[166:169] offset:41472
	s_add_u32 vcc_lo, s0, 0x14b8000
	s_addc_u32 vcc_hi, s1, 0
	s_nop 0
	v_lshl_add_u64 v[158:159], v[182:183], 0, vcc
	global_load_dwordx4 v[158:161], v[158:159], off offset:256
	v_mfma_f32_32x32x16_bf16 v[18:33], v[216:219], v[246:249], v[18:33]
	s_waitcnt vmcnt(9)
	ds_write_b128 v188, v[170:173] offset:46080
	s_add_u32 vcc_lo, s0, 0x14c8000
	s_addc_u32 vcc_hi, s1, 0
	s_nop 0
	v_lshl_add_u64 v[162:163], v[182:183], 0, vcc
	global_load_dwordx4 v[162:165], v[162:163], off offset:256
	v_mfma_f32_32x32x16_bf16 v[2:17], v[224:227], v[246:249], v[2:17]
	s_waitcnt vmcnt(9)
	ds_write_b128 v188, v[174:177] offset:50688
	s_add_u32 vcc_lo, s0, 0x14d8000
	s_addc_u32 vcc_hi, s1, 0
	s_nop 0
	v_lshl_add_u64 v[166:167], v[182:183], 0, vcc
	global_load_dwordx4 v[166:169], v[166:167], off offset:256
	s_add_u32 vcc_lo, s0, 0x14e8000
	s_addc_u32 vcc_hi, s1, 0
	s_nop 0
	v_lshl_add_u64 v[170:171], v[182:183], 0, vcc
	global_load_dwordx4 v[170:173], v[170:171], off offset:256
	s_add_u32 vcc_lo, s0, 0x14f8000
	s_addc_u32 vcc_hi, s1, 0
	s_nop 0
	v_lshl_add_u64 v[174:175], v[182:183], 0, vcc
	global_load_dwordx4 v[174:177], v[174:175], off offset:256
	s_setprio 0
	s_branch .LBB0_676
; __device__ __forceinline__ void lds_barrier() { asm volatile("s_waitcnt lgkmcnt(0)\n\ts_barrier" ::: "memory"); }
; __device__ __forceinline__ f32x16 mfma32(bf16x8 a, bf16x8 b, f32x16 c) { return __builtin_amdgcn_mfma_f32_32x32x16_bf16(a, b, c, 0, 0, 0); }
; __device__ __forceinline__ void gemm_big(const bf16_t* __restrict__ A, long lda, const bf16_t* __restrict__ Bt, int K, f32x16 (&acc)[2][4], unsigned char* lds) {
;     ...
;             if (ks < 3) {
;                 af[nb][0] = *(const bf16x8*)(Ac + (ks + 1) * 16); af[nb][1] = *(const bf16x8*)(Ac + 32 * GLD + (ks + 1) * 16);
; #pragma unroll
;                 for (int ni = 0; ni < 4; ++ni) bfr[nb][ni] = *(const bf16x8*)(Bc + ni * 32 * GLD + (ks + 1) * 16);
;             }
;             __builtin_amdgcn_sched_barrier(0);
; #pragma unroll
;             for (int ni = 0; ni < 4; ++ni) { acc[0][ni] = mfma32(af[cb][0], bfr[cb][ni], acc[0][ni]); acc[1][ni] = mfma32(af[cb][1], bfr[cb][ni], acc[1][ni]); }
;             __builtin_amdgcn_sched_barrier(0);
;         }
;         __builtin_amdgcn_s_setprio(0);
;         lds_barrier();
;         if (kc + 1 < nk) {
;             lstore();
;             if (kc + 2 < nk) gload(kc + 2);
;             lds_barrier();
;         }
.Lmy_gB_2:
	v_mfma_f32_32x32x16_bf16 v[50:65], v[192:195], v[208:211], v[50:65]
	s_waitcnt vmcnt(9)
	ds_write_b128 v188, v[130:133]
	v_mfma_f32_32x32x16_bf16 v[34:49], v[196:199], v[208:211], v[34:49]
	ds_write_b128 v188, v[134:137] offset:4608
	v_mfma_f32_32x32x16_bf16 v[18:33], v[192:195], v[212:215], v[18:33]
	ds_write_b128 v188, v[138:141] offset:9216
	v_mfma_f32_32x32x16_bf16 v[2:17], v[196:199], v[212:215], v[2:17]
	s_waitcnt vmcnt(7)
	ds_write_b128 v188, v[142:145] offset:13824
	v_mfma_f32_32x32x16_bf16 v[114:129], v[216:219], v[234:237], v[114:129]
	ds_write_b128 v188, v[146:149] offset:18432
	v_mfma_f32_32x32x16_bf16 v[98:113], v[224:227], v[234:237], v[98:113]
	s_waitcnt vmcnt(6)
	ds_write_b128 v188, v[150:153] offset:23040
	v_mfma_f32_32x32x16_bf16 v[82:97], v[216:219], v[238:241], v[82:97]
	s_waitcnt vmcnt(5)
	ds_write_b128 v188, v[154:157] offset:27648
	v_mfma_f32_32x32x16_bf16 v[66:81], v[224:227], v[238:241], v[66:81]
	s_waitcnt vmcnt(4)
	ds_write_b128 v188, v[158:161] offset:32256
	v_mfma_f32_32x32x16_bf16 v[50:65], v[216:219], v[242:245], v[50:65]
	s_waitcnt vmcnt(3)
	ds_write_b128 v188, v[162:165] offset:36864
	v_mfma_f32_32x32x16_bf16 v[34:49], v[224:227], v[242:245], v[34:49]
	s_waitcnt vmcnt(2)
	ds_write_b128 v188, v[166:169] offset:41472
	v_mfma_f32_32x32x16_bf16 v[18:33], v[216:219], v[246:249], v[18:33]
	s_waitcnt vmcnt(1)
	ds_write_b128 v188, v[170:173] offset:46080
	v_mfma_f32_32x32x16_bf16 v[2:17], v[224:227], v[246:249], v[2:17]
	s_waitcnt vmcnt(0)
	ds_write_b128 v188, v[174:177] offset:50688
	s_setprio 0
	s_branch .LBB0_676

; __device__ __forceinline__ void lds_barrier() { asm volatile("s_waitcnt lgkmcnt(0)\n\ts_barrier" ::: "memory"); }
; __device__ __forceinline__ f32x16 mfma32(bf16x8 a, bf16x8 b, f32x16 c) { return __builtin_amdgcn_mfma_f32_32x32x16_bf16(a, b, c, 0, 0, 0); }
; __device__ __forceinline__ void gemm_big(const bf16_t* __restrict__ A, long lda, const bf16_t* __restrict__ Bt, int K, f32x16 (&acc)[2][4], unsigned char* lds) {
;     ...
;     for (int kc = 0; kc < nk; ++kc) {
;         bf16x8 af[2][2], bfr[2][4];
;         af[0][0] = *(const bf16x8*)(Ac); af[0][1] = *(const bf16x8*)(Ac + 32 * GLD);
; #pragma unroll
;         for (int ni = 0; ni < 4; ++ni) bfr[0][ni] = *(const bf16x8*)(Bc + ni * 32 * GLD);
;         __builtin_amdgcn_s_setprio(3);
; #pragma unroll
;         for (int ks = 0; ks < 4; ++ks) {
;             const int cb = ks & 1, nb = cb ^ 1;
;             if (ks < 3) {
;                 af[nb][0] = *(const bf16x8*)(Ac + (ks + 1) * 16); af[nb][1] = *(const bf16x8*)(Ac + 32 * GLD + (ks + 1) * 16);
; #pragma unroll
;                 for (int ni = 0; ni < 4; ++ni) bfr[nb][ni] = *(const bf16x8*)(Bc + ni * 32 * GLD + (ks + 1) * 16);
;             }
;             __builtin_amdgcn_sched_barrier(0);
; #pragma unroll
;             for (int ni = 0; ni < 4; ++ni) { acc[0][ni] = mfma32(af[cb][0], bfr[cb][ni], acc[0][ni]); acc[1][ni] = mfma32(af[cb][1], bfr[cb][ni], acc[1][ni]); }
;             __builtin_amdgcn_sched_barrier(0);
;         }
;         __builtin_amdgcn_s_setprio(0);
;         lds_barrier();
;         if (kc + 1 < nk) {
;             lstore();
;             if (kc + 2 < nk) gload(kc + 2);
;             lds_barrier();
;         }
.LBB0_775:
	s_cmp_gt_u32 s14, 42
	s_cbranch_scc1 .Lmy_gorig_1
	ds_read_b128 v[190:193], v187
	ds_read_b128 v[194:197], v187 offset:4608
	ds_read_b128 v[198:201], v188 offset:18432
	ds_read_b128 v[202:205], v188 offset:23040
	ds_read_b128 v[206:209], v188 offset:27648
	ds_read_b128 v[210:213], v188 offset:32256
	s_setprio 3
	ds_read_b128 v[214:217], v187 offset:32
	ds_read_b128 v[218:221], v187 offset:4640
	ds_read_b128 v[234:237], v188 offset:18464
	ds_read_b128 v[238:241], v188 offset:23072
	ds_read_b128 v[242:245], v188 offset:27680
	ds_read_b128 v[246:249], v188 offset:32288
	s_waitcnt lgkmcnt(9)
	v_mfma_f32_32x32x16_bf16 v[114:129], v[190:193], v[198:201], v[114:129]
	v_mfma_f32_32x32x16_bf16 v[50:65], v[194:197], v[198:201], v[50:65]
	s_waitcnt lgkmcnt(8)
	v_mfma_f32_32x32x16_bf16 v[98:113], v[190:193], v[202:205], v[98:113]
	v_mfma_f32_32x32x16_bf16 v[34:49], v[194:197], v[202:205], v[34:49]
	s_waitcnt lgkmcnt(7)
	v_mfma_f32_32x32x16_bf16 v[82:97], v[190:193], v[206:209], v[82:97]
	v_mfma_f32_32x32x16_bf16 v[18:33], v[194:197], v[206:209], v[18:33]
	s_waitcnt lgkmcnt(6)
	v_mfma_f32_32x32x16_bf16 v[66:81], v[190:193], v[210:213], v[66:81]
	v_mfma_f32_32x32x16_bf16 v[2:17], v[194:197], v[210:213], v[2:17]
	ds_read_b128 v[190:193], v187 offset:64
	ds_read_b128 v[194:197], v187 offset:4672
	ds_read_b128 v[198:201], v188 offset:18496
	ds_read_b128 v[202:205], v188 offset:23104
	ds_read_b128 v[206:209], v188 offset:27712
	ds_read_b128 v[210:213], v188 offset:32320
	s_waitcnt lgkmcnt(9)
	v_mfma_f32_32x32x16_bf16 v[114:129], v[214:217], v[234:237], v[114:129]
	v_mfma_f32_32x32x16_bf16 v[50:65], v[218:221], v[234:237], v[50:65]
	s_waitcnt lgkmcnt(8)
	v_mfma_f32_32x32x16_bf16 v[98:113], v[214:217], v[238:241], v[98:113]
	v_mfma_f32_32x32x16_bf16 v[34:49], v[218:221], v[238:241], v[34:49]
	s_waitcnt lgkmcnt(7)
	v_mfma_f32_32x32x16_bf16 v[82:97], v[214:217], v[242:245], v[82:97]
	v_mfma_f32_32x32x16_bf16 v[18:33], v[218:221], v[242:245], v[18:33]
	s_waitcnt lgkmcnt(6)
	v_mfma_f32_32x32x16_bf16 v[66:81], v[214:217], v[246:249], v[66:81]
	v_mfma_f32_32x32x16_bf16 v[2:17], v[218:221], v[246:249], v[2:17]
	ds_read_b128 v[214:217], v187 offset:96
	ds_read_b128 v[218:221], v187 offset:4704
	ds_read_b128 v[234:237], v188 offset:18528
	ds_read_b128 v[238:241], v188 offset:23136
	ds_read_b128 v[242:245], v188 offset:27744
	ds_read_b128 v[246:249], v188 offset:32352
	s_waitcnt lgkmcnt(9)
	v_mfma_f32_32x32x16_bf16 v[114:129], v[190:193], v[198:201], v[114:129]
	v_mfma_f32_32x32x16_bf16 v[50:65], v[194:197], v[198:201], v[50:65]
	s_waitcnt lgkmcnt(8)
	v_mfma_f32_32x32x16_bf16 v[98:113], v[190:193], v[202:205], v[98:113]
	v_mfma_f32_32x32x16_bf16 v[34:49], v[194:197], v[202:205], v[34:49]
	s_waitcnt lgkmcnt(0)
	s_barrier
	s_cmpk_eq_i32 s4, 0x1500
	s_cbranch_scc1 .Lmy_gB_1
	v_mfma_f32_32x32x16_bf16 v[82:97], v[190:193], v[206:209], v[82:97]
	s_waitcnt vmcnt(9)
	ds_write_b128 v189, v[130:133]
	v_mfma_f32_32x32x16_bf16 v[18:33], v[194:197], v[206:209], v[18:33]
	ds_write_b128 v189, v[134:137] offset:4608
	v_mfma_f32_32x32x16_bf16 v[66:81], v[190:193], v[210:213], v[66:81]
	ds_write_b128 v189, v[138:141] offset:9216
	s_add_u32 vcc_lo, s4, 0x78a8000
	s_addc_u32 vcc_hi, s5, 0
	s_nop 0
	v_lshl_add_u64 v[130:131], v[184:185], 0, vcc
	global_load_dwordx4 v[130:133], v[130:131], off offset:256
	v_mfma_f32_32x32x16_bf16 v[2:17], v[194:197], v[210:213], v[2:17]
	s_waitcnt vmcnt(8)
	ds_write_b128 v189, v[142:145] offset:13824
	s_add_u32 vcc_lo, s4, 0x78d4000
	s_addc_u32 vcc_hi, s5, 0
	s_nop 0
	v_lshl_add_u64 v[134:135], v[184:185], 0, vcc
	global_load_dwordx4 v[134:137], v[134:135], off offset:256
	v_mfma_f32_32x32x16_bf16 v[114:129], v[214:217], v[234:237], v[114:129]
	ds_write_b128 v189, v[146:149] offset:18432
	s_add_u32 vcc_lo, s4, 0x7900000
	s_addc_u32 vcc_hi, s5, 0
	s_nop 0
	v_lshl_add_u64 v[138:139], v[184:185], 0, vcc
	global_load_dwordx4 v[138:141], v[138:139], off offset:256
	v_mfma_f32_32x32x16_bf16 v[50:65], v[218:221], v[234:237], v[50:65]
	s_waitcnt vmcnt(9)
	ds_write_b128 v189, v[150:153] offset:23040
	s_add_u32 vcc_lo, s4, 0x792c000
	s_addc_u32 vcc_hi, s5, 0
	s_nop 0
	v_lshl_add_u64 v[142:143], v[184:185], 0, vcc
	global_load_dwordx4 v[142:145], v[142:143], off offset:256
	v_mfma_f32_32x32x16_bf16 v[98:113], v[214:217], v[238:241], v[98:113]
	s_waitcnt vmcnt(9)
	ds_write_b128 v189, v[154:157] offset:27648
	s_add_u32 vcc_lo, s4, 0xf08000
	s_addc_u32 vcc_hi, s5, 0
	s_nop 0
	v_lshl_add_u64 v[146:147], v[182:183], 0, vcc
	global_load_dwordx4 v[146:149], v[146:147], off offset:256
	v_mfma_f32_32x32x16_bf16 v[34:49], v[218:221], v[238:241], v[34:49]
	s_waitcnt vmcnt(9)
	ds_write_b128 v189, v[158:161] offset:32256
	s_add_u32 vcc_lo, s4, 0xf34000
	s_addc_u32 vcc_hi, s5, 0
	s_nop 0
	v_lshl_add_u64 v[150:151], v[182:183], 0, vcc
	global_load_dwordx4 v[150:153], v[150:151], off offset:256
	v_mfma_f32_32x32x16_bf16 v[82:97], v[214:217], v[242:245], v[82:97]
	s_waitcnt vmcnt(9)
	ds_write_b128 v189, v[162:165] offset:36864
	s_add_u32 vcc_lo, s4, 0xf60000
	s_addc_u32 vcc_hi, s5, 0
	s_nop 0
	v_lshl_add_u64 v[154:155], v[182:183], 0, vcc
	global_load_dwordx4 v[154:157], v[154:155], off offset:256
	v_mfma_f32_32x32x16_bf16 v[18:33], v[218:221], v[242:245], v[18:33]
	s_waitcnt vmcnt(9)
	ds_write_b128 v189, v[166:169] offset:41472
	s_add_u32 vcc_lo, s4, 0xf8c000
	s_addc_u32 vcc_hi, s5, 0
	s_nop 0
	v_lshl_add_u64 v[158:159], v[182:183], 0, vcc
	global_load_dwordx4 v[158:161], v[158:159], off offset:256
	v_mfma_f32_32x32x16_bf16 v[66:81], v[214:217], v[246:249], v[66:81]
	s_waitcnt vmcnt(9)
	ds_write_b128 v189, v[170:173] offset:46080
	s_add_u32 vcc_lo, s4, 0xfb8000
	s_addc_u32 vcc_hi, s5, 0
	s_nop 0
	v_lshl_add_u64 v[162:163], v[182:183], 0, vcc
	global_load_dwordx4 v[162:165], v[162:163], off offset:256
	v_mfma_f32_32x32x16_bf16 v[2:17], v[218:221], v[246:249], v[2:17]
	s_waitcnt vmcnt(9)
	ds_write_b128 v189, v[174:177] offset:50688
	s_add_u32 vcc_lo, s4, 0xfe4000
	s_addc_u32 vcc_hi, s5, 0
	s_nop 0
	v_lshl_add_u64 v[166:167], v[182:183], 0, vcc
	global_load_dwordx4 v[166:169], v[166:167], off offset:256
	s_add_u32 vcc_lo, s4, 0x1010000
	s_addc_u32 vcc_hi, s5, 0
	s_nop 0
	v_lshl_add_u64 v[170:171], v[182:183], 0, vcc
	global_load_dwordx4 v[170:173], v[170:171], off offset:256
	s_add_u32 vcc_lo, s4, 0x103c000
	s_addc_u32 vcc_hi, s5, 0
	s_nop 0
	v_lshl_add_u64 v[174:175], v[182:183], 0, vcc
	global_load_dwordx4 v[174:177], v[174:175], off offset:256
	s_setprio 0
	s_branch .LBB0_773
; __device__ __forceinline__ void lds_barrier() { asm volatile("s_waitcnt lgkmcnt(0)\n\ts_barrier" ::: "memory"); }
; __device__ __forceinline__ f32x16 mfma32(bf16x8 a, bf16x8 b, f32x16 c) { return __builtin_amdgcn_mfma_f32_32x32x16_bf16(a, b, c, 0, 0, 0); }
; __device__ __forceinline__ void gemm_big(const bf16_t* __restrict__ A, long lda, const bf16_t* __restrict__ Bt, int K, f32x16 (&acc)[2][4], unsigned char* lds) {
;     ...
;             if (ks < 3) {
;                 af[nb][0] = *(const bf16x8*)(Ac + (ks + 1) * 16); af[nb][1] = *(const bf16x8*)(Ac + 32 * GLD + (ks + 1) * 16);
; #pragma unroll
;                 for (int ni = 0; ni < 4; ++ni) bfr[nb][ni] = *(const bf16x8*)(Bc + ni * 32 * GLD + (ks + 1) * 16);
;             }
;             __builtin_amdgcn_sched_barrier(0);
; #pragma unroll
;             for (int ni = 0; ni < 4; ++ni) { acc[0][ni] = mfma32(af[cb][0], bfr[cb][ni], acc[0][ni]); acc[1][ni] = mfma32(af[cb][1], bfr[cb][ni], acc[1][ni]); }
;             __builtin_amdgcn_sched_barrier(0);
;         }
;         __builtin_amdgcn_s_setprio(0);
;         lds_barrier();
;         if (kc + 1 < nk) {
;             lstore();
;             if (kc + 2 < nk) gload(kc + 2);
;             lds_barrier();
;         }
.Lmy_gB_1:
	v_mfma_f32_32x32x16_bf16 v[82:97], v[190:193], v[206:209], v[82:97]
	s_waitcnt vmcnt(9)
	ds_write_b128 v189, v[130:133]
	v_mfma_f32_32x32x16_bf16 v[18:33], v[194:197], v[206:209], v[18:33]
	ds_write_b128 v189, v[134:137] offset:4608
	v_mfma_f32_32x32x16_bf16 v[66:81], v[190:193], v[210:213], v[66:81]
	ds_write_b128 v189, v[138:141] offset:9216
	v_mfma_f32_32x32x16_bf16 v[2:17], v[194:197], v[210:213], v[2:17]
	s_waitcnt vmcnt(7)
	ds_write_b128 v189, v[142:145] offset:13824
	v_mfma_f32_32x32x16_bf16 v[114:129], v[214:217], v[234:237], v[114:129]
	ds_write_b128 v189, v[146:149] offset:18432
	v_mfma_f32_32x32x16_bf16 v[50:65], v[218:221], v[234:237], v[50:65]
	s_waitcnt vmcnt(6)
	ds_write_b128 v189, v[150:153] offset:23040
	v_mfma_f32_32x32x16_bf16 v[98:113], v[214:217], v[238:241], v[98:113]
	s_waitcnt vmcnt(5)
	ds_write_b128 v189, v[154:157] offset:27648
	v_mfma_f32_32x32x16_bf16 v[34:49], v[218:221], v[238:241], v[34:49]
	s_waitcnt vmcnt(4)
	ds_write_b128 v189, v[158:161] offset:32256
	v_mfma_f32_32x32x16_bf16 v[82:97], v[214:217], v[242:245], v[82:97]
	s_waitcnt vmcnt(3)
	ds_write_b128 v189, v[162:165] offset:36864
	v_mfma_f32_32x32x16_bf16 v[18:33], v[218:221], v[242:245], v[18:33]
	s_waitcnt vmcnt(2)
	ds_write_b128 v189, v[166:169] offset:41472
	v_mfma_f32_32x32x16_bf16 v[66:81], v[214:217], v[246:249], v[66:81]
	s_waitcnt vmcnt(1)
	ds_write_b128 v189, v[170:173] offset:46080
	v_mfma_f32_32x32x16_bf16 v[2:17], v[218:221], v[246:249], v[2:17]
	s_waitcnt vmcnt(0)
	ds_write_b128 v189, v[174:177] offset:50688
	s_setprio 0
	s_branch .LBB0_773

; __device__ __forceinline__ void lds_barrier() { asm volatile("s_waitcnt lgkmcnt(0)\n\ts_barrier" ::: "memory"); }
; __device__ __forceinline__ f32x16 mfma32(bf16x8 a, bf16x8 b, f32x16 c) { return __builtin_amdgcn_mfma_f32_32x32x16_bf16(a, b, c, 0, 0, 0); }
; __device__ __forceinline__ void gemm_big(const bf16_t* __restrict__ A, long lda, const bf16_t* __restrict__ Bt, int K, f32x16 (&acc)[2][4], unsigned char* lds) {
;     ...
;     for (int kc = 0; kc < nk; ++kc) {
;         bf16x8 af[2][2], bfr[2][4];
;         af[0][0] = *(const bf16x8*)(Ac); af[0][1] = *(const bf16x8*)(Ac + 32 * GLD);
; #pragma unroll
;         for (int ni = 0; ni < 4; ++ni) bfr[0][ni] = *(const bf16x8*)(Bc + ni * 32 * GLD);
;         __builtin_amdgcn_s_setprio(3);
; #pragma unroll
;         for (int ks = 0; ks < 4; ++ks) {
;             const int cb = ks & 1, nb = cb ^ 1;
;             if (ks < 3) {
;                 af[nb][0] = *(const bf16x8*)(Ac + (ks + 1) * 16); af[nb][1] = *(const bf16x8*)(Ac + 32 * GLD + (ks + 1) * 16);
; #pragma unroll
;                 for (int ni = 0; ni < 4; ++ni) bfr[nb][ni] = *(const bf16x8*)(Bc + ni * 32 * GLD + (ks + 1) * 16);
;             }
;             __builtin_amdgcn_sched_barrier(0);
; #pragma unroll
;             for (int ni = 0; ni < 4; ++ni) { acc[0][ni] = mfma32(af[cb][0], bfr[cb][ni], acc[0][ni]); acc[1][ni] = mfma32(af[cb][1], bfr[cb][ni], acc[1][ni]); }
;             __builtin_amdgcn_sched_barrier(0);
;         }
;         __builtin_amdgcn_s_setprio(0);
;         lds_barrier();
;         if (kc + 1 < nk) {
;             lstore();
;             if (kc + 2 < nk) gload(kc + 2);
;             lds_barrier();
;         }
.LBB0_788:
	s_cmp_gt_u32 s5, 14
	s_cbranch_scc1 .Lmy_gorig_0
	ds_read_b128 v[190:193], v188
	ds_read_b128 v[194:197], v188 offset:4608
	ds_read_b128 v[198:201], v189 offset:18432
	ds_read_b128 v[202:205], v189 offset:23040
	ds_read_b128 v[206:209], v189 offset:27648
	ds_read_b128 v[210:213], v189 offset:32256
	s_setprio 3
	ds_read_b128 v[214:217], v188 offset:32
	ds_read_b128 v[234:237], v188 offset:4640
	ds_read_b128 v[238:241], v189 offset:18464
	ds_read_b128 v[242:245], v189 offset:23072
	ds_read_b128 v[246:249], v189 offset:27680
	ds_read_b128 v[218:221], v189 offset:32288
	s_waitcnt lgkmcnt(9)
	v_mfma_f32_32x32x16_bf16 v[114:129], v[190:193], v[198:201], v[114:129]
	v_mfma_f32_32x32x16_bf16 v[82:97], v[194:197], v[198:201], v[82:97]
	s_waitcnt lgkmcnt(8)
	v_mfma_f32_32x32x16_bf16 v[98:113], v[190:193], v[202:205], v[98:113]
	v_mfma_f32_32x32x16_bf16 v[66:81], v[194:197], v[202:205], v[66:81]
	s_waitcnt lgkmcnt(7)
	v_mfma_f32_32x32x16_bf16 v[50:65], v[190:193], v[206:209], v[50:65]
	v_mfma_f32_32x32x16_bf16 v[18:33], v[194:197], v[206:209], v[18:33]
	s_waitcnt lgkmcnt(6)
	v_mfma_f32_32x32x16_bf16 v[34:49], v[190:193], v[210:213], v[34:49]
	v_mfma_f32_32x32x16_bf16 v[2:17], v[194:197], v[210:213], v[2:17]
	ds_read_b128 v[190:193], v188 offset:64
	ds_read_b128 v[194:197], v188 offset:4672
	ds_read_b128 v[198:201], v189 offset:18496
	ds_read_b128 v[202:205], v189 offset:23104
	ds_read_b128 v[206:209], v189 offset:27712
	ds_read_b128 v[210:213], v189 offset:32320
	s_waitcnt lgkmcnt(9)
	v_mfma_f32_32x32x16_bf16 v[114:129], v[214:217], v[238:241], v[114:129]
	v_mfma_f32_32x32x16_bf16 v[82:97], v[234:237], v[238:241], v[82:97]
	s_waitcnt lgkmcnt(8)
	v_mfma_f32_32x32x16_bf16 v[98:113], v[214:217], v[242:245], v[98:113]
	v_mfma_f32_32x32x16_bf16 v[66:81], v[234:237], v[242:245], v[66:81]
	s_waitcnt lgkmcnt(7)
	v_mfma_f32_32x32x16_bf16 v[50:65], v[214:217], v[246:249], v[50:65]
	v_mfma_f32_32x32x16_bf16 v[18:33], v[234:237], v[246:249], v[18:33]
	s_waitcnt lgkmcnt(6)
	v_mfma_f32_32x32x16_bf16 v[34:49], v[214:217], v[218:221], v[34:49]
	v_mfma_f32_32x32x16_bf16 v[2:17], v[234:237], v[218:221], v[2:17]
	ds_read_b128 v[214:217], v188 offset:96
	ds_read_b128 v[218:221], v188 offset:4704
	ds_read_b128 v[234:237], v189 offset:18528
	ds_read_b128 v[238:241], v189 offset:23136
	ds_read_b128 v[242:245], v189 offset:27744
	ds_read_b128 v[246:249], v189 offset:32352
	s_waitcnt lgkmcnt(9)
	v_mfma_f32_32x32x16_bf16 v[114:129], v[190:193], v[198:201], v[114:129]
	v_mfma_f32_32x32x16_bf16 v[82:97], v[194:197], v[198:201], v[82:97]
	s_waitcnt lgkmcnt(8)
	v_mfma_f32_32x32x16_bf16 v[98:113], v[190:193], v[202:205], v[98:113]
	v_mfma_f32_32x32x16_bf16 v[66:81], v[194:197], v[202:205], v[66:81]
	s_waitcnt lgkmcnt(0)
	s_barrier
	s_cmpk_eq_i32 s6, 0x700
	s_cbranch_scc1 .Lmy_gB_0
	v_mfma_f32_32x32x16_bf16 v[50:65], v[190:193], v[206:209], v[50:65]
	s_waitcnt vmcnt(9)
	ds_write_b128 v187, v[130:133]
	v_mfma_f32_32x32x16_bf16 v[18:33], v[194:197], v[206:209], v[18:33]
	ds_write_b128 v187, v[134:137] offset:4608
	v_mfma_f32_32x32x16_bf16 v[34:49], v[190:193], v[210:213], v[34:49]
	ds_write_b128 v187, v[138:141] offset:9216
	s_add_u32 vcc_lo, s6, 0x38a8000
	s_addc_u32 vcc_hi, s7, 0
	s_nop 0
	v_lshl_add_u64 v[130:131], v[184:185], 0, vcc
	global_load_dwordx4 v[130:133], v[130:131], off offset:256
	v_mfma_f32_32x32x16_bf16 v[2:17], v[194:197], v[210:213], v[2:17]
	s_waitcnt vmcnt(8)
	ds_write_b128 v187, v[142:145] offset:13824
	s_add_u32 vcc_lo, s6, 0x38b8000
	s_addc_u32 vcc_hi, s7, 0
	s_nop 0
	v_lshl_add_u64 v[134:135], v[184:185], 0, vcc
	global_load_dwordx4 v[134:137], v[134:135], off offset:256
	v_mfma_f32_32x32x16_bf16 v[114:129], v[214:217], v[234:237], v[114:129]
	ds_write_b128 v187, v[146:149] offset:18432
	s_add_u32 vcc_lo, s6, 0x38c8000
	s_addc_u32 vcc_hi, s7, 0
	s_nop 0
	v_lshl_add_u64 v[138:139], v[184:185], 0, vcc
	global_load_dwordx4 v[138:141], v[138:139], off offset:256
	v_mfma_f32_32x32x16_bf16 v[82:97], v[218:221], v[234:237], v[82:97]
	s_waitcnt vmcnt(9)
	ds_write_b128 v187, v[150:153] offset:23040
	s_add_u32 vcc_lo, s6, 0x38d8000
	s_addc_u32 vcc_hi, s7, 0
	s_nop 0
	v_lshl_add_u64 v[142:143], v[184:185], 0, vcc
	global_load_dwordx4 v[142:145], v[142:143], off offset:256
	v_mfma_f32_32x32x16_bf16 v[98:113], v[214:217], v[238:241], v[98:113]
	s_waitcnt vmcnt(9)
	ds_write_b128 v187, v[154:157] offset:27648
	s_add_u32 vcc_lo, s6, 0x408000
	s_addc_u32 vcc_hi, s7, 0
	s_nop 0
	v_lshl_add_u64 v[146:147], v[182:183], 0, vcc
	global_load_dwordx4 v[146:149], v[146:147], off offset:256
	v_mfma_f32_32x32x16_bf16 v[66:81], v[218:221], v[238:241], v[66:81]
	s_waitcnt vmcnt(9)
	ds_write_b128 v187, v[158:161] offset:32256
	s_add_u32 vcc_lo, s6, 0x418000
	s_addc_u32 vcc_hi, s7, 0
	s_nop 0
	v_lshl_add_u64 v[150:151], v[182:183], 0, vcc
	global_load_dwordx4 v[150:153], v[150:151], off offset:256
	v_mfma_f32_32x32x16_bf16 v[50:65], v[214:217], v[242:245], v[50:65]
	s_waitcnt vmcnt(9)
	ds_write_b128 v187, v[162:165] offset:36864
	s_add_u32 vcc_lo, s6, 0x428000
	s_addc_u32 vcc_hi, s7, 0
	s_nop 0
	v_lshl_add_u64 v[154:155], v[182:183], 0, vcc
	global_load_dwordx4 v[154:157], v[154:155], off offset:256
	v_mfma_f32_32x32x16_bf16 v[18:33], v[218:221], v[242:245], v[18:33]
	s_waitcnt vmcnt(9)
	ds_write_b128 v187, v[166:169] offset:41472
	s_add_u32 vcc_lo, s6, 0x438000
	s_addc_u32 vcc_hi, s7, 0
	s_nop 0
	v_lshl_add_u64 v[158:159], v[182:183], 0, vcc
	global_load_dwordx4 v[158:161], v[158:159], off offset:256
	v_mfma_f32_32x32x16_bf16 v[34:49], v[214:217], v[246:249], v[34:49]
	s_waitcnt vmcnt(9)
	ds_write_b128 v187, v[170:173] offset:46080
	s_add_u32 vcc_lo, s6, 0x448000
	s_addc_u32 vcc_hi, s7, 0
	s_nop 0
	v_lshl_add_u64 v[162:163], v[182:183], 0, vcc
	global_load_dwordx4 v[162:165], v[162:163], off offset:256
	v_mfma_f32_32x32x16_bf16 v[2:17], v[218:221], v[246:249], v[2:17]
	s_waitcnt vmcnt(9)
	ds_write_b128 v187, v[174:177] offset:50688
	s_add_u32 vcc_lo, s6, 0x458000
	s_addc_u32 vcc_hi, s7, 0
	s_nop 0
	v_lshl_add_u64 v[166:167], v[182:183], 0, vcc
	global_load_dwordx4 v[166:169], v[166:167], off offset:256
	s_add_u32 vcc_lo, s6, 0x468000
	s_addc_u32 vcc_hi, s7, 0
	s_nop 0
	v_lshl_add_u64 v[170:171], v[182:183], 0, vcc
	global_load_dwordx4 v[170:173], v[170:171], off offset:256
	s_add_u32 vcc_lo, s6, 0x478000
	s_addc_u32 vcc_hi, s7, 0
	s_nop 0
	v_lshl_add_u64 v[174:175], v[182:183], 0, vcc
	global_load_dwordx4 v[174:177], v[174:175], off offset:256
	s_setprio 0
	s_branch .LBB0_786
; __device__ __forceinline__ void lds_barrier() { asm volatile("s_waitcnt lgkmcnt(0)\n\ts_barrier" ::: "memory"); }
; __device__ __forceinline__ f32x16 mfma32(bf16x8 a, bf16x8 b, f32x16 c) { return __builtin_amdgcn_mfma_f32_32x32x16_bf16(a, b, c, 0, 0, 0); }
; __device__ __forceinline__ void gemm_big(const bf16_t* __restrict__ A, long lda, const bf16_t* __restrict__ Bt, int K, f32x16 (&acc)[2][4], unsigned char* lds) {
;     ...
;             if (ks < 3) {
;                 af[nb][0] = *(const bf16x8*)(Ac + (ks + 1) * 16); af[nb][1] = *(const bf16x8*)(Ac + 32 * GLD + (ks + 1) * 16);
; #pragma unroll
;                 for (int ni = 0; ni < 4; ++ni) bfr[nb][ni] = *(const bf16x8*)(Bc + ni * 32 * GLD + (ks + 1) * 16);
;             }
;             __builtin_amdgcn_sched_barrier(0);
; #pragma unroll
;             for (int ni = 0; ni < 4; ++ni) { acc[0][ni] = mfma32(af[cb][0], bfr[cb][ni], acc[0][ni]); acc[1][ni] = mfma32(af[cb][1], bfr[cb][ni], acc[1][ni]); }
;             __builtin_amdgcn_sched_barrier(0);
;         }
;         __builtin_amdgcn_s_setprio(0);
;         lds_barrier();
;         if (kc + 1 < nk) {
;             lstore();
;             if (kc + 2 < nk) gload(kc + 2);
;             lds_barrier();
;         }
.Lmy_gB_0:
	v_mfma_f32_32x32x16_bf16 v[50:65], v[190:193], v[206:209], v[50:65]
	s_waitcnt vmcnt(9)
	ds_write_b128 v187, v[130:133]
	v_mfma_f32_32x32x16_bf16 v[18:33], v[194:197], v[206:209], v[18:33]
	ds_write_b128 v187, v[134:137] offset:4608
	v_mfma_f32_32x32x16_bf16 v[34:49], v[190:193], v[210:213], v[34:49]
	ds_write_b128 v187, v[138:141] offset:9216
	v_mfma_f32_32x32x16_bf16 v[2:17], v[194:197], v[210:213], v[2:17]
	s_waitcnt vmcnt(7)
	ds_write_b128 v187, v[142:145] offset:13824
	v_mfma_f32_32x32x16_bf16 v[114:129], v[214:217], v[234:237], v[114:129]
	ds_write_b128 v187, v[146:149] offset:18432
	v_mfma_f32_32x32x16_bf16 v[82:97], v[218:221], v[234:237], v[82:97]
	s_waitcnt vmcnt(6)
	ds_write_b128 v187, v[150:153] offset:23040
	v_mfma_f32_32x32x16_bf16 v[98:113], v[214:217], v[238:241], v[98:113]
	s_waitcnt vmcnt(5)
	ds_write_b128 v187, v[154:157] offset:27648
	v_mfma_f32_32x32x16_bf16 v[66:81], v[218:221], v[238:241], v[66:81]
	s_waitcnt vmcnt(4)
	ds_write_b128 v187, v[158:161] offset:32256
	v_mfma_f32_32x32x16_bf16 v[50:65], v[214:217], v[242:245], v[50:65]
	s_waitcnt vmcnt(3)
	ds_write_b128 v187, v[162:165] offset:36864
	v_mfma_f32_32x32x16_bf16 v[18:33], v[218:221], v[242:245], v[18:33]
	s_waitcnt vmcnt(2)
	ds_write_b128 v187, v[166:169] offset:41472
	v_mfma_f32_32x32x16_bf16 v[34:49], v[214:217], v[246:249], v[34:49]
	s_waitcnt vmcnt(1)
	ds_write_b128 v187, v[170:173] offset:46080
	v_mfma_f32_32x32x16_bf16 v[2:17], v[218:221], v[246:249], v[2:17]
	s_waitcnt vmcnt(0)
	ds_write_b128 v187, v[174:177] offset:50688
	s_setprio 0
	s_branch .LBB0_786
